# RES_MIX/RES_FFN epilogues: lines of residual rounds 1-3 touched right after the round-0 loads so later rounds hit L2
# baseline (speedup 1.0000x reference)
.LBB0_707:
	s_add_i32 s58, s64, 0xffffe000
	s_lshr_b32 s58, s58, 12
	s_mulk_i32 s58, 0x1800
	s_addk_i32 s58, 0x1800
	s_cmp_gt_i32 s6, 63
	s_cselect_b32 s6, s58, 0
	s_lshl_b64 s[58:59], s[6:7], 2
	v_mov_b32_e32 v70, s68
	s_add_u32 s6, s14, s58
	ds_read_b64 v[70:71], v70
	s_addc_u32 s63, s15, s59
	s_lshl_b32 s58, s69, 14
	s_add_i32 s58, s58, 0x20000
	s_ashr_i32 s59, s58, 31
	s_lshl_b64 s[58:59], s[58:59], 2
	s_add_u32 s58, s10, s58
	s_waitcnt lgkmcnt(0)
	v_readfirstlane_b32 s70, v70
	s_addc_u32 s59, s11, s59
	v_add_u32_e32 v70, s64, v141
	s_add_u32 s60, s6, 0x5ba2000
	v_lshlrev_b32_e32 v190, 10, v70
	s_addc_u32 s61, s63, 0
	v_or_b32_e32 v102, s66, v140
	v_or_b32_e32 v188, 0x400, v190
	v_or_b32_e32 v187, 0x4400, v190
	v_or_b32_e32 v191, 0x4c00, v190
	v_or_b32_e32 v195, 0x6c00, v190
	v_readfirstlane_b32 s71, v71
	s_add_u32 s62, s6, 0x5ba4000
	v_ashrrev_i32_e32 v103, 31, v102
	v_add_u32_e32 v134, v190, v102
	v_add_u32_e32 v136, v188, v102
	v_or_b32_e32 v186, 0x800, v190
	v_or_b32_e32 v185, 0xc00, v190
	v_or_b32_e32 v183, 0x2000, v190
	v_or_b32_e32 v181, 0x2400, v190
	v_or_b32_e32 v71, 0x2800, v190
	v_or_b32_e32 v182, 0x2c00, v190
	v_or_b32_e32 v184, 0x4000, v190
	v_add_u32_e32 v114, v187, v102
	v_or_b32_e32 v189, 0x4800, v190
	v_add_u32_e32 v120, v191, v102
	v_or_b32_e32 v192, 0x6000, v190
	v_or_b32_e32 v193, 0x6400, v190
	v_or_b32_e32 v194, 0x6800, v190
	v_add_u32_e32 v130, v195, v102
	s_addc_u32 s63, s63, 0
	v_lshlrev_b64 v[72:73], 2, v[102:103]
	v_ashrrev_i32_e32 v137, 31, v136
	v_add_u32_e32 v138, v186, v102
	v_add_u32_e32 v132, v185, v102
	v_add_u32_e32 v124, v183, v102
	v_add_u32_e32 v116, v181, v102
	v_add_u32_e32 v108, v71, v102
	v_add_u32_e32 v110, v182, v102
	v_add_u32_e32 v112, v184, v102
	v_ashrrev_i32_e32 v115, 31, v114
	v_add_u32_e32 v118, v189, v102
	v_ashrrev_i32_e32 v121, 31, v120
	v_add_u32_e32 v122, v192, v102
	v_add_u32_e32 v126, v193, v102
	v_add_u32_e32 v128, v194, v102
	v_ashrrev_i32_e32 v131, 31, v130
	v_ashrrev_i32_e32 v135, 31, v134
	v_lshl_add_u64 v[74:75], s[60:61], 0, v[72:73]
	v_lshl_add_u64 v[104:105], s[70:71], 0, v[72:73]
	v_lshl_add_u64 v[72:73], s[62:63], 0, v[72:73]
	v_lshl_add_u64 v[88:89], v[136:137], 2, s[12:13]
	v_ashrrev_i32_e32 v139, 31, v138
	v_ashrrev_i32_e32 v133, 31, v132
	v_ashrrev_i32_e32 v125, 31, v124
	v_ashrrev_i32_e32 v117, 31, v116
	v_ashrrev_i32_e32 v109, 31, v108
	v_ashrrev_i32_e32 v111, 31, v110
	v_ashrrev_i32_e32 v113, 31, v112
	v_lshl_add_u64 v[86:87], v[114:115], 2, s[12:13]
	v_ashrrev_i32_e32 v119, 31, v118
	v_lshl_add_u64 v[92:93], v[120:121], 2, s[12:13]
	v_ashrrev_i32_e32 v123, 31, v122
	v_ashrrev_i32_e32 v127, 31, v126
	v_ashrrev_i32_e32 v129, 31, v128
	v_lshl_add_u64 v[100:101], v[130:131], 2, s[12:13]
	v_lshl_add_u64 v[106:107], v[134:135], 2, s[12:13]
	global_load_dword v196, v[74:75], off
	global_load_dword v198, v[72:73], off
	global_load_dword v197, v[104:105], off
	v_lshl_add_u64 v[84:85], v[138:139], 2, s[12:13]
	v_lshl_add_u64 v[82:83], v[132:133], 2, s[12:13]
	v_lshl_add_u64 v[78:79], v[124:125], 2, s[12:13]
	v_lshl_add_u64 v[72:73], v[116:117], 2, s[12:13]
	v_lshl_add_u64 v[74:75], v[108:109], 2, s[12:13]
	v_lshl_add_u64 v[76:77], v[110:111], 2, s[12:13]
	v_lshl_add_u64 v[80:81], v[112:113], 2, s[12:13]
	global_load_dword v180, v[88:89], off
	global_load_dword v179, v[84:85], off
	global_load_dword v178, v[82:83], off
	global_load_dword v177, v[78:79], off
	global_load_dword v176, v[72:73], off
	global_load_dword v175, v[74:75], off
	global_load_dword v174, v[76:77], off
	global_load_dword v173, v[80:81], off
	v_lshl_add_u64 v[90:91], v[118:119], 2, s[12:13]
	global_load_dword v172, v[86:87], off
	global_load_dword v170, v[90:91], off
	v_lshl_add_u64 v[94:95], v[122:123], 2, s[12:13]
	v_lshl_add_u64 v[96:97], v[126:127], 2, s[12:13]
	v_lshl_add_u64 v[98:99], v[128:129], 2, s[12:13]
	global_load_dword v171, v[92:93], off
	global_load_dword v169, v[94:95], off
	global_load_dword v168, v[96:97], off
	global_load_dword v167, v[98:99], off
	global_load_dword v103, v[100:101], off
	global_load_dword v202, v[106:107], off
	v_lshl_add_u64 v[108:109], v[108:109], 1, s[8:9]
	global_load_dword v255, v[88:89], off offset:128
	global_load_dword v255, v[88:89], off offset:256
	global_load_dword v255, v[88:89], off offset:384
	global_load_dword v255, v[84:85], off offset:128
	global_load_dword v255, v[84:85], off offset:256
	global_load_dword v255, v[84:85], off offset:384
	global_load_dword v255, v[82:83], off offset:128
	global_load_dword v255, v[82:83], off offset:256
	global_load_dword v255, v[82:83], off offset:384
	global_load_dword v255, v[78:79], off offset:128
	global_load_dword v255, v[78:79], off offset:256
	global_load_dword v255, v[78:79], off offset:384
	global_load_dword v255, v[72:73], off offset:128
	global_load_dword v255, v[72:73], off offset:256
	global_load_dword v255, v[72:73], off offset:384
	global_load_dword v255, v[74:75], off offset:128
	global_load_dword v255, v[74:75], off offset:256
	global_load_dword v255, v[74:75], off offset:384
	global_load_dword v255, v[76:77], off offset:128
	global_load_dword v255, v[76:77], off offset:256
	global_load_dword v255, v[76:77], off offset:384
	global_load_dword v255, v[80:81], off offset:128
	global_load_dword v255, v[80:81], off offset:256
	global_load_dword v255, v[80:81], off offset:384
	global_load_dword v255, v[86:87], off offset:128
	global_load_dword v255, v[86:87], off offset:256
	global_load_dword v255, v[86:87], off offset:384
	global_load_dword v255, v[90:91], off offset:128
	global_load_dword v255, v[90:91], off offset:256
	global_load_dword v255, v[90:91], off offset:384
	global_load_dword v255, v[92:93], off offset:128
	global_load_dword v255, v[92:93], off offset:256
	global_load_dword v255, v[92:93], off offset:384
	global_load_dword v255, v[94:95], off offset:128
	global_load_dword v255, v[94:95], off offset:256
	global_load_dword v255, v[94:95], off offset:384
	global_load_dword v255, v[96:97], off offset:128
	global_load_dword v255, v[96:97], off offset:256
	global_load_dword v255, v[96:97], off offset:384
	global_load_dword v255, v[98:99], off offset:128
	global_load_dword v255, v[98:99], off offset:256
	global_load_dword v255, v[98:99], off offset:384
	global_load_dword v255, v[100:101], off offset:128
	global_load_dword v255, v[100:101], off offset:256
	global_load_dword v255, v[100:101], off offset:384
	global_load_dword v255, v[106:107], off offset:128
	global_load_dword v255, v[106:107], off offset:256
	global_load_dword v255, v[106:107], off offset:384
	s_waitcnt vmcnt(0)
	v_add_f32_e32 v198, 1.0, v198
	v_mul_f32_e32 v197, v197, v198
	v_fmac_f32_e32 v180, v49, v196
	v_fmac_f32_e32 v179, v50, v196
	v_fmac_f32_e32 v178, v51, v196
	v_fmac_f32_e32 v177, v52, v196
	v_fmac_f32_e32 v176, v53, v196
	v_fmac_f32_e32 v175, v54, v196
	v_fmac_f32_e32 v174, v55, v196
	v_fmac_f32_e32 v173, v56, v196
	v_fmac_f32_e32 v172, v57, v196
	v_fmac_f32_e32 v170, v58, v196
	v_fmac_f32_e32 v171, v59, v196
	v_fmac_f32_e32 v169, v60, v196
	v_fmac_f32_e32 v168, v61, v196
	v_fmac_f32_e32 v167, v62, v196
	v_fmac_f32_e32 v103, v63, v196
	v_fmac_f32_e32 v202, v48, v196
	v_or_b32_e32 v48, 32, v102
	v_ashrrev_i32_e32 v49, 31, v48
	v_lshlrev_b64 v[50:51], 2, v[48:49]
	global_store_dword v[88:89], v180, off sc1
	global_store_dword v[84:85], v179, off sc1
	global_store_dword v[82:83], v178, off sc1
	global_store_dword v[78:79], v177, off sc1
	global_store_dword v[72:73], v176, off sc1
	global_store_dword v[74:75], v175, off sc1
	global_store_dword v[76:77], v174, off sc1
	global_store_dword v[80:81], v173, off sc1
	global_store_dword v[86:87], v172, off sc1
	global_store_dword v[90:91], v170, off sc1
	global_store_dword v[92:93], v171, off sc1
	global_store_dword v[94:95], v169, off sc1
	global_store_dword v[96:97], v168, off sc1
	global_store_dword v[98:99], v167, off sc1
	global_store_dword v[100:101], v103, off sc1
	global_store_dword v[106:107], v202, off sc1
	v_mul_f32_e32 v54, v197, v202
	v_lshl_add_u64 v[52:53], s[60:61], 0, v[50:51]
	v_lshl_add_u64 v[50:51], s[62:63], 0, v[50:51]
	global_load_dword v198, v[106:107], off offset:128
	global_load_dword v196, v[52:53], off
	global_load_dword v203, v[50:51], off
	global_load_dword v204, v[104:105], off offset:128
	v_cvt_pk_bf16_f32 v49, v54, s0
	v_lshl_add_u64 v[50:51], v[134:135], 1, s[8:9]
	global_store_short v[50:51], v49, off sc1
	v_mul_f32_e32 v49, v197, v180
	v_cvt_pk_bf16_f32 v49, v49, s0
	v_lshl_add_u64 v[50:51], v[136:137], 1, s[8:9]
	global_store_short v[50:51], v49, off sc1
	v_mul_f32_e32 v49, v197, v179
	v_cvt_pk_bf16_f32 v49, v49, s0
	v_lshl_add_u64 v[50:51], v[138:139], 1, s[8:9]
	global_store_short v[50:51], v49, off sc1
	v_mul_f32_e32 v49, v197, v178
	v_cvt_pk_bf16_f32 v49, v49, s0
	v_lshl_add_u64 v[50:51], v[132:133], 1, s[8:9]
	global_store_short v[50:51], v49, off sc1
	v_mul_f32_e32 v49, v197, v177
	v_cvt_pk_bf16_f32 v49, v49, s0
	v_lshl_add_u64 v[50:51], v[124:125], 1, s[8:9]
	global_store_short v[50:51], v49, off sc1
	v_mul_f32_e32 v49, v197, v176
	v_cvt_pk_bf16_f32 v49, v49, s0
	v_lshl_add_u64 v[50:51], v[116:117], 1, s[8:9]
	global_store_short v[50:51], v49, off sc1
	v_mul_f32_e32 v49, v197, v175
	global_load_dword v62, v[84:85], off offset:128
	global_load_dword v60, v[78:79], off offset:128
	global_load_dword v59, v[72:73], off offset:128
	global_load_dword v58, v[74:75], off offset:128
	global_load_dword v56, v[80:81], off offset:128
	global_load_dword v57, v[76:77], off offset:128
	global_load_dword v55, v[86:87], off offset:128
	global_load_dword v61, v[82:83], off offset:128
	global_load_dword v54, v[90:91], off offset:128
	global_load_dword v53, v[92:93], off offset:128
	global_load_dword v52, v[94:95], off offset:128
	global_load_dword v51, v[96:97], off offset:128
	global_load_dword v50, v[98:99], off offset:128
	v_cvt_pk_bf16_f32 v63, v49, s0
	global_load_dword v49, v[100:101], off offset:128
	s_waitcnt vmcnt(22)
	v_fmac_f32_e32 v198, v32, v196
	global_store_short v[108:109], v63, off sc1
	global_load_dword v63, v[88:89], off offset:128
	v_mul_f32_e32 v108, v197, v174
	v_cvt_pk_bf16_f32 v116, v108, s0
	v_lshl_add_u64 v[108:109], v[110:111], 1, s[8:9]
	global_store_short v[108:109], v116, off sc1
	v_mul_f32_e32 v108, v197, v173
	v_cvt_pk_bf16_f32 v110, v108, s0
	v_lshl_add_u64 v[108:109], v[112:113], 1, s[8:9]
	global_store_short v[108:109], v110, off sc1
	v_mul_f32_e32 v108, v197, v172
	v_cvt_pk_bf16_f32 v110, v108, s0
	v_lshl_add_u64 v[108:109], v[114:115], 1, s[8:9]
	global_store_short v[108:109], v110, off sc1
	v_mul_f32_e32 v108, v197, v170
	v_cvt_pk_bf16_f32 v110, v108, s0
	v_lshl_add_u64 v[108:109], v[118:119], 1, s[8:9]
	global_store_short v[108:109], v110, off sc1
	v_mul_f32_e32 v108, v197, v171
	v_cvt_pk_bf16_f32 v110, v108, s0
	v_lshl_add_u64 v[108:109], v[120:121], 1, s[8:9]
	global_store_short v[108:109], v110, off sc1
	v_mul_f32_e32 v108, v197, v169
	v_cvt_pk_bf16_f32 v110, v108, s0
	v_lshl_add_u64 v[108:109], v[122:123], 1, s[8:9]
	global_store_short v[108:109], v110, off sc1
	v_mul_f32_e32 v108, v197, v168
	v_cvt_pk_bf16_f32 v110, v108, s0
	v_lshl_add_u64 v[108:109], v[126:127], 1, s[8:9]
	global_store_short v[108:109], v110, off sc1
	v_mul_f32_e32 v108, v197, v167
	v_cvt_pk_bf16_f32 v110, v108, s0
	v_lshl_add_u64 v[108:109], v[128:129], 1, s[8:9]
	global_store_short v[108:109], v110, off sc1
	v_mul_f32_e32 v108, v197, v103
	v_cvt_pk_bf16_f32 v110, v108, s0
	v_lshl_add_u64 v[108:109], v[130:131], 1, s[8:9]
	global_store_short v[108:109], v110, off sc1
	s_waitcnt vmcnt(32)
	v_add_f32_e32 v108, 1.0, v203
	s_waitcnt vmcnt(31)
	v_mul_f32_e32 v112, v204, v108
	v_add_u32_e32 v108, v190, v48
	s_waitcnt vmcnt(24)
	v_fmac_f32_e32 v62, v34, v196
	s_waitcnt vmcnt(17)
	v_fmac_f32_e32 v61, v35, v196
	v_fmac_f32_e32 v60, v36, v196
	v_fmac_f32_e32 v59, v37, v196
	v_fmac_f32_e32 v58, v38, v196
	v_fmac_f32_e32 v57, v39, v196
	v_fmac_f32_e32 v56, v40, v196
	v_fmac_f32_e32 v55, v41, v196
	s_waitcnt vmcnt(16)
	v_fmac_f32_e32 v54, v42, v196
	s_waitcnt vmcnt(15)
	v_fmac_f32_e32 v53, v43, v196
	s_waitcnt vmcnt(14)
	v_fmac_f32_e32 v52, v44, v196
	s_waitcnt vmcnt(13)
	v_fmac_f32_e32 v51, v45, v196
	s_waitcnt vmcnt(12)
	v_fmac_f32_e32 v50, v46, v196
	s_waitcnt vmcnt(11)
	v_fmac_f32_e32 v49, v47, v196
	v_ashrrev_i32_e32 v109, 31, v108
	global_store_dword v[106:107], v198, off offset:128 sc1
	v_mul_f32_e32 v32, v112, v198
	global_store_dword v[84:85], v62, off offset:128 sc1
	global_store_dword v[82:83], v61, off offset:128 sc1
	global_store_dword v[78:79], v60, off offset:128 sc1
	global_store_dword v[72:73], v59, off offset:128 sc1
	global_store_dword v[74:75], v58, off offset:128 sc1
	global_store_dword v[76:77], v57, off offset:128 sc1
	global_store_dword v[80:81], v56, off offset:128 sc1
	global_store_dword v[86:87], v55, off offset:128 sc1
	global_store_dword v[90:91], v54, off offset:128 sc1
	global_store_dword v[92:93], v53, off offset:128 sc1
	global_store_dword v[94:95], v52, off offset:128 sc1
	global_store_dword v[96:97], v51, off offset:128 sc1
	global_store_dword v[98:99], v50, off offset:128 sc1
	global_store_dword v[100:101], v49, off offset:128 sc1
	v_cvt_pk_bf16_f32 v32, v32, s0
	v_lshl_add_u64 v[108:109], v[108:109], 1, s[8:9]
	v_add_u32_e32 v110, v188, v48
	global_load_dword v45, v[88:89], off offset:256
	v_ashrrev_i32_e32 v111, 31, v110
	global_store_short v[108:109], v32, off sc1
	v_mul_f32_e32 v40, v112, v59
	v_mul_f32_e32 v115, v112, v56
	v_cvt_pk_bf16_f32 v115, v115, s0
	s_waitcnt vmcnt(26)
	v_fmac_f32_e32 v63, v33, v196
	v_mul_f32_e32 v32, v112, v63
	v_cvt_pk_bf16_f32 v34, v32, s0
	v_lshl_add_u64 v[32:33], v[110:111], 1, s[8:9]
	global_store_short v[32:33], v34, off sc1
	v_add_u32_e32 v32, v186, v48
	v_ashrrev_i32_e32 v33, 31, v32
	v_mul_f32_e32 v34, v112, v62
	v_cvt_pk_bf16_f32 v34, v34, s0
	v_lshl_add_u64 v[32:33], v[32:33], 1, s[8:9]
	global_store_short v[32:33], v34, off sc1
	v_add_u32_e32 v32, v185, v48
	v_ashrrev_i32_e32 v33, 31, v32
	v_mul_f32_e32 v34, v112, v61
	v_cvt_pk_bf16_f32 v34, v34, s0
	v_lshl_add_u64 v[32:33], v[32:33], 1, s[8:9]
	global_store_short v[32:33], v34, off sc1
	v_add_u32_e32 v32, v183, v48
	v_ashrrev_i32_e32 v33, 31, v32
	v_mul_f32_e32 v34, v112, v60
	v_cvt_pk_bf16_f32 v34, v34, s0
	v_lshl_add_u64 v[32:33], v[32:33], 1, s[8:9]
	global_store_short v[32:33], v34, off sc1
	v_or_b32_e32 v32, 64, v102
	v_add_u32_e32 v34, v181, v48
	v_ashrrev_i32_e32 v33, 31, v32
	v_ashrrev_i32_e32 v35, 31, v34
	v_lshlrev_b64 v[36:37], 2, v[32:33]
	global_store_dword v[88:89], v63, off offset:128 sc1
	v_lshl_add_u64 v[38:39], s[60:61], 0, v[36:37]
	v_cvt_pk_bf16_f32 v33, v40, s0
	v_lshl_add_u64 v[34:35], v[34:35], 1, s[8:9]
	v_lshl_add_u64 v[36:37], s[62:63], 0, v[36:37]
	global_load_dword v109, v[38:39], off
	global_load_dword v113, v[36:37], off
	global_load_dword v114, v[104:105], off offset:256
	global_load_dword v116, v[106:107], off offset:256
	global_load_dword v47, v[84:85], off offset:256
	global_load_dword v44, v[78:79], off offset:256
	global_load_dword v39, v[86:87], off offset:256
	global_load_dword v46, v[82:83], off offset:256
	global_load_dword v43, v[72:73], off offset:256
	global_load_dword v42, v[74:75], off offset:256
	global_load_dword v40, v[80:81], off offset:256
	global_load_dword v41, v[76:77], off offset:256
	global_load_dword v38, v[90:91], off offset:256
	global_load_dword v37, v[92:93], off offset:256
	global_load_dword v36, v[94:95], off offset:256
	v_add_u32_e32 v110, v184, v48
	global_store_short v[34:35], v33, off sc1
	v_add_u32_e32 v34, v71, v48
	v_ashrrev_i32_e32 v35, 31, v34
	v_mul_f32_e32 v33, v112, v58
	v_cvt_pk_bf16_f32 v33, v33, s0
	v_lshl_add_u64 v[34:35], v[34:35], 1, s[8:9]
	global_store_short v[34:35], v33, off sc1
	v_add_u32_e32 v34, v182, v48
	v_ashrrev_i32_e32 v35, 31, v34
	v_mul_f32_e32 v33, v112, v57
	v_cvt_pk_bf16_f32 v33, v33, s0
	v_lshl_add_u64 v[34:35], v[34:35], 1, s[8:9]
	global_store_short v[34:35], v33, off sc1
	global_load_dword v35, v[96:97], off offset:256
	v_ashrrev_i32_e32 v111, 31, v110
	global_load_dword v34, v[98:99], off offset:256
	global_load_dword v33, v[100:101], off offset:256
	v_lshl_add_u64 v[110:111], v[110:111], 1, s[8:9]
	global_store_short v[110:111], v115, off sc1
	v_add_u32_e32 v110, v187, v48
	v_ashrrev_i32_e32 v111, 31, v110
	v_mul_f32_e32 v115, v112, v55
	v_cvt_pk_bf16_f32 v115, v115, s0
	v_lshl_add_u64 v[110:111], v[110:111], 1, s[8:9]
	global_store_short v[110:111], v115, off sc1
	v_add_u32_e32 v110, v189, v48
	v_ashrrev_i32_e32 v111, 31, v110
	v_mul_f32_e32 v115, v112, v54
	v_cvt_pk_bf16_f32 v115, v115, s0
	v_lshl_add_u64 v[110:111], v[110:111], 1, s[8:9]
	global_store_short v[110:111], v115, off sc1
	v_add_u32_e32 v110, v191, v48
	v_ashrrev_i32_e32 v111, 31, v110
	v_mul_f32_e32 v115, v112, v53
	v_cvt_pk_bf16_f32 v115, v115, s0
	v_lshl_add_u64 v[110:111], v[110:111], 1, s[8:9]
	global_store_short v[110:111], v115, off sc1
	v_add_u32_e32 v110, v192, v48
	v_ashrrev_i32_e32 v111, 31, v110
	v_mul_f32_e32 v115, v112, v52
	v_cvt_pk_bf16_f32 v115, v115, s0
	v_lshl_add_u64 v[110:111], v[110:111], 1, s[8:9]
	global_store_short v[110:111], v115, off sc1
	v_add_u32_e32 v110, v193, v48
	v_ashrrev_i32_e32 v111, 31, v110
	v_mul_f32_e32 v115, v112, v51
	v_cvt_pk_bf16_f32 v115, v115, s0
	v_lshl_add_u64 v[110:111], v[110:111], 1, s[8:9]
	global_store_short v[110:111], v115, off sc1
	v_add_u32_e32 v110, v194, v48
	v_ashrrev_i32_e32 v111, 31, v110
	v_mul_f32_e32 v115, v112, v50
	v_cvt_pk_bf16_f32 v115, v115, s0
	v_lshl_add_u64 v[110:111], v[110:111], 1, s[8:9]
	global_store_short v[110:111], v115, off sc1
	v_add_u32_e32 v110, v195, v48
	v_ashrrev_i32_e32 v111, 31, v110
	v_mul_f32_e32 v48, v112, v49
	v_cvt_pk_bf16_f32 v48, v48, s0
	v_lshl_add_u64 v[110:111], v[110:111], 1, s[8:9]
	global_store_short v[110:111], v48, off sc1
	v_add_u32_e32 v110, v190, v32
	v_ashrrev_i32_e32 v111, 31, v110
	v_mul_f32_e32 v108, v198, v198
	s_waitcnt vmcnt(28)
	v_fmac_f32_e32 v45, v17, v109
	s_waitcnt vmcnt(27)
	v_add_f32_e32 v48, 1.0, v113
	s_waitcnt vmcnt(26)
	v_mul_f32_e32 v48, v114, v48
	s_waitcnt vmcnt(25)
	v_fmac_f32_e32 v116, v16, v109
	v_mul_f32_e32 v16, v48, v116
	s_waitcnt vmcnt(24)
	v_fmac_f32_e32 v47, v18, v109
	v_cvt_pk_bf16_f32 v18, v16, s0
	v_lshl_add_u64 v[16:17], v[110:111], 1, s[8:9]
	global_store_short v[16:17], v18, off sc1
	v_add_u32_e32 v16, v188, v32
	v_ashrrev_i32_e32 v17, 31, v16
	v_mul_f32_e32 v18, v48, v45
	v_cvt_pk_bf16_f32 v18, v18, s0
	v_lshl_add_u64 v[16:17], v[16:17], 1, s[8:9]
	global_store_short v[16:17], v18, off sc1
	v_add_u32_e32 v16, v186, v32
	v_ashrrev_i32_e32 v17, 31, v16
	v_mul_f32_e32 v18, v48, v47
	v_cvt_pk_bf16_f32 v18, v18, s0
	v_lshl_add_u64 v[16:17], v[16:17], 1, s[8:9]
	s_waitcnt vmcnt(23)
	v_fmac_f32_e32 v46, v19, v109
	global_store_short v[16:17], v18, off sc1
	v_add_u32_e32 v16, v185, v32
	v_ashrrev_i32_e32 v17, 31, v16
	v_mul_f32_e32 v18, v48, v46
	v_cvt_pk_bf16_f32 v18, v18, s0
	v_lshl_add_u64 v[16:17], v[16:17], 1, s[8:9]
	global_store_short v[16:17], v18, off sc1
	v_or_b32_e32 v16, 0x60, v102
	v_ashrrev_i32_e32 v17, 31, v16
	v_fmac_f32_e32 v44, v20, v109
	s_waitcnt vmcnt(24)
	v_fmac_f32_e32 v43, v21, v109
	s_waitcnt vmcnt(23)
	v_fmac_f32_e32 v42, v22, v109
	s_waitcnt vmcnt(21)
	v_fmac_f32_e32 v41, v23, v109
	v_fmac_f32_e32 v40, v24, v109
	v_fmac_f32_e32 v39, v25, v109
	s_waitcnt vmcnt(20)
	v_fmac_f32_e32 v38, v26, v109
	s_waitcnt vmcnt(19)
	v_fmac_f32_e32 v37, v27, v109
	s_waitcnt vmcnt(18)
	v_fmac_f32_e32 v36, v28, v109
	s_waitcnt vmcnt(14)
	v_fmac_f32_e32 v35, v29, v109
	s_waitcnt vmcnt(13)
	v_fmac_f32_e32 v34, v30, v109
	s_waitcnt vmcnt(12)
	v_fmac_f32_e32 v33, v31, v109
	v_lshlrev_b64 v[20:21], 2, v[16:17]
	global_store_dword v[88:89], v45, off offset:256 sc1
	global_store_dword v[84:85], v47, off offset:256 sc1
	global_store_dword v[82:83], v46, off offset:256 sc1
	global_store_dword v[78:79], v44, off offset:256 sc1
	global_store_dword v[72:73], v43, off offset:256 sc1
	global_store_dword v[74:75], v42, off offset:256 sc1
	global_store_dword v[76:77], v41, off offset:256 sc1
	global_store_dword v[80:81], v40, off offset:256 sc1
	global_store_dword v[86:87], v39, off offset:256 sc1
	global_store_dword v[90:91], v38, off offset:256 sc1
	global_store_dword v[92:93], v37, off offset:256 sc1
	global_store_dword v[94:95], v36, off offset:256 sc1
	global_store_dword v[96:97], v35, off offset:256 sc1
	global_store_dword v[98:99], v34, off offset:256 sc1
	global_store_dword v[100:101], v33, off offset:256 sc1
	global_store_dword v[106:107], v116, off offset:256 sc1
	v_lshl_add_u64 v[22:23], s[60:61], 0, v[20:21]
	v_lshl_add_u64 v[20:21], s[62:63], 0, v[20:21]
	global_load_dword v29, v[106:107], off offset:384
	global_load_dword v102, v[22:23], off
	global_load_dword v17, v[20:21], off
	s_nop 0
	global_load_dword v20, v[104:105], off offset:384
	v_add_u32_e32 v18, v183, v32
	v_ashrrev_i32_e32 v19, 31, v18
	v_mul_f32_e32 v21, v48, v44
	v_cvt_pk_bf16_f32 v21, v21, s0
	v_lshl_add_u64 v[18:19], v[18:19], 1, s[8:9]
	global_store_short v[18:19], v21, off sc1
	v_add_u32_e32 v18, v181, v32
	v_ashrrev_i32_e32 v19, 31, v18
	v_mul_f32_e32 v21, v48, v43
	v_cvt_pk_bf16_f32 v21, v21, s0
	v_lshl_add_u64 v[18:19], v[18:19], 1, s[8:9]
	global_store_short v[18:19], v21, off sc1
	v_add_u32_e32 v18, v71, v32
	v_ashrrev_i32_e32 v19, 31, v18
	v_mul_f32_e32 v21, v48, v42
	v_cvt_pk_bf16_f32 v21, v21, s0
	v_lshl_add_u64 v[18:19], v[18:19], 1, s[8:9]
	global_store_short v[18:19], v21, off sc1
	v_add_u32_e32 v18, v182, v32
	v_ashrrev_i32_e32 v19, 31, v18
	v_mul_f32_e32 v21, v48, v41
	v_cvt_pk_bf16_f32 v21, v21, s0
	v_lshl_add_u64 v[18:19], v[18:19], 1, s[8:9]
	global_store_short v[18:19], v21, off sc1
	v_add_u32_e32 v18, v184, v32
	v_ashrrev_i32_e32 v19, 31, v18
	v_mul_f32_e32 v21, v48, v40
	v_cvt_pk_bf16_f32 v21, v21, s0
	v_lshl_add_u64 v[18:19], v[18:19], 1, s[8:9]
	global_store_short v[18:19], v21, off sc1
	v_add_u32_e32 v18, v187, v32
	v_ashrrev_i32_e32 v19, 31, v18
	v_mul_f32_e32 v21, v48, v39
	v_cvt_pk_bf16_f32 v21, v21, s0
	v_lshl_add_u64 v[18:19], v[18:19], 1, s[8:9]
	global_store_short v[18:19], v21, off sc1
	v_add_u32_e32 v18, v189, v32
	v_ashrrev_i32_e32 v19, 31, v18
	v_mul_f32_e32 v21, v48, v38
	v_cvt_pk_bf16_f32 v21, v21, s0
	v_lshl_add_u64 v[18:19], v[18:19], 1, s[8:9]
	global_store_short v[18:19], v21, off sc1
	v_add_u32_e32 v18, v191, v32
	v_ashrrev_i32_e32 v19, 31, v18
	v_mul_f32_e32 v21, v48, v37
	v_cvt_pk_bf16_f32 v21, v21, s0
	v_lshl_add_u64 v[18:19], v[18:19], 1, s[8:9]
	global_store_short v[18:19], v21, off sc1
	v_add_u32_e32 v18, v192, v32
	v_ashrrev_i32_e32 v19, 31, v18
	v_mul_f32_e32 v21, v48, v36
	v_cvt_pk_bf16_f32 v21, v21, s0
	v_lshl_add_u64 v[18:19], v[18:19], 1, s[8:9]
	global_load_dword v28, v[88:89], off offset:384
	global_load_dword v27, v[84:85], off offset:384
	global_load_dword v25, v[78:79], off offset:384
	global_load_dword v24, v[72:73], off offset:384
	global_load_dword v23, v[74:75], off offset:384
	v_mul_f32_e32 v30, v48, v33
	global_store_short v[18:19], v21, off sc1
	v_add_u32_e32 v18, v193, v32
	v_ashrrev_i32_e32 v19, 31, v18
	v_mul_f32_e32 v21, v48, v35
	v_cvt_pk_bf16_f32 v21, v21, s0
	v_lshl_add_u64 v[18:19], v[18:19], 1, s[8:9]
	global_store_short v[18:19], v21, off sc1
	v_add_u32_e32 v18, v194, v32
	v_ashrrev_i32_e32 v19, 31, v18
	v_mul_f32_e32 v21, v48, v34
	v_cvt_pk_bf16_f32 v21, v21, s0
	v_lshl_add_u64 v[18:19], v[18:19], 1, s[8:9]
	global_store_short v[18:19], v21, off sc1
	v_add_u32_e32 v18, v195, v32
	global_load_dword v21, v[80:81], off offset:384
	global_load_dword v22, v[76:77], off offset:384
	v_ashrrev_i32_e32 v19, 31, v18
	v_cvt_pk_bf16_f32 v30, v30, s0
	v_lshl_add_u64 v[18:19], v[18:19], 1, s[8:9]
	s_waitcnt vmcnt(19)
	v_add_f32_e32 v17, 1.0, v17
	s_waitcnt vmcnt(18)
	v_mul_f32_e32 v32, v20, v17
	global_load_dword v20, v[86:87], off offset:384
	global_load_dword v26, v[82:83], off offset:384
	v_fmac_f32_e32 v29, v0, v102
	global_store_short v[18:19], v30, off sc1
	v_add_u32_e32 v18, v190, v16
	v_ashrrev_i32_e32 v19, 31, v18
	v_mul_f32_e32 v0, v32, v29
	v_cvt_pk_bf16_f32 v0, v0, s0
	v_lshl_add_u64 v[18:19], v[18:19], 1, s[8:9]
	global_store_short v[18:19], v0, off sc1
	global_load_dword v19, v[90:91], off offset:384
	v_add_u32_e32 v30, v188, v16
	global_load_dword v18, v[92:93], off offset:384
	v_ashrrev_i32_e32 v31, 31, v30
	v_fmac_f32_e32 v108, v202, v202
	v_fmac_f32_e32 v108, v116, v116
	v_fmac_f32_e32 v108, v29, v29
	global_store_dword v[106:107], v29, off offset:384 sc1
	s_waitcnt vmcnt(16)
	v_fmac_f32_e32 v28, v1, v102
	v_mul_f32_e32 v0, v32, v28
	v_cvt_pk_bf16_f32 v17, v0, s0
	v_lshl_add_u64 v[0:1], v[30:31], 1, s[8:9]
	global_store_short v[0:1], v17, off sc1
	v_add_u32_e32 v0, v186, v16
	s_waitcnt vmcnt(16)
	v_fmac_f32_e32 v27, v2, v102
	global_load_dword v17, v[94:95], off offset:384
	v_ashrrev_i32_e32 v1, 31, v0
	v_mul_f32_e32 v2, v32, v27
	v_cvt_pk_bf16_f32 v2, v2, s0
	v_lshl_add_u64 v[0:1], v[0:1], 1, s[8:9]
	global_store_short v[0:1], v2, off sc1
	v_add_u32_e32 v0, v185, v16
	global_load_dword v2, v[96:97], off offset:384
	v_ashrrev_i32_e32 v1, 31, v0
	v_lshl_add_u64 v[0:1], v[0:1], 1, s[8:9]
	v_add_u32_e32 v30, v183, v16
	s_waitcnt vmcnt(18)
	v_fmac_f32_e32 v25, v4, v102
	v_ashrrev_i32_e32 v31, 31, v30
	v_lshl_add_u64 v[30:31], v[30:31], 1, s[8:9]
	s_waitcnt vmcnt(17)
	v_fmac_f32_e32 v24, v5, v102
	s_waitcnt vmcnt(16)
	v_fmac_f32_e32 v23, v6, v102
	s_waitcnt vmcnt(11)
	v_fmac_f32_e32 v22, v7, v102
	v_fmac_f32_e32 v21, v8, v102
	global_store_dword v[88:89], v28, off offset:384 sc1
	global_store_dword v[84:85], v27, off offset:384 sc1
	s_waitcnt vmcnt(12)
	v_fmac_f32_e32 v20, v9, v102
	s_waitcnt vmcnt(11)
	v_fmac_f32_e32 v26, v3, v102
	v_mul_f32_e32 v3, v32, v26
	v_cvt_pk_bf16_f32 v3, v3, s0
	global_store_short v[0:1], v3, off sc1
	global_load_dword v1, v[98:99], off offset:384
	v_mul_f32_e32 v0, v32, v25
	v_cvt_pk_bf16_f32 v0, v0, s0
	global_store_short v[30:31], v0, off sc1
	global_load_dword v0, v[100:101], off offset:384
	v_add_u32_e32 v30, v181, v16
	v_ashrrev_i32_e32 v31, 31, v30
	v_mul_f32_e32 v3, v32, v24
	v_cvt_pk_bf16_f32 v3, v3, s0
	v_lshl_add_u64 v[4:5], v[30:31], 1, s[8:9]
	global_store_short v[4:5], v3, off sc1
	v_add_u32_e32 v4, v71, v16
	v_ashrrev_i32_e32 v5, 31, v4
	v_mul_f32_e32 v3, v32, v23
	v_cvt_pk_bf16_f32 v3, v3, s0
	v_lshl_add_u64 v[4:5], v[4:5], 1, s[8:9]
	global_store_short v[4:5], v3, off sc1
	v_add_u32_e32 v4, v182, v16
	v_ashrrev_i32_e32 v5, 31, v4
	v_mul_f32_e32 v3, v32, v22
	v_cvt_pk_bf16_f32 v3, v3, s0
	v_lshl_add_u64 v[4:5], v[4:5], 1, s[8:9]
	global_store_short v[4:5], v3, off sc1
	v_add_u32_e32 v4, v184, v16
	v_ashrrev_i32_e32 v5, 31, v4
	v_mul_f32_e32 v3, v32, v21
	v_cvt_pk_bf16_f32 v3, v3, s0
	v_lshl_add_u64 v[4:5], v[4:5], 1, s[8:9]
	global_store_short v[4:5], v3, off sc1
	v_add_u32_e32 v4, v187, v16
	v_ashrrev_i32_e32 v5, 31, v4
	v_mul_f32_e32 v3, v32, v20
	v_cvt_pk_bf16_f32 v3, v3, s0
	v_lshl_add_u64 v[4:5], v[4:5], 1, s[8:9]
	global_store_short v[4:5], v3, off sc1
	v_add_u32_e32 v4, v189, v16
	s_waitcnt vmcnt(17)
	v_fmac_f32_e32 v19, v10, v102
	v_ashrrev_i32_e32 v5, 31, v4
	v_mul_f32_e32 v3, v32, v19
	v_cvt_pk_bf16_f32 v3, v3, s0
	v_lshl_add_u64 v[4:5], v[4:5], 1, s[8:9]
	global_store_short v[4:5], v3, off sc1
	v_add_u32_e32 v4, v191, v16
	s_waitcnt vmcnt(17)
	v_fmac_f32_e32 v18, v11, v102
	v_ashrrev_i32_e32 v5, 31, v4
	v_mul_f32_e32 v3, v32, v18
	v_cvt_pk_bf16_f32 v3, v3, s0
	v_lshl_add_u64 v[4:5], v[4:5], 1, s[8:9]
	global_store_short v[4:5], v3, off sc1
	v_add_u32_e32 v4, v192, v16
	v_ashrrev_i32_e32 v5, 31, v4
	v_lshl_add_u64 v[4:5], v[4:5], 1, s[8:9]
	v_add_u32_e32 v10, v195, v16
	v_ashrrev_i32_e32 v11, 31, v10
	v_lshl_add_u64 v[10:11], v[10:11], 1, s[8:9]
	s_waitcnt vmcnt(15)
	v_fmac_f32_e32 v17, v12, v102
	v_mul_f32_e32 v3, v32, v17
	v_cvt_pk_bf16_f32 v3, v3, s0
	global_store_short v[4:5], v3, off sc1
	v_add_u32_e32 v4, v193, v16
	v_ashrrev_i32_e32 v5, 31, v4
	v_lshl_add_u64 v[4:5], v[4:5], 1, s[8:9]
	s_waitcnt vmcnt(14)
	v_fmac_f32_e32 v2, v13, v102
	v_mul_f32_e32 v3, v32, v2
	v_cvt_pk_bf16_f32 v3, v3, s0
	global_store_short v[4:5], v3, off sc1
	v_add_u32_e32 v4, v194, v16
	v_ashrrev_i32_e32 v5, 31, v4
	v_lshl_add_u64 v[4:5], v[4:5], 1, s[8:9]
	v_xor_b32_e32 v13, 16, v166
	v_ashrrev_i32_e32 v71, 31, v70
	global_store_dword v[82:83], v26, off offset:384 sc1
	global_store_dword v[78:79], v25, off offset:384 sc1
	global_store_dword v[72:73], v24, off offset:384 sc1
	global_store_dword v[74:75], v23, off offset:384 sc1
	global_store_dword v[76:77], v22, off offset:384 sc1
	global_store_dword v[80:81], v21, off offset:384 sc1
	global_store_dword v[86:87], v20, off offset:384 sc1
	global_store_dword v[90:91], v19, off offset:384 sc1
	global_store_dword v[92:93], v18, off offset:384 sc1
	s_waitcnt vmcnt(20)
	v_fmac_f32_e32 v1, v14, v102
	v_mul_f32_e32 v3, v32, v1
	v_cvt_pk_bf16_f32 v3, v3, s0
	global_store_short v[4:5], v3, off sc1
	v_and_b32_e32 v4, 64, v166
	v_xor_b32_e32 v3, 1, v166
	v_add_u32_e32 v7, 64, v4
	v_cmp_lt_i32_e32 vcc, v3, v7
	v_xor_b32_e32 v4, 2, v166
	s_waitcnt vmcnt(19)
	v_fmac_f32_e32 v0, v15, v102
	v_cndmask_b32_e32 v3, v166, v3, vcc
	v_lshlrev_b32_e32 v3, 2, v3
	ds_bpermute_b32 v5, v3, v108
	v_cmp_lt_i32_e32 vcc, v4, v7
	v_mul_f32_e32 v12, v32, v0
	v_cvt_pk_bf16_f32 v12, v12, s0
	v_cndmask_b32_e32 v4, v166, v4, vcc
	v_lshlrev_b32_e32 v4, 2, v4
	s_waitcnt lgkmcnt(0)
	v_add_f32_e32 v6, v108, v5
	ds_bpermute_b32 v8, v4, v6
	v_xor_b32_e32 v5, 4, v166
	v_cmp_lt_i32_e32 vcc, v5, v7
	global_store_dword v[94:95], v17, off offset:384 sc1
	global_store_dword v[96:97], v2, off offset:384 sc1
	v_cndmask_b32_e32 v5, v166, v5, vcc
	v_lshlrev_b32_e32 v5, 2, v5
	s_waitcnt lgkmcnt(0)
	v_add_f32_e32 v8, v6, v8
	ds_bpermute_b32 v9, v5, v8
	v_xor_b32_e32 v6, 8, v166
	v_cmp_lt_i32_e32 vcc, v6, v7
	global_store_dword v[98:99], v1, off offset:384 sc1
	global_store_dword v[100:101], v0, off offset:384 sc1
	v_cndmask_b32_e32 v6, v166, v6, vcc
	v_lshlrev_b32_e32 v6, 2, v6
	s_waitcnt lgkmcnt(0)
	v_add_f32_e32 v8, v8, v9
	ds_bpermute_b32 v9, v6, v8
	v_cmp_lt_i32_e32 vcc, v13, v7
	global_store_short v[10:11], v12, off sc1
	s_waitcnt lgkmcnt(0)
	v_add_f32_e32 v8, v8, v9
	v_cndmask_b32_e32 v7, v166, v13, vcc
	v_lshlrev_b32_e32 v7, 2, v7
	ds_bpermute_b32 v9, v7, v8
	s_and_saveexec_b64 s[60:61], s[0:1]
	s_cbranch_execz .LBB0_709
	s_waitcnt lgkmcnt(0)
	v_add_f32_e32 v10, v8, v9
	v_lshl_add_u64 v[8:9], v[70:71], 2, s[58:59]
	global_store_dword v[8:9], v10, off sc1

.LBB0_779:
	s_add_i32 s58, s67, 0xffffe000
	s_lshr_b32 s58, s58, 12
	s_mulk_i32 s58, 0x1800
	s_addk_i32 s58, 0x1800
	s_cmp_gt_i32 s6, 63
	s_cselect_b32 s6, s58, 0
	s_lshl_b64 s[58:59], s[6:7], 2
	s_add_u32 s58, s14, s58
	s_addc_u32 s59, s15, s59
	s_add_u32 s60, s58, 0x5ba5000
	s_addc_u32 s61, s59, 0
	s_addk_i32 s6, 0x4800
	s_lshl_b64 s[58:59], s[6:7], 2
	v_mov_b32_e32 v70, s66
	s_add_u32 s6, s14, s58
	ds_read_b64 v[70:71], v70
	s_addc_u32 s65, s15, s59
	s_lshl_b32 s58, s64, 14
	s_add_i32 s58, s58, 0x40000
	s_ashr_i32 s59, s58, 31
	s_lshl_b64 s[58:59], s[58:59], 2
	s_add_u32 s58, s10, s58
	s_waitcnt lgkmcnt(0)
	v_readfirstlane_b32 s62, v70
	s_addc_u32 s59, s11, s59
	v_or_b32_e32 v102, s68, v138
	v_add_u32_e32 v70, s67, v139
	v_readfirstlane_b32 s63, v71
	s_add_u32 s62, s62, 0x1000
	v_ashrrev_i32_e32 v103, 31, v102
	v_lshlrev_b32_e32 v191, 10, v70
	s_addc_u32 s63, s63, 0
	v_lshlrev_b64 v[72:73], 2, v[102:103]
	v_or_b32_e32 v187, 0x400, v191
	v_or_b32_e32 v186, 0x4400, v191
	v_or_b32_e32 v189, 0x4c00, v191
	v_or_b32_e32 v194, 0x6c00, v191
	s_add_u32 s64, s6, 0x5ba1000
	v_lshl_add_u64 v[74:75], s[60:61], 0, v[72:73]
	v_add_u32_e32 v130, v191, v102
	v_add_u32_e32 v132, v187, v102
	v_or_b32_e32 v185, 0x800, v191
	v_or_b32_e32 v184, 0xc00, v191
	v_or_b32_e32 v182, 0x2000, v191
	v_or_b32_e32 v180, 0x2400, v191
	v_or_b32_e32 v71, 0x2800, v191
	v_or_b32_e32 v181, 0x2c00, v191
	v_or_b32_e32 v183, 0x4000, v191
	v_add_u32_e32 v112, v186, v102
	v_or_b32_e32 v188, 0x4800, v191
	v_add_u32_e32 v116, v189, v102
	v_or_b32_e32 v190, 0x6000, v191
	v_or_b32_e32 v192, 0x6400, v191
	v_or_b32_e32 v193, 0x6800, v191
	v_add_u32_e32 v128, v194, v102
	s_addc_u32 s65, s65, 0
	global_load_dword v195, v[74:75], off
	v_lshl_add_u64 v[74:75], s[62:63], 0, v[72:73]
	v_ashrrev_i32_e32 v133, 31, v132
	v_add_u32_e32 v134, v185, v102
	v_add_u32_e32 v136, v184, v102
	v_add_u32_e32 v126, v182, v102
	v_add_u32_e32 v118, v180, v102
	v_add_u32_e32 v110, v71, v102
	v_add_u32_e32 v106, v181, v102
	v_add_u32_e32 v108, v183, v102
	v_ashrrev_i32_e32 v113, 31, v112
	v_add_u32_e32 v114, v188, v102
	v_ashrrev_i32_e32 v117, 31, v116
	v_add_u32_e32 v120, v190, v102
	v_add_u32_e32 v122, v192, v102
	v_add_u32_e32 v124, v193, v102
	v_ashrrev_i32_e32 v129, 31, v128
	v_ashrrev_i32_e32 v131, 31, v130
	v_lshl_add_u64 v[72:73], s[64:65], 0, v[72:73]
	global_load_dword v196, v[74:75], off
	global_load_dword v197, v[72:73], off
	v_lshl_add_u64 v[88:89], v[132:133], 2, s[12:13]
	v_ashrrev_i32_e32 v135, 31, v134
	v_ashrrev_i32_e32 v137, 31, v136
	v_ashrrev_i32_e32 v127, 31, v126
	v_ashrrev_i32_e32 v119, 31, v118
	v_ashrrev_i32_e32 v111, 31, v110
	v_ashrrev_i32_e32 v107, 31, v106
	v_ashrrev_i32_e32 v109, 31, v108
	v_lshl_add_u64 v[86:87], v[112:113], 2, s[12:13]
	v_ashrrev_i32_e32 v115, 31, v114
	v_lshl_add_u64 v[92:93], v[116:117], 2, s[12:13]
	v_ashrrev_i32_e32 v121, 31, v120
	v_ashrrev_i32_e32 v123, 31, v122
	v_ashrrev_i32_e32 v125, 31, v124
	v_lshl_add_u64 v[100:101], v[128:129], 2, s[12:13]
	v_lshl_add_u64 v[104:105], v[130:131], 2, s[12:13]
	v_lshl_add_u64 v[84:85], v[134:135], 2, s[12:13]
	v_lshl_add_u64 v[82:83], v[136:137], 2, s[12:13]
	v_lshl_add_u64 v[78:79], v[126:127], 2, s[12:13]
	v_lshl_add_u64 v[72:73], v[118:119], 2, s[12:13]
	v_lshl_add_u64 v[74:75], v[110:111], 2, s[12:13]
	v_lshl_add_u64 v[76:77], v[106:107], 2, s[12:13]
	v_lshl_add_u64 v[80:81], v[108:109], 2, s[12:13]
	global_load_dword v179, v[88:89], off
	global_load_dword v178, v[84:85], off
	global_load_dword v177, v[82:83], off
	global_load_dword v176, v[78:79], off
	global_load_dword v175, v[72:73], off
	global_load_dword v174, v[74:75], off
	global_load_dword v173, v[76:77], off
	global_load_dword v172, v[80:81], off
	v_lshl_add_u64 v[90:91], v[114:115], 2, s[12:13]
	global_load_dword v171, v[86:87], off
	global_load_dword v169, v[90:91], off
	v_lshl_add_u64 v[94:95], v[120:121], 2, s[12:13]
	v_lshl_add_u64 v[96:97], v[122:123], 2, s[12:13]
	v_lshl_add_u64 v[98:99], v[124:125], 2, s[12:13]
	global_load_dword v170, v[92:93], off
	global_load_dword v168, v[94:95], off
	global_load_dword v167, v[96:97], off
	global_load_dword v166, v[98:99], off
	global_load_dword v103, v[100:101], off
	global_load_dword v198, v[104:105], off
	v_lshl_add_u64 v[110:111], v[110:111], 1, s[8:9]
	v_lshl_add_u64 v[106:107], v[106:107], 1, s[8:9]
	global_load_dword v255, v[88:89], off offset:128
	global_load_dword v255, v[88:89], off offset:256
	global_load_dword v255, v[88:89], off offset:384
	global_load_dword v255, v[84:85], off offset:128
	global_load_dword v255, v[84:85], off offset:256
	global_load_dword v255, v[84:85], off offset:384
	global_load_dword v255, v[82:83], off offset:128
	global_load_dword v255, v[82:83], off offset:256
	global_load_dword v255, v[82:83], off offset:384
	global_load_dword v255, v[78:79], off offset:128
	global_load_dword v255, v[78:79], off offset:256
	global_load_dword v255, v[78:79], off offset:384
	global_load_dword v255, v[72:73], off offset:128
	global_load_dword v255, v[72:73], off offset:256
	global_load_dword v255, v[72:73], off offset:384
	global_load_dword v255, v[74:75], off offset:128
	global_load_dword v255, v[74:75], off offset:256
	global_load_dword v255, v[74:75], off offset:384
	global_load_dword v255, v[76:77], off offset:128
	global_load_dword v255, v[76:77], off offset:256
	global_load_dword v255, v[76:77], off offset:384
	global_load_dword v255, v[80:81], off offset:128
	global_load_dword v255, v[80:81], off offset:256
	global_load_dword v255, v[80:81], off offset:384
	global_load_dword v255, v[86:87], off offset:128
	global_load_dword v255, v[86:87], off offset:256
	global_load_dword v255, v[86:87], off offset:384
	global_load_dword v255, v[90:91], off offset:128
	global_load_dword v255, v[90:91], off offset:256
	global_load_dword v255, v[90:91], off offset:384
	global_load_dword v255, v[92:93], off offset:128
	global_load_dword v255, v[92:93], off offset:256
	global_load_dword v255, v[92:93], off offset:384
	global_load_dword v255, v[94:95], off offset:128
	global_load_dword v255, v[94:95], off offset:256
	global_load_dword v255, v[94:95], off offset:384
	global_load_dword v255, v[96:97], off offset:128
	global_load_dword v255, v[96:97], off offset:256
	global_load_dword v255, v[96:97], off offset:384
	global_load_dword v255, v[98:99], off offset:128
	global_load_dword v255, v[98:99], off offset:256
	global_load_dword v255, v[98:99], off offset:384
	global_load_dword v255, v[100:101], off offset:128
	global_load_dword v255, v[100:101], off offset:256
	global_load_dword v255, v[100:101], off offset:384
	global_load_dword v255, v[104:105], off offset:128
	global_load_dword v255, v[104:105], off offset:256
	global_load_dword v255, v[104:105], off offset:384
	s_waitcnt vmcnt(0)
	v_add_f32_e32 v197, 1.0, v197
	v_mul_f32_e32 v196, v196, v197
	v_fmac_f32_e32 v179, v49, v195
	v_fmac_f32_e32 v178, v50, v195
	v_fmac_f32_e32 v177, v51, v195
	v_fmac_f32_e32 v176, v52, v195
	v_fmac_f32_e32 v175, v53, v195
	v_fmac_f32_e32 v174, v54, v195
	v_fmac_f32_e32 v173, v55, v195
	v_fmac_f32_e32 v172, v56, v195
	v_fmac_f32_e32 v171, v57, v195
	v_fmac_f32_e32 v169, v58, v195
	v_fmac_f32_e32 v170, v59, v195
	v_fmac_f32_e32 v168, v60, v195
	v_fmac_f32_e32 v167, v61, v195
	v_fmac_f32_e32 v166, v62, v195
	v_fmac_f32_e32 v103, v63, v195
	v_fmac_f32_e32 v198, v48, v195
	v_mul_f32_e32 v48, v196, v198
	v_cvt_pk_bf16_f32 v58, v48, s0
	v_or_b32_e32 v48, 32, v102
	v_ashrrev_i32_e32 v49, 31, v48
	v_lshlrev_b64 v[52:53], 2, v[48:49]
	global_store_dword v[88:89], v179, off sc1
	global_store_dword v[84:85], v178, off sc1
	global_store_dword v[82:83], v177, off sc1
	global_store_dword v[78:79], v176, off sc1
	global_store_dword v[72:73], v175, off sc1
	global_store_dword v[74:75], v174, off sc1
	global_store_dword v[76:77], v173, off sc1
	global_store_dword v[80:81], v172, off sc1
	global_store_dword v[86:87], v171, off sc1
	global_store_dword v[90:91], v169, off sc1
	global_store_dword v[92:93], v170, off sc1
	global_store_dword v[94:95], v168, off sc1
	global_store_dword v[96:97], v167, off sc1
	global_store_dword v[98:99], v166, off sc1
	global_store_dword v[100:101], v103, off sc1
	global_store_dword v[104:105], v198, off sc1
	v_lshl_add_u64 v[50:51], v[130:131], 1, s[8:9]
	v_lshl_add_u64 v[56:57], s[64:65], 0, v[52:53]
	global_load_dword v197, v[104:105], off offset:128
	v_lshl_add_u64 v[54:55], s[62:63], 0, v[52:53]
	global_load_dword v130, v[56:57], off
	global_load_dword v131, v[54:55], off
	v_mul_f32_e32 v49, v196, v179
	global_store_short v[50:51], v58, off sc1
	v_lshl_add_u64 v[50:51], s[60:61], 0, v[52:53]
	global_load_dword v195, v[50:51], off
	v_lshl_add_u64 v[50:51], v[132:133], 1, s[8:9]
	v_cvt_pk_bf16_f32 v49, v49, s0
	global_store_short v[50:51], v49, off sc1
	v_mul_f32_e32 v49, v196, v178
	v_lshl_add_u64 v[50:51], v[134:135], 1, s[8:9]
	v_cvt_pk_bf16_f32 v49, v49, s0
	global_store_short v[50:51], v49, off sc1
	v_mul_f32_e32 v49, v196, v177
	v_lshl_add_u64 v[50:51], v[136:137], 1, s[8:9]
	v_cvt_pk_bf16_f32 v49, v49, s0
	global_store_short v[50:51], v49, off sc1
	v_mul_f32_e32 v49, v196, v176
	v_lshl_add_u64 v[50:51], v[126:127], 1, s[8:9]
	v_cvt_pk_bf16_f32 v49, v49, s0
	global_store_short v[50:51], v49, off sc1
	v_mul_f32_e32 v49, v196, v175
	v_lshl_add_u64 v[50:51], v[118:119], 1, s[8:9]
	v_cvt_pk_bf16_f32 v49, v49, s0
	global_load_dword v62, v[84:85], off offset:128
	global_load_dword v60, v[78:79], off offset:128
	global_load_dword v59, v[72:73], off offset:128
	global_load_dword v58, v[74:75], off offset:128
	global_load_dword v56, v[80:81], off offset:128
	global_load_dword v57, v[76:77], off offset:128
	global_load_dword v55, v[86:87], off offset:128
	global_load_dword v61, v[82:83], off offset:128
	global_load_dword v54, v[90:91], off offset:128
	global_load_dword v53, v[92:93], off offset:128
	global_load_dword v52, v[94:95], off offset:128
	v_mul_f32_e32 v63, v196, v174
	global_store_short v[50:51], v49, off sc1
	global_load_dword v51, v[96:97], off offset:128
	v_cvt_pk_bf16_f32 v63, v63, s0
	global_load_dword v50, v[98:99], off offset:128
	global_load_dword v49, v[100:101], off offset:128
	s_waitcnt vmcnt(19)
	v_fmac_f32_e32 v197, v32, v195
	global_store_short v[110:111], v63, off sc1
	global_load_dword v63, v[88:89], off offset:128
	v_mul_f32_e32 v110, v196, v173
	v_cvt_pk_bf16_f32 v110, v110, s0
	global_store_short v[106:107], v110, off sc1
	v_lshl_add_u64 v[106:107], v[108:109], 1, s[8:9]
	v_mul_f32_e32 v108, v196, v172
	v_cvt_pk_bf16_f32 v108, v108, s0
	global_store_short v[106:107], v108, off sc1
	v_mul_f32_e32 v108, v196, v171
	v_lshl_add_u64 v[106:107], v[112:113], 1, s[8:9]
	v_cvt_pk_bf16_f32 v108, v108, s0
	global_store_short v[106:107], v108, off sc1
	v_mul_f32_e32 v108, v196, v169
	v_lshl_add_u64 v[106:107], v[114:115], 1, s[8:9]
	v_cvt_pk_bf16_f32 v108, v108, s0
	global_store_short v[106:107], v108, off sc1
	v_mul_f32_e32 v108, v196, v170
	v_lshl_add_u64 v[106:107], v[116:117], 1, s[8:9]
	v_cvt_pk_bf16_f32 v108, v108, s0
	global_store_short v[106:107], v108, off sc1
	v_mul_f32_e32 v108, v196, v168
	v_lshl_add_u64 v[106:107], v[120:121], 1, s[8:9]
	v_cvt_pk_bf16_f32 v108, v108, s0
	global_store_short v[106:107], v108, off sc1
	v_mul_f32_e32 v108, v196, v167
	v_lshl_add_u64 v[106:107], v[122:123], 1, s[8:9]
	v_cvt_pk_bf16_f32 v108, v108, s0
	global_store_short v[106:107], v108, off sc1
	v_mul_f32_e32 v108, v196, v166
	v_lshl_add_u64 v[106:107], v[124:125], 1, s[8:9]
	v_cvt_pk_bf16_f32 v108, v108, s0
	global_store_short v[106:107], v108, off sc1
	v_mul_f32_e32 v108, v196, v103
	v_lshl_add_u64 v[106:107], v[128:129], 1, s[8:9]
	v_cvt_pk_bf16_f32 v108, v108, s0
	global_store_short v[106:107], v108, off sc1
	v_add_f32_e32 v106, 1.0, v130
	v_mul_f32_e32 v107, v131, v106
	v_add_u32_e32 v108, v191, v48
	v_ashrrev_i32_e32 v109, 31, v108
	v_mul_f32_e32 v32, v107, v197
	s_waitcnt vmcnt(25)
	v_fmac_f32_e32 v62, v34, v195
	s_waitcnt vmcnt(18)
	v_fmac_f32_e32 v61, v35, v195
	v_fmac_f32_e32 v60, v36, v195
	v_fmac_f32_e32 v59, v37, v195
	v_fmac_f32_e32 v58, v38, v195
	v_fmac_f32_e32 v57, v39, v195
	v_fmac_f32_e32 v56, v40, v195
	v_fmac_f32_e32 v55, v41, v195
	s_waitcnt vmcnt(17)
	v_fmac_f32_e32 v54, v42, v195
	s_waitcnt vmcnt(16)
	v_fmac_f32_e32 v53, v43, v195
	s_waitcnt vmcnt(15)
	v_fmac_f32_e32 v52, v44, v195
	s_waitcnt vmcnt(13)
	v_fmac_f32_e32 v51, v45, v195
	s_waitcnt vmcnt(12)
	v_fmac_f32_e32 v50, v46, v195
	s_waitcnt vmcnt(11)
	v_fmac_f32_e32 v49, v47, v195
	global_store_dword v[104:105], v197, off offset:128 sc1
	v_lshl_add_u64 v[108:109], v[108:109], 1, s[8:9]
	v_cvt_pk_bf16_f32 v32, v32, s0
	global_store_dword v[84:85], v62, off offset:128 sc1
	global_store_dword v[82:83], v61, off offset:128 sc1
	global_store_dword v[78:79], v60, off offset:128 sc1
	global_store_dword v[72:73], v59, off offset:128 sc1
	global_store_dword v[74:75], v58, off offset:128 sc1
	global_store_dword v[76:77], v57, off offset:128 sc1
	global_store_dword v[80:81], v56, off offset:128 sc1
	global_store_dword v[86:87], v55, off offset:128 sc1
	global_store_dword v[90:91], v54, off offset:128 sc1
	global_store_dword v[92:93], v53, off offset:128 sc1
	global_store_dword v[94:95], v52, off offset:128 sc1
	global_store_dword v[96:97], v51, off offset:128 sc1
	global_store_dword v[98:99], v50, off offset:128 sc1
	global_store_dword v[100:101], v49, off offset:128 sc1
	global_store_short v[108:109], v32, off sc1
	v_add_u32_e32 v108, v187, v48
	global_load_dword v45, v[88:89], off offset:256
	v_ashrrev_i32_e32 v109, 31, v108
	v_mul_f32_e32 v113, v107, v56
	v_cvt_pk_bf16_f32 v113, v113, s0
	v_mul_f32_e32 v106, v197, v197
	v_fmac_f32_e32 v106, v198, v198
	s_waitcnt vmcnt(26)
	v_fmac_f32_e32 v63, v33, v195
	v_mul_f32_e32 v34, v107, v63
	v_lshl_add_u64 v[32:33], v[108:109], 1, s[8:9]
	v_cvt_pk_bf16_f32 v34, v34, s0
	global_store_short v[32:33], v34, off sc1
	v_add_u32_e32 v32, v185, v48
	v_ashrrev_i32_e32 v33, 31, v32
	v_mul_f32_e32 v34, v107, v62
	v_lshl_add_u64 v[32:33], v[32:33], 1, s[8:9]
	v_cvt_pk_bf16_f32 v34, v34, s0
	global_store_short v[32:33], v34, off sc1
	v_add_u32_e32 v32, v184, v48
	v_ashrrev_i32_e32 v33, 31, v32
	v_mul_f32_e32 v34, v107, v61
	v_lshl_add_u64 v[32:33], v[32:33], 1, s[8:9]
	v_cvt_pk_bf16_f32 v34, v34, s0
	global_store_short v[32:33], v34, off sc1
	v_add_u32_e32 v32, v182, v48
	v_ashrrev_i32_e32 v33, 31, v32
	v_mul_f32_e32 v34, v107, v60
	v_lshl_add_u64 v[32:33], v[32:33], 1, s[8:9]
	v_cvt_pk_bf16_f32 v34, v34, s0
	global_store_short v[32:33], v34, off sc1
	v_add_u32_e32 v32, v180, v48
	v_ashrrev_i32_e32 v33, 31, v32
	v_lshl_add_u64 v[34:35], v[32:33], 1, s[8:9]
	v_mul_f32_e32 v32, v107, v59
	v_cvt_pk_bf16_f32 v42, v32, s0
	v_or_b32_e32 v32, 64, v102
	v_ashrrev_i32_e32 v33, 31, v32
	v_lshlrev_b64 v[36:37], 2, v[32:33]
	global_store_dword v[88:89], v63, off offset:128 sc1
	v_lshl_add_u64 v[40:41], s[64:65], 0, v[36:37]
	v_lshl_add_u64 v[38:39], s[62:63], 0, v[36:37]
	global_load_dword v110, v[40:41], off
	global_load_dword v111, v[38:39], off
	v_mul_f32_e32 v33, v107, v58
	global_store_short v[34:35], v42, off sc1
	v_lshl_add_u64 v[34:35], s[60:61], 0, v[36:37]
	global_load_dword v112, v[34:35], off
	v_add_u32_e32 v34, v71, v48
	v_ashrrev_i32_e32 v35, 31, v34
	v_lshl_add_u64 v[34:35], v[34:35], 1, s[8:9]
	v_cvt_pk_bf16_f32 v33, v33, s0
	global_store_short v[34:35], v33, off sc1
	v_add_u32_e32 v34, v181, v48
	v_ashrrev_i32_e32 v35, 31, v34
	v_mul_f32_e32 v33, v107, v57
	v_lshl_add_u64 v[34:35], v[34:35], 1, s[8:9]
	v_cvt_pk_bf16_f32 v33, v33, s0
	global_load_dword v38, v[90:91], off offset:256
	global_load_dword v37, v[92:93], off offset:256
	global_load_dword v36, v[94:95], off offset:256
	global_load_dword v114, v[104:105], off offset:256
	global_load_dword v47, v[84:85], off offset:256
	global_load_dword v39, v[86:87], off offset:256
	global_load_dword v46, v[82:83], off offset:256
	global_load_dword v44, v[78:79], off offset:256
	global_load_dword v43, v[72:73], off offset:256
	global_load_dword v42, v[74:75], off offset:256
	global_load_dword v40, v[80:81], off offset:256
	global_load_dword v41, v[76:77], off offset:256
	v_add_u32_e32 v108, v183, v48
	global_store_short v[34:35], v33, off sc1
	global_load_dword v35, v[96:97], off offset:256
	v_ashrrev_i32_e32 v109, 31, v108
	global_load_dword v34, v[98:99], off offset:256
	global_load_dword v33, v[100:101], off offset:256
	v_lshl_add_u64 v[108:109], v[108:109], 1, s[8:9]
	global_store_short v[108:109], v113, off sc1
	v_add_u32_e32 v108, v186, v48
	v_ashrrev_i32_e32 v109, 31, v108
	v_mul_f32_e32 v113, v107, v55
	v_lshl_add_u64 v[108:109], v[108:109], 1, s[8:9]
	v_cvt_pk_bf16_f32 v113, v113, s0
	global_store_short v[108:109], v113, off sc1
	v_add_u32_e32 v108, v188, v48
	v_ashrrev_i32_e32 v109, 31, v108
	v_mul_f32_e32 v113, v107, v54
	v_lshl_add_u64 v[108:109], v[108:109], 1, s[8:9]
	v_cvt_pk_bf16_f32 v113, v113, s0
	global_store_short v[108:109], v113, off sc1
	v_add_u32_e32 v108, v189, v48
	v_ashrrev_i32_e32 v109, 31, v108
	v_mul_f32_e32 v113, v107, v53
	v_lshl_add_u64 v[108:109], v[108:109], 1, s[8:9]
	v_cvt_pk_bf16_f32 v113, v113, s0
	global_store_short v[108:109], v113, off sc1
	v_add_u32_e32 v108, v190, v48
	v_ashrrev_i32_e32 v109, 31, v108
	v_mul_f32_e32 v113, v107, v52
	v_lshl_add_u64 v[108:109], v[108:109], 1, s[8:9]
	v_cvt_pk_bf16_f32 v113, v113, s0
	global_store_short v[108:109], v113, off sc1
	v_add_u32_e32 v108, v192, v48
	v_ashrrev_i32_e32 v109, 31, v108
	v_mul_f32_e32 v113, v107, v51
	v_lshl_add_u64 v[108:109], v[108:109], 1, s[8:9]
	v_cvt_pk_bf16_f32 v113, v113, s0
	global_store_short v[108:109], v113, off sc1
	v_add_u32_e32 v108, v193, v48
	v_ashrrev_i32_e32 v109, 31, v108
	v_mul_f32_e32 v113, v107, v50
	v_lshl_add_u64 v[108:109], v[108:109], 1, s[8:9]
	v_cvt_pk_bf16_f32 v113, v113, s0
	global_store_short v[108:109], v113, off sc1
	v_add_u32_e32 v108, v194, v48
	v_ashrrev_i32_e32 v109, 31, v108
	v_mul_f32_e32 v48, v107, v49
	v_lshl_add_u64 v[108:109], v[108:109], 1, s[8:9]
	v_cvt_pk_bf16_f32 v48, v48, s0
	global_store_short v[108:109], v48, off sc1
	v_add_u32_e32 v108, v191, v32
	v_ashrrev_i32_e32 v109, 31, v108
	s_waitcnt vmcnt(28)
	v_add_f32_e32 v48, 1.0, v110
	s_waitcnt vmcnt(27)
	v_mul_f32_e32 v48, v111, v48
	s_waitcnt vmcnt(25)
	v_fmac_f32_e32 v45, v17, v112
	global_store_dword v[88:89], v45, off offset:256 sc1
	s_waitcnt vmcnt(24)
	v_fmac_f32_e32 v38, v26, v112
	s_waitcnt vmcnt(23)
	v_fmac_f32_e32 v37, v27, v112
	s_waitcnt vmcnt(22)
	v_fmac_f32_e32 v36, v28, v112
	s_waitcnt vmcnt(21)
	v_fmac_f32_e32 v114, v16, v112
	s_waitcnt vmcnt(20)
	v_fmac_f32_e32 v47, v18, v112
	v_mul_f32_e32 v18, v48, v114
	v_lshl_add_u64 v[16:17], v[108:109], 1, s[8:9]
	v_cvt_pk_bf16_f32 v18, v18, s0
	global_store_short v[16:17], v18, off sc1
	v_add_u32_e32 v16, v187, v32
	v_ashrrev_i32_e32 v17, 31, v16
	v_mul_f32_e32 v18, v48, v45
	v_lshl_add_u64 v[16:17], v[16:17], 1, s[8:9]
	v_cvt_pk_bf16_f32 v18, v18, s0
	global_store_short v[16:17], v18, off sc1
	v_add_u32_e32 v16, v185, v32
	v_ashrrev_i32_e32 v17, 31, v16
	v_mul_f32_e32 v18, v48, v47
	v_lshl_add_u64 v[16:17], v[16:17], 1, s[8:9]
	v_cvt_pk_bf16_f32 v18, v18, s0
	s_waitcnt vmcnt(20)
	v_fmac_f32_e32 v46, v19, v112
	global_store_short v[16:17], v18, off sc1
	v_add_u32_e32 v16, v184, v32
	v_ashrrev_i32_e32 v17, 31, v16
	v_mul_f32_e32 v18, v48, v46
	v_lshl_add_u64 v[16:17], v[16:17], 1, s[8:9]
	v_cvt_pk_bf16_f32 v18, v18, s0
	global_store_short v[16:17], v18, off sc1
	v_add_u32_e32 v16, v182, v32
	v_ashrrev_i32_e32 v17, 31, v16
	v_lshl_add_u64 v[18:19], v[16:17], 1, s[8:9]
	v_or_b32_e32 v16, 0x60, v102
	v_ashrrev_i32_e32 v17, 31, v16
	s_waitcnt vmcnt(21)
	v_fmac_f32_e32 v44, v20, v112
	s_waitcnt vmcnt(20)
	v_fmac_f32_e32 v43, v21, v112
	s_waitcnt vmcnt(19)
	v_fmac_f32_e32 v42, v22, v112
	s_waitcnt vmcnt(17)
	v_fmac_f32_e32 v41, v23, v112
	v_fmac_f32_e32 v40, v24, v112
	v_fmac_f32_e32 v39, v25, v112
	s_waitcnt vmcnt(15)
	v_fmac_f32_e32 v35, v29, v112
	s_waitcnt vmcnt(14)
	v_fmac_f32_e32 v34, v30, v112
	s_waitcnt vmcnt(13)
	v_fmac_f32_e32 v33, v31, v112
	v_lshlrev_b64 v[20:21], 2, v[16:17]
	global_store_dword v[84:85], v47, off offset:256 sc1
	global_store_dword v[82:83], v46, off offset:256 sc1
	global_store_dword v[78:79], v44, off offset:256 sc1
	global_store_dword v[72:73], v43, off offset:256 sc1
	global_store_dword v[74:75], v42, off offset:256 sc1
	global_store_dword v[76:77], v41, off offset:256 sc1
	global_store_dword v[80:81], v40, off offset:256 sc1
	global_store_dword v[86:87], v39, off offset:256 sc1
	global_store_dword v[90:91], v38, off offset:256 sc1
	global_store_dword v[92:93], v37, off offset:256 sc1
	global_store_dword v[94:95], v36, off offset:256 sc1
	global_store_dword v[96:97], v35, off offset:256 sc1
	global_store_dword v[98:99], v34, off offset:256 sc1
	global_store_dword v[100:101], v33, off offset:256 sc1
	global_store_dword v[104:105], v114, off offset:256 sc1
	v_mul_f32_e32 v26, v48, v44
	v_lshl_add_u64 v[22:23], s[62:63], 0, v[20:21]
	v_lshl_add_u64 v[24:25], s[64:65], 0, v[20:21]
	global_load_dword v29, v[104:105], off offset:384
	global_load_dword v17, v[24:25], off
	global_load_dword v30, v[22:23], off
	v_cvt_pk_bf16_f32 v22, v26, s0
	global_store_short v[18:19], v22, off sc1
	v_lshl_add_u64 v[18:19], s[60:61], 0, v[20:21]
	global_load_dword v102, v[18:19], off
	v_add_u32_e32 v18, v180, v32
	v_ashrrev_i32_e32 v19, 31, v18
	v_mul_f32_e32 v20, v48, v43
	v_lshl_add_u64 v[18:19], v[18:19], 1, s[8:9]
	v_cvt_pk_bf16_f32 v20, v20, s0
	global_store_short v[18:19], v20, off sc1
	v_add_u32_e32 v18, v71, v32
	v_ashrrev_i32_e32 v19, 31, v18
	v_mul_f32_e32 v20, v48, v42
	v_lshl_add_u64 v[18:19], v[18:19], 1, s[8:9]
	v_cvt_pk_bf16_f32 v20, v20, s0
	global_store_short v[18:19], v20, off sc1
	v_add_u32_e32 v18, v181, v32
	v_ashrrev_i32_e32 v19, 31, v18
	v_mul_f32_e32 v20, v48, v41
	v_lshl_add_u64 v[18:19], v[18:19], 1, s[8:9]
	v_cvt_pk_bf16_f32 v20, v20, s0
	global_store_short v[18:19], v20, off sc1
	v_add_u32_e32 v18, v183, v32
	v_ashrrev_i32_e32 v19, 31, v18
	v_mul_f32_e32 v20, v48, v40
	v_lshl_add_u64 v[18:19], v[18:19], 1, s[8:9]
	v_cvt_pk_bf16_f32 v20, v20, s0
	global_store_short v[18:19], v20, off sc1
	v_add_u32_e32 v18, v186, v32
	v_ashrrev_i32_e32 v19, 31, v18
	v_mul_f32_e32 v20, v48, v39
	v_lshl_add_u64 v[18:19], v[18:19], 1, s[8:9]
	v_cvt_pk_bf16_f32 v20, v20, s0
	global_store_short v[18:19], v20, off sc1
	v_add_u32_e32 v18, v188, v32
	v_ashrrev_i32_e32 v19, 31, v18
	v_mul_f32_e32 v20, v48, v38
	v_lshl_add_u64 v[18:19], v[18:19], 1, s[8:9]
	v_cvt_pk_bf16_f32 v20, v20, s0
	global_store_short v[18:19], v20, off sc1
	v_add_u32_e32 v18, v189, v32
	v_ashrrev_i32_e32 v19, 31, v18
	v_mul_f32_e32 v20, v48, v37
	v_lshl_add_u64 v[18:19], v[18:19], 1, s[8:9]
	v_cvt_pk_bf16_f32 v20, v20, s0
	global_store_short v[18:19], v20, off sc1
	v_add_u32_e32 v18, v190, v32
	v_ashrrev_i32_e32 v19, 31, v18
	v_mul_f32_e32 v20, v48, v36
	v_lshl_add_u64 v[18:19], v[18:19], 1, s[8:9]
	v_cvt_pk_bf16_f32 v20, v20, s0
	global_store_short v[18:19], v20, off sc1
	v_add_u32_e32 v18, v192, v32
	v_ashrrev_i32_e32 v19, 31, v18
	v_mul_f32_e32 v20, v48, v35
	v_lshl_add_u64 v[18:19], v[18:19], 1, s[8:9]
	v_cvt_pk_bf16_f32 v20, v20, s0
	global_load_dword v28, v[88:89], off offset:384
	global_load_dword v27, v[84:85], off offset:384
	global_load_dword v25, v[78:79], off offset:384
	global_load_dword v24, v[72:73], off offset:384
	global_load_dword v23, v[74:75], off offset:384
	global_load_dword v21, v[80:81], off offset:384
	global_load_dword v22, v[76:77], off offset:384
	v_fmac_f32_e32 v106, v114, v114
	global_store_short v[18:19], v20, off sc1
	v_add_u32_e32 v18, v193, v32
	v_ashrrev_i32_e32 v19, 31, v18
	v_mul_f32_e32 v20, v48, v34
	v_lshl_add_u64 v[18:19], v[18:19], 1, s[8:9]
	v_cvt_pk_bf16_f32 v20, v20, s0
	global_store_short v[18:19], v20, off sc1
	v_add_u32_e32 v18, v194, v32
	v_ashrrev_i32_e32 v19, 31, v18
	v_mul_f32_e32 v20, v48, v33
	v_lshl_add_u64 v[18:19], v[18:19], 1, s[8:9]
	v_cvt_pk_bf16_f32 v20, v20, s0
	global_store_short v[18:19], v20, off sc1
	global_load_dword v20, v[86:87], off offset:384
	s_waitcnt vmcnt(22)
	v_add_f32_e32 v17, 1.0, v17
	global_load_dword v26, v[82:83], off offset:384
	s_waitcnt vmcnt(22)
	v_mul_f32_e32 v32, v30, v17
	v_add_u32_e32 v18, v191, v16
	s_waitcnt vmcnt(20)
	v_fmac_f32_e32 v29, v0, v102
	v_ashrrev_i32_e32 v19, 31, v18
	v_mul_f32_e32 v0, v32, v29
	v_lshl_add_u64 v[18:19], v[18:19], 1, s[8:9]
	v_cvt_pk_bf16_f32 v0, v0, s0
	global_store_short v[18:19], v0, off sc1
	global_load_dword v19, v[90:91], off offset:384
	v_add_u32_e32 v30, v187, v16
	global_load_dword v18, v[92:93], off offset:384
	v_ashrrev_i32_e32 v31, 31, v30
	v_fmac_f32_e32 v106, v29, v29
	global_store_dword v[104:105], v29, off offset:384 sc1
	s_waitcnt vmcnt(15)
	v_fmac_f32_e32 v28, v1, v102
	v_mul_f32_e32 v17, v32, v28
	v_lshl_add_u64 v[0:1], v[30:31], 1, s[8:9]
	v_cvt_pk_bf16_f32 v17, v17, s0
	global_store_short v[0:1], v17, off sc1
	v_add_u32_e32 v0, v185, v16
	s_waitcnt vmcnt(15)
	v_fmac_f32_e32 v27, v2, v102
	global_load_dword v17, v[94:95], off offset:384
	v_ashrrev_i32_e32 v1, 31, v0
	v_mul_f32_e32 v2, v32, v27
	v_lshl_add_u64 v[0:1], v[0:1], 1, s[8:9]
	v_cvt_pk_bf16_f32 v2, v2, s0
	global_store_short v[0:1], v2, off sc1
	v_add_u32_e32 v0, v184, v16
	global_load_dword v2, v[96:97], off offset:384
	v_ashrrev_i32_e32 v1, 31, v0
	v_lshl_add_u64 v[0:1], v[0:1], 1, s[8:9]
	v_add_u32_e32 v30, v182, v16
	s_waitcnt vmcnt(17)
	v_fmac_f32_e32 v25, v4, v102
	v_ashrrev_i32_e32 v31, 31, v30
	v_lshl_add_u64 v[30:31], v[30:31], 1, s[8:9]
	s_waitcnt vmcnt(16)
	v_fmac_f32_e32 v24, v5, v102
	s_waitcnt vmcnt(15)
	v_fmac_f32_e32 v23, v6, v102
	s_waitcnt vmcnt(8)
	v_fmac_f32_e32 v26, v3, v102
	v_mul_f32_e32 v3, v32, v26
	v_cvt_pk_bf16_f32 v3, v3, s0
	global_store_short v[0:1], v3, off sc1
	global_load_dword v1, v[98:99], off offset:384
	v_mul_f32_e32 v0, v32, v25
	v_cvt_pk_bf16_f32 v0, v0, s0
	global_store_short v[30:31], v0, off sc1
	global_load_dword v0, v[100:101], off offset:384
	v_add_u32_e32 v30, v180, v16
	v_ashrrev_i32_e32 v31, 31, v30
	v_mul_f32_e32 v3, v32, v24
	v_lshl_add_u64 v[4:5], v[30:31], 1, s[8:9]
	v_cvt_pk_bf16_f32 v3, v3, s0
	global_store_short v[4:5], v3, off sc1
	v_add_u32_e32 v4, v71, v16
	v_ashrrev_i32_e32 v5, 31, v4
	v_mul_f32_e32 v3, v32, v23
	v_lshl_add_u64 v[4:5], v[4:5], 1, s[8:9]
	v_cvt_pk_bf16_f32 v3, v3, s0
	global_store_short v[4:5], v3, off sc1
	v_add_u32_e32 v4, v181, v16
	v_fmac_f32_e32 v22, v7, v102
	v_ashrrev_i32_e32 v5, 31, v4
	v_mul_f32_e32 v3, v32, v22
	v_lshl_add_u64 v[4:5], v[4:5], 1, s[8:9]
	v_cvt_pk_bf16_f32 v3, v3, s0
	global_store_short v[4:5], v3, off sc1
	v_add_u32_e32 v4, v183, v16
	v_fmac_f32_e32 v21, v8, v102
	v_ashrrev_i32_e32 v5, 31, v4
	v_mul_f32_e32 v3, v32, v21
	v_lshl_add_u64 v[4:5], v[4:5], 1, s[8:9]
	v_cvt_pk_bf16_f32 v3, v3, s0
	global_store_short v[4:5], v3, off sc1
	v_add_u32_e32 v4, v186, v16
	v_fmac_f32_e32 v20, v9, v102
	v_ashrrev_i32_e32 v5, 31, v4
	v_mul_f32_e32 v3, v32, v20
	v_lshl_add_u64 v[4:5], v[4:5], 1, s[8:9]
	v_cvt_pk_bf16_f32 v3, v3, s0
	global_store_short v[4:5], v3, off sc1
	v_add_u32_e32 v4, v188, v16
	s_waitcnt vmcnt(15)
	v_fmac_f32_e32 v19, v10, v102
	v_ashrrev_i32_e32 v5, 31, v4
	v_mul_f32_e32 v3, v32, v19
	v_lshl_add_u64 v[4:5], v[4:5], 1, s[8:9]
	v_cvt_pk_bf16_f32 v3, v3, s0
	global_store_short v[4:5], v3, off sc1
	v_add_u32_e32 v4, v189, v16
	s_waitcnt vmcnt(15)
	v_fmac_f32_e32 v18, v11, v102
	v_ashrrev_i32_e32 v5, 31, v4
	v_mul_f32_e32 v3, v32, v18
	v_lshl_add_u64 v[4:5], v[4:5], 1, s[8:9]
	v_cvt_pk_bf16_f32 v3, v3, s0
	global_store_short v[4:5], v3, off sc1
	v_add_u32_e32 v4, v190, v16
	v_ashrrev_i32_e32 v5, 31, v4
	v_lshl_add_u64 v[4:5], v[4:5], 1, s[8:9]
	v_ashrrev_i32_e32 v71, 31, v70
	global_store_dword v[88:89], v28, off offset:384 sc1
	global_store_dword v[84:85], v27, off offset:384 sc1
	global_store_dword v[82:83], v26, off offset:384 sc1
	global_store_dword v[78:79], v25, off offset:384 sc1
	s_waitcnt vmcnt(17)
	v_fmac_f32_e32 v17, v12, v102
	v_mul_f32_e32 v3, v32, v17
	v_cvt_pk_bf16_f32 v3, v3, s0
	global_store_short v[4:5], v3, off sc1
	v_add_u32_e32 v4, v192, v16
	v_ashrrev_i32_e32 v5, 31, v4
	v_lshl_add_u64 v[4:5], v[4:5], 1, s[8:9]
	s_waitcnt vmcnt(16)
	v_fmac_f32_e32 v2, v13, v102
	v_mul_f32_e32 v3, v32, v2
	v_cvt_pk_bf16_f32 v3, v3, s0
	global_store_short v[4:5], v3, off sc1
	v_add_u32_e32 v4, v193, v16
	v_ashrrev_i32_e32 v5, 31, v4
	v_lshl_add_u64 v[4:5], v[4:5], 1, s[8:9]
	v_xor_b32_e32 v12, 16, v165
	global_store_dword v[72:73], v24, off offset:384 sc1
	global_store_dword v[74:75], v23, off offset:384 sc1
	global_store_dword v[76:77], v22, off offset:384 sc1
	global_store_dword v[80:81], v21, off offset:384 sc1
	global_store_dword v[86:87], v20, off offset:384 sc1
	s_waitcnt vmcnt(20)
	v_fmac_f32_e32 v1, v14, v102
	v_mul_f32_e32 v3, v32, v1
	v_cvt_pk_bf16_f32 v3, v3, s0
	global_store_short v[4:5], v3, off sc1
	v_add_u32_e32 v4, v194, v16
	v_ashrrev_i32_e32 v5, 31, v4
	v_lshl_add_u64 v[10:11], v[4:5], 1, s[8:9]
	v_and_b32_e32 v4, 64, v165
	v_xor_b32_e32 v3, 1, v165
	v_add_u32_e32 v7, 64, v4
	v_cmp_lt_i32_e32 vcc, v3, v7
	v_xor_b32_e32 v4, 2, v165
	s_waitcnt vmcnt(19)
	v_fmac_f32_e32 v0, v15, v102
	v_cndmask_b32_e32 v3, v165, v3, vcc
	v_lshlrev_b32_e32 v3, 2, v3
	ds_bpermute_b32 v5, v3, v106
	v_cmp_lt_i32_e32 vcc, v4, v7
	global_store_dword v[90:91], v19, off offset:384 sc1
	global_store_dword v[92:93], v18, off offset:384 sc1
	v_cndmask_b32_e32 v4, v165, v4, vcc
	v_lshlrev_b32_e32 v4, 2, v4
	s_waitcnt lgkmcnt(0)
	v_add_f32_e32 v6, v106, v5
	ds_bpermute_b32 v8, v4, v6
	v_xor_b32_e32 v5, 4, v165
	v_cmp_lt_i32_e32 vcc, v5, v7
	global_store_dword v[94:95], v17, off offset:384 sc1
	global_store_dword v[96:97], v2, off offset:384 sc1
	v_cndmask_b32_e32 v5, v165, v5, vcc
	v_lshlrev_b32_e32 v5, 2, v5
	s_waitcnt lgkmcnt(0)
	v_add_f32_e32 v8, v6, v8
	ds_bpermute_b32 v9, v5, v8
	v_xor_b32_e32 v6, 8, v165
	v_cmp_lt_i32_e32 vcc, v6, v7
	global_store_dword v[98:99], v1, off offset:384 sc1
	global_store_dword v[100:101], v0, off offset:384 sc1
	v_cndmask_b32_e32 v6, v165, v6, vcc
	v_lshlrev_b32_e32 v6, 2, v6
	s_waitcnt lgkmcnt(0)
	v_add_f32_e32 v8, v8, v9
	ds_bpermute_b32 v9, v6, v8
	v_cmp_lt_i32_e32 vcc, v12, v7
	s_waitcnt lgkmcnt(0)
	v_add_f32_e32 v8, v8, v9
	v_cndmask_b32_e32 v7, v165, v12, vcc
	v_lshlrev_b32_e32 v7, 2, v7
	ds_bpermute_b32 v9, v7, v8
	v_mul_f32_e32 v12, v32, v0
	v_cvt_pk_bf16_f32 v12, v12, s0
	global_store_short v[10:11], v12, off sc1
	s_and_saveexec_b64 s[60:61], s[0:1]
	s_cbranch_execz .LBB0_781
	s_waitcnt lgkmcnt(0)
	v_add_f32_e32 v10, v8, v9
	v_lshl_add_u64 v[8:9], v[70:71], 2, s[58:59]
	global_store_dword v[8:9], v10, off sc1

.LBB0_1050:
	s_add_i32 s58, s66, 0xffffe000
	s_lshr_b32 s58, s58, 12
	s_mulk_i32 s58, 0x1800
	v_mov_b32_e32 v70, s70
	s_addk_i32 s58, 0x6000
	ds_read_b64 v[70:71], v70
	s_cmp_gt_i32 s6, 63
	s_cselect_b32 s6, s58, 0x4800
	s_lshl_b64 s[58:59], s[6:7], 2
	s_add_u32 s6, s14, s58
	s_addc_u32 s65, s15, s59
	s_waitcnt lgkmcnt(0)
	v_readfirstlane_b32 s58, v70
	v_readfirstlane_b32 s59, v71
	s_add_u32 s60, s58, 0x1000
	s_addc_u32 s61, s59, 0
	s_lshl_b32 s58, s64, 14
	s_add_i32 s58, s58, 0x60000
	s_ashr_i32 s59, s58, 31
	s_lshl_b64 s[58:59], s[58:59], 2
	s_add_u32 s58, s10, s58
	s_addc_u32 s59, s11, s59
	s_add_u32 s62, s6, 0x5ba2000
	v_or_b32_e32 v102, s68, v138
	v_add_u32_e32 v70, s66, v139
	s_addc_u32 s63, s65, 0
	v_lshlrev_b32_e32 v188, 10, v70
	v_ashrrev_i32_e32 v103, 31, v102
	s_add_u32 s64, s6, 0x5ba4000
	v_lshlrev_b64 v[72:73], 2, v[102:103]
	v_or_b32_e32 v186, 0x400, v188
	v_or_b32_e32 v185, 0x4400, v188
	v_or_b32_e32 v189, 0x4c00, v188
	v_or_b32_e32 v193, 0x6c00, v188
	s_addc_u32 s65, s65, 0
	v_lshl_add_u64 v[74:75], s[62:63], 0, v[72:73]
	v_add_u32_e32 v132, v188, v102
	v_add_u32_e32 v134, v186, v102
	v_or_b32_e32 v184, 0x800, v188
	v_or_b32_e32 v183, 0xc00, v188
	v_or_b32_e32 v181, 0x2000, v188
	v_or_b32_e32 v179, 0x2400, v188
	v_or_b32_e32 v71, 0x2800, v188
	v_or_b32_e32 v180, 0x2c00, v188
	v_or_b32_e32 v182, 0x4000, v188
	v_add_u32_e32 v112, v185, v102
	v_or_b32_e32 v187, 0x4800, v188
	v_add_u32_e32 v118, v189, v102
	v_or_b32_e32 v190, 0x6000, v188
	v_or_b32_e32 v191, 0x6400, v188
	v_or_b32_e32 v192, 0x6800, v188
	v_add_u32_e32 v128, v193, v102
	global_load_dword v194, v[74:75], off
	v_lshl_add_u64 v[74:75], s[60:61], 0, v[72:73]
	v_lshl_add_u64 v[72:73], s[64:65], 0, v[72:73]
	v_ashrrev_i32_e32 v135, 31, v134
	v_add_u32_e32 v136, v184, v102
	v_add_u32_e32 v130, v183, v102
	v_add_u32_e32 v122, v181, v102
	v_add_u32_e32 v114, v179, v102
	v_add_u32_e32 v106, v71, v102
	v_add_u32_e32 v108, v180, v102
	v_add_u32_e32 v110, v182, v102
	v_ashrrev_i32_e32 v113, 31, v112
	v_add_u32_e32 v116, v187, v102
	v_ashrrev_i32_e32 v119, 31, v118
	v_add_u32_e32 v120, v190, v102
	v_add_u32_e32 v124, v191, v102
	v_add_u32_e32 v126, v192, v102
	v_ashrrev_i32_e32 v129, 31, v128
	v_ashrrev_i32_e32 v133, 31, v132
	global_load_dword v196, v[72:73], off
	v_lshl_add_u64 v[88:89], v[134:135], 2, s[12:13]
	v_ashrrev_i32_e32 v137, 31, v136
	v_ashrrev_i32_e32 v131, 31, v130
	v_ashrrev_i32_e32 v123, 31, v122
	v_ashrrev_i32_e32 v115, 31, v114
	v_ashrrev_i32_e32 v107, 31, v106
	v_ashrrev_i32_e32 v109, 31, v108
	v_ashrrev_i32_e32 v111, 31, v110
	v_lshl_add_u64 v[86:87], v[112:113], 2, s[12:13]
	v_ashrrev_i32_e32 v117, 31, v116
	v_lshl_add_u64 v[92:93], v[118:119], 2, s[12:13]
	v_ashrrev_i32_e32 v121, 31, v120
	v_ashrrev_i32_e32 v125, 31, v124
	v_ashrrev_i32_e32 v127, 31, v126
	v_lshl_add_u64 v[100:101], v[128:129], 2, s[12:13]
	v_lshl_add_u64 v[104:105], v[132:133], 2, s[12:13]
	global_load_dword v195, v[74:75], off
	v_lshl_add_u64 v[84:85], v[136:137], 2, s[12:13]
	v_lshl_add_u64 v[82:83], v[130:131], 2, s[12:13]
	v_lshl_add_u64 v[78:79], v[122:123], 2, s[12:13]
	v_lshl_add_u64 v[72:73], v[114:115], 2, s[12:13]
	v_lshl_add_u64 v[74:75], v[106:107], 2, s[12:13]
	v_lshl_add_u64 v[76:77], v[108:109], 2, s[12:13]
	v_lshl_add_u64 v[80:81], v[110:111], 2, s[12:13]
	global_load_dword v178, v[88:89], off
	global_load_dword v177, v[84:85], off
	global_load_dword v176, v[82:83], off
	global_load_dword v175, v[78:79], off
	global_load_dword v174, v[72:73], off
	global_load_dword v173, v[74:75], off
	global_load_dword v172, v[76:77], off
	global_load_dword v171, v[80:81], off
	v_lshl_add_u64 v[90:91], v[116:117], 2, s[12:13]
	global_load_dword v170, v[86:87], off
	global_load_dword v168, v[90:91], off
	v_lshl_add_u64 v[94:95], v[120:121], 2, s[12:13]
	v_lshl_add_u64 v[96:97], v[124:125], 2, s[12:13]
	v_lshl_add_u64 v[98:99], v[126:127], 2, s[12:13]
	global_load_dword v169, v[92:93], off
	global_load_dword v167, v[94:95], off
	global_load_dword v166, v[96:97], off
	global_load_dword v165, v[98:99], off
	global_load_dword v103, v[100:101], off
	global_load_dword v197, v[104:105], off
	v_lshl_add_u64 v[106:107], v[106:107], 1, s[8:9]
	global_load_dword v255, v[88:89], off offset:128
	global_load_dword v255, v[88:89], off offset:256
	global_load_dword v255, v[88:89], off offset:384
	global_load_dword v255, v[84:85], off offset:128
	global_load_dword v255, v[84:85], off offset:256
	global_load_dword v255, v[84:85], off offset:384
	global_load_dword v255, v[82:83], off offset:128
	global_load_dword v255, v[82:83], off offset:256
	global_load_dword v255, v[82:83], off offset:384
	global_load_dword v255, v[78:79], off offset:128
	global_load_dword v255, v[78:79], off offset:256
	global_load_dword v255, v[78:79], off offset:384
	global_load_dword v255, v[72:73], off offset:128
	global_load_dword v255, v[72:73], off offset:256
	global_load_dword v255, v[72:73], off offset:384
	global_load_dword v255, v[74:75], off offset:128
	global_load_dword v255, v[74:75], off offset:256
	global_load_dword v255, v[74:75], off offset:384
	global_load_dword v255, v[76:77], off offset:128
	global_load_dword v255, v[76:77], off offset:256
	global_load_dword v255, v[76:77], off offset:384
	global_load_dword v255, v[80:81], off offset:128
	global_load_dword v255, v[80:81], off offset:256
	global_load_dword v255, v[80:81], off offset:384
	global_load_dword v255, v[86:87], off offset:128
	global_load_dword v255, v[86:87], off offset:256
	global_load_dword v255, v[86:87], off offset:384
	global_load_dword v255, v[90:91], off offset:128
	global_load_dword v255, v[90:91], off offset:256
	global_load_dword v255, v[90:91], off offset:384
	global_load_dword v255, v[92:93], off offset:128
	global_load_dword v255, v[92:93], off offset:256
	global_load_dword v255, v[92:93], off offset:384
	global_load_dword v255, v[94:95], off offset:128
	global_load_dword v255, v[94:95], off offset:256
	global_load_dword v255, v[94:95], off offset:384
	global_load_dword v255, v[96:97], off offset:128
	global_load_dword v255, v[96:97], off offset:256
	global_load_dword v255, v[96:97], off offset:384
	global_load_dword v255, v[98:99], off offset:128
	global_load_dword v255, v[98:99], off offset:256
	global_load_dword v255, v[98:99], off offset:384
	global_load_dword v255, v[100:101], off offset:128
	global_load_dword v255, v[100:101], off offset:256
	global_load_dword v255, v[100:101], off offset:384
	global_load_dword v255, v[104:105], off offset:128
	global_load_dword v255, v[104:105], off offset:256
	global_load_dword v255, v[104:105], off offset:384
	s_waitcnt vmcnt(0)
	v_add_f32_e32 v196, 1.0, v196
	v_mul_f32_e32 v195, v195, v196
	v_fmac_f32_e32 v178, v49, v194
	v_fmac_f32_e32 v177, v50, v194
	v_fmac_f32_e32 v176, v51, v194
	v_fmac_f32_e32 v175, v52, v194
	v_fmac_f32_e32 v174, v53, v194
	v_fmac_f32_e32 v173, v54, v194
	v_fmac_f32_e32 v172, v55, v194
	v_fmac_f32_e32 v171, v56, v194
	v_fmac_f32_e32 v170, v57, v194
	v_fmac_f32_e32 v168, v58, v194
	v_fmac_f32_e32 v169, v59, v194
	v_fmac_f32_e32 v167, v60, v194
	v_fmac_f32_e32 v166, v61, v194
	v_fmac_f32_e32 v165, v62, v194
	v_fmac_f32_e32 v103, v63, v194
	v_fmac_f32_e32 v197, v48, v194
	v_mul_f32_e32 v48, v195, v197
	v_cvt_pk_bf16_f32 v58, v48, s0
	v_or_b32_e32 v48, 32, v102
	v_ashrrev_i32_e32 v49, 31, v48
	v_lshlrev_b64 v[52:53], 2, v[48:49]
	global_store_dword v[88:89], v178, off sc1
	global_store_dword v[84:85], v177, off sc1
	global_store_dword v[82:83], v176, off sc1
	global_store_dword v[78:79], v175, off sc1
	global_store_dword v[72:73], v174, off sc1
	global_store_dword v[74:75], v173, off sc1
	global_store_dword v[76:77], v172, off sc1
	global_store_dword v[80:81], v171, off sc1
	global_store_dword v[86:87], v170, off sc1
	global_store_dword v[90:91], v168, off sc1
	global_store_dword v[92:93], v169, off sc1
	global_store_dword v[94:95], v167, off sc1
	global_store_dword v[96:97], v166, off sc1
	global_store_dword v[98:99], v165, off sc1
	global_store_dword v[100:101], v103, off sc1
	global_store_dword v[104:105], v197, off sc1
	v_lshl_add_u64 v[50:51], v[132:133], 1, s[8:9]
	v_lshl_add_u64 v[56:57], s[64:65], 0, v[52:53]
	global_load_dword v196, v[104:105], off offset:128
	v_lshl_add_u64 v[54:55], s[60:61], 0, v[52:53]
	global_load_dword v132, v[56:57], off
	global_load_dword v133, v[54:55], off
	v_mul_f32_e32 v49, v195, v178
	global_store_short v[50:51], v58, off sc1
	v_lshl_add_u64 v[50:51], s[62:63], 0, v[52:53]
	global_load_dword v194, v[50:51], off
	v_cvt_pk_bf16_f32 v49, v49, s0
	v_lshl_add_u64 v[50:51], v[134:135], 1, s[8:9]
	global_store_short v[50:51], v49, off sc1
	v_mul_f32_e32 v49, v195, v177
	v_cvt_pk_bf16_f32 v49, v49, s0
	v_lshl_add_u64 v[50:51], v[136:137], 1, s[8:9]
	global_store_short v[50:51], v49, off sc1
	v_mul_f32_e32 v49, v195, v176
	v_cvt_pk_bf16_f32 v49, v49, s0
	v_lshl_add_u64 v[50:51], v[130:131], 1, s[8:9]
	global_store_short v[50:51], v49, off sc1
	v_mul_f32_e32 v49, v195, v175
	v_cvt_pk_bf16_f32 v49, v49, s0
	v_lshl_add_u64 v[50:51], v[122:123], 1, s[8:9]
	global_store_short v[50:51], v49, off sc1
	v_mul_f32_e32 v49, v195, v174
	v_cvt_pk_bf16_f32 v49, v49, s0
	v_lshl_add_u64 v[50:51], v[114:115], 1, s[8:9]
	global_store_short v[50:51], v49, off sc1
	v_mul_f32_e32 v49, v195, v173
	global_load_dword v62, v[84:85], off offset:128
	global_load_dword v60, v[78:79], off offset:128
	global_load_dword v59, v[72:73], off offset:128
	global_load_dword v58, v[74:75], off offset:128
	global_load_dword v56, v[80:81], off offset:128
	global_load_dword v57, v[76:77], off offset:128
	global_load_dword v55, v[86:87], off offset:128
	global_load_dword v61, v[82:83], off offset:128
	global_load_dword v54, v[90:91], off offset:128
	global_load_dword v53, v[92:93], off offset:128
	global_load_dword v52, v[94:95], off offset:128
	global_load_dword v51, v[96:97], off offset:128
	global_load_dword v50, v[98:99], off offset:128
	v_cvt_pk_bf16_f32 v63, v49, s0
	global_load_dword v49, v[100:101], off offset:128
	s_waitcnt vmcnt(19)
	v_fmac_f32_e32 v196, v32, v194
	global_store_short v[106:107], v63, off sc1
	global_load_dword v63, v[88:89], off offset:128
	v_mul_f32_e32 v106, v195, v172
	v_cvt_pk_bf16_f32 v114, v106, s0
	v_lshl_add_u64 v[106:107], v[108:109], 1, s[8:9]
	global_store_short v[106:107], v114, off sc1
	v_mul_f32_e32 v106, v195, v171
	v_cvt_pk_bf16_f32 v108, v106, s0
	v_lshl_add_u64 v[106:107], v[110:111], 1, s[8:9]
	global_store_short v[106:107], v108, off sc1
	v_mul_f32_e32 v106, v195, v170
	v_cvt_pk_bf16_f32 v108, v106, s0
	v_lshl_add_u64 v[106:107], v[112:113], 1, s[8:9]
	global_store_short v[106:107], v108, off sc1
	v_mul_f32_e32 v106, v195, v168
	v_cvt_pk_bf16_f32 v108, v106, s0
	v_lshl_add_u64 v[106:107], v[116:117], 1, s[8:9]
	global_store_short v[106:107], v108, off sc1
	v_mul_f32_e32 v106, v195, v169
	v_cvt_pk_bf16_f32 v108, v106, s0
	v_lshl_add_u64 v[106:107], v[118:119], 1, s[8:9]
	global_store_short v[106:107], v108, off sc1
	v_mul_f32_e32 v106, v195, v167
	v_cvt_pk_bf16_f32 v108, v106, s0
	v_lshl_add_u64 v[106:107], v[120:121], 1, s[8:9]
	global_store_short v[106:107], v108, off sc1
	v_mul_f32_e32 v106, v195, v166
	v_cvt_pk_bf16_f32 v108, v106, s0
	v_lshl_add_u64 v[106:107], v[124:125], 1, s[8:9]
	global_store_short v[106:107], v108, off sc1
	v_mul_f32_e32 v106, v195, v165
	v_cvt_pk_bf16_f32 v108, v106, s0
	v_lshl_add_u64 v[106:107], v[126:127], 1, s[8:9]
	global_store_short v[106:107], v108, off sc1
	v_mul_f32_e32 v106, v195, v103
	v_cvt_pk_bf16_f32 v108, v106, s0
	v_lshl_add_u64 v[106:107], v[128:129], 1, s[8:9]
	global_store_short v[106:107], v108, off sc1
	v_add_f32_e32 v106, 1.0, v132
	v_mul_f32_e32 v110, v133, v106
	v_add_u32_e32 v106, v188, v48
	s_waitcnt vmcnt(24)
	v_fmac_f32_e32 v62, v34, v194
	s_waitcnt vmcnt(17)
	v_fmac_f32_e32 v61, v35, v194
	v_fmac_f32_e32 v60, v36, v194
	v_fmac_f32_e32 v59, v37, v194
	v_fmac_f32_e32 v58, v38, v194
	v_fmac_f32_e32 v57, v39, v194
	v_fmac_f32_e32 v56, v40, v194
	v_fmac_f32_e32 v55, v41, v194
	s_waitcnt vmcnt(16)
	v_fmac_f32_e32 v54, v42, v194
	s_waitcnt vmcnt(15)
	v_fmac_f32_e32 v53, v43, v194
	s_waitcnt vmcnt(14)
	v_fmac_f32_e32 v52, v44, v194
	s_waitcnt vmcnt(13)
	v_fmac_f32_e32 v51, v45, v194
	s_waitcnt vmcnt(12)
	v_fmac_f32_e32 v50, v46, v194
	s_waitcnt vmcnt(11)
	v_fmac_f32_e32 v49, v47, v194
	v_ashrrev_i32_e32 v107, 31, v106
	global_store_dword v[104:105], v196, off offset:128 sc1
	v_mul_f32_e32 v32, v110, v196
	global_store_dword v[84:85], v62, off offset:128 sc1
	global_store_dword v[82:83], v61, off offset:128 sc1
	global_store_dword v[78:79], v60, off offset:128 sc1
	global_store_dword v[72:73], v59, off offset:128 sc1
	global_store_dword v[74:75], v58, off offset:128 sc1
	global_store_dword v[76:77], v57, off offset:128 sc1
	global_store_dword v[80:81], v56, off offset:128 sc1
	global_store_dword v[86:87], v55, off offset:128 sc1
	global_store_dword v[90:91], v54, off offset:128 sc1
	global_store_dword v[92:93], v53, off offset:128 sc1
	global_store_dword v[94:95], v52, off offset:128 sc1
	global_store_dword v[96:97], v51, off offset:128 sc1
	global_store_dword v[98:99], v50, off offset:128 sc1
	global_store_dword v[100:101], v49, off offset:128 sc1
	v_cvt_pk_bf16_f32 v32, v32, s0
	v_lshl_add_u64 v[106:107], v[106:107], 1, s[8:9]
	v_add_u32_e32 v108, v186, v48
	global_load_dword v45, v[88:89], off offset:256
	v_ashrrev_i32_e32 v109, 31, v108
	global_store_short v[106:107], v32, off sc1
	v_mul_f32_e32 v113, v110, v56
	v_cvt_pk_bf16_f32 v113, v113, s0
	v_mul_f32_e32 v106, v196, v196
	s_waitcnt vmcnt(26)
	v_fmac_f32_e32 v63, v33, v194
	v_mul_f32_e32 v32, v110, v63
	v_cvt_pk_bf16_f32 v34, v32, s0
	v_lshl_add_u64 v[32:33], v[108:109], 1, s[8:9]
	global_store_short v[32:33], v34, off sc1
	v_add_u32_e32 v32, v184, v48
	v_ashrrev_i32_e32 v33, 31, v32
	v_mul_f32_e32 v34, v110, v62
	v_cvt_pk_bf16_f32 v34, v34, s0
	v_lshl_add_u64 v[32:33], v[32:33], 1, s[8:9]
	global_store_short v[32:33], v34, off sc1
	v_add_u32_e32 v32, v183, v48
	v_ashrrev_i32_e32 v33, 31, v32
	v_mul_f32_e32 v34, v110, v61
	v_cvt_pk_bf16_f32 v34, v34, s0
	v_lshl_add_u64 v[32:33], v[32:33], 1, s[8:9]
	global_store_short v[32:33], v34, off sc1
	v_add_u32_e32 v32, v181, v48
	v_ashrrev_i32_e32 v33, 31, v32
	v_mul_f32_e32 v34, v110, v60
	v_cvt_pk_bf16_f32 v34, v34, s0
	v_lshl_add_u64 v[32:33], v[32:33], 1, s[8:9]
	global_store_short v[32:33], v34, off sc1
	v_add_u32_e32 v32, v179, v48
	v_ashrrev_i32_e32 v33, 31, v32
	v_mul_f32_e32 v34, v110, v59
	v_cvt_pk_bf16_f32 v42, v34, s0
	v_lshl_add_u64 v[34:35], v[32:33], 1, s[8:9]
	v_or_b32_e32 v32, 64, v102
	v_ashrrev_i32_e32 v33, 31, v32
	v_lshlrev_b64 v[36:37], 2, v[32:33]
	global_store_dword v[88:89], v63, off offset:128 sc1
	v_lshl_add_u64 v[40:41], s[64:65], 0, v[36:37]
	v_lshl_add_u64 v[38:39], s[60:61], 0, v[36:37]
	global_load_dword v107, v[40:41], off
	global_load_dword v111, v[38:39], off
	v_mul_f32_e32 v33, v110, v58
	global_store_short v[34:35], v42, off sc1
	v_lshl_add_u64 v[34:35], s[62:63], 0, v[36:37]
	global_load_dword v112, v[34:35], off
	v_add_u32_e32 v34, v71, v48
	v_ashrrev_i32_e32 v35, 31, v34
	v_cvt_pk_bf16_f32 v33, v33, s0
	v_lshl_add_u64 v[34:35], v[34:35], 1, s[8:9]
	global_store_short v[34:35], v33, off sc1
	v_add_u32_e32 v34, v180, v48
	v_ashrrev_i32_e32 v35, 31, v34
	v_mul_f32_e32 v33, v110, v57
	v_cvt_pk_bf16_f32 v33, v33, s0
	v_lshl_add_u64 v[34:35], v[34:35], 1, s[8:9]
	global_load_dword v38, v[90:91], off offset:256
	global_load_dword v37, v[92:93], off offset:256
	global_load_dword v36, v[94:95], off offset:256
	global_load_dword v114, v[104:105], off offset:256
	global_load_dword v47, v[84:85], off offset:256
	global_load_dword v39, v[86:87], off offset:256
	global_load_dword v46, v[82:83], off offset:256
	global_load_dword v44, v[78:79], off offset:256
	global_load_dword v43, v[72:73], off offset:256
	global_load_dword v42, v[74:75], off offset:256
	global_load_dword v40, v[80:81], off offset:256
	global_load_dword v41, v[76:77], off offset:256
	v_add_u32_e32 v108, v182, v48
	global_store_short v[34:35], v33, off sc1
	global_load_dword v35, v[96:97], off offset:256
	v_ashrrev_i32_e32 v109, 31, v108
	global_load_dword v34, v[98:99], off offset:256
	global_load_dword v33, v[100:101], off offset:256
	v_lshl_add_u64 v[108:109], v[108:109], 1, s[8:9]
	global_store_short v[108:109], v113, off sc1
	v_add_u32_e32 v108, v185, v48
	v_ashrrev_i32_e32 v109, 31, v108
	v_mul_f32_e32 v113, v110, v55
	v_cvt_pk_bf16_f32 v113, v113, s0
	v_lshl_add_u64 v[108:109], v[108:109], 1, s[8:9]
	global_store_short v[108:109], v113, off sc1
	v_add_u32_e32 v108, v187, v48
	v_ashrrev_i32_e32 v109, 31, v108
	v_mul_f32_e32 v113, v110, v54
	v_cvt_pk_bf16_f32 v113, v113, s0
	v_lshl_add_u64 v[108:109], v[108:109], 1, s[8:9]
	global_store_short v[108:109], v113, off sc1
	v_add_u32_e32 v108, v189, v48
	v_ashrrev_i32_e32 v109, 31, v108
	v_mul_f32_e32 v113, v110, v53
	v_cvt_pk_bf16_f32 v113, v113, s0
	v_lshl_add_u64 v[108:109], v[108:109], 1, s[8:9]
	global_store_short v[108:109], v113, off sc1
	v_add_u32_e32 v108, v190, v48
	v_ashrrev_i32_e32 v109, 31, v108
	v_mul_f32_e32 v113, v110, v52
	v_cvt_pk_bf16_f32 v113, v113, s0
	v_lshl_add_u64 v[108:109], v[108:109], 1, s[8:9]
	global_store_short v[108:109], v113, off sc1
	v_add_u32_e32 v108, v191, v48
	v_ashrrev_i32_e32 v109, 31, v108
	v_mul_f32_e32 v113, v110, v51
	v_cvt_pk_bf16_f32 v113, v113, s0
	v_lshl_add_u64 v[108:109], v[108:109], 1, s[8:9]
	global_store_short v[108:109], v113, off sc1
	v_add_u32_e32 v108, v192, v48
	v_ashrrev_i32_e32 v109, 31, v108
	v_mul_f32_e32 v113, v110, v50
	v_cvt_pk_bf16_f32 v113, v113, s0
	v_lshl_add_u64 v[108:109], v[108:109], 1, s[8:9]
	global_store_short v[108:109], v113, off sc1
	v_add_u32_e32 v108, v193, v48
	v_ashrrev_i32_e32 v109, 31, v108
	v_mul_f32_e32 v48, v110, v49
	v_cvt_pk_bf16_f32 v48, v48, s0
	v_lshl_add_u64 v[108:109], v[108:109], 1, s[8:9]
	global_store_short v[108:109], v48, off sc1
	v_add_u32_e32 v108, v188, v32
	v_ashrrev_i32_e32 v109, 31, v108
	s_waitcnt vmcnt(28)
	v_add_f32_e32 v48, 1.0, v107
	s_waitcnt vmcnt(27)
	v_mul_f32_e32 v48, v111, v48
	v_fmac_f32_e32 v106, v197, v197
	s_waitcnt vmcnt(25)
	v_fmac_f32_e32 v45, v17, v112
	global_store_dword v[88:89], v45, off offset:256 sc1
	s_waitcnt vmcnt(24)
	v_fmac_f32_e32 v38, v26, v112
	s_waitcnt vmcnt(23)
	v_fmac_f32_e32 v37, v27, v112
	s_waitcnt vmcnt(22)
	v_fmac_f32_e32 v36, v28, v112
	s_waitcnt vmcnt(21)
	v_fmac_f32_e32 v114, v16, v112
	v_mul_f32_e32 v16, v48, v114
	s_waitcnt vmcnt(20)
	v_fmac_f32_e32 v47, v18, v112
	v_cvt_pk_bf16_f32 v18, v16, s0
	v_lshl_add_u64 v[16:17], v[108:109], 1, s[8:9]
	global_store_short v[16:17], v18, off sc1
	v_add_u32_e32 v16, v186, v32
	v_ashrrev_i32_e32 v17, 31, v16
	v_mul_f32_e32 v18, v48, v45
	v_cvt_pk_bf16_f32 v18, v18, s0
	v_lshl_add_u64 v[16:17], v[16:17], 1, s[8:9]
	global_store_short v[16:17], v18, off sc1
	v_add_u32_e32 v16, v184, v32
	v_ashrrev_i32_e32 v17, 31, v16
	v_mul_f32_e32 v18, v48, v47
	v_cvt_pk_bf16_f32 v18, v18, s0
	v_lshl_add_u64 v[16:17], v[16:17], 1, s[8:9]
	s_waitcnt vmcnt(20)
	v_fmac_f32_e32 v46, v19, v112
	global_store_short v[16:17], v18, off sc1
	v_add_u32_e32 v16, v183, v32
	v_ashrrev_i32_e32 v17, 31, v16
	v_mul_f32_e32 v18, v48, v46
	s_waitcnt vmcnt(20)
	v_fmac_f32_e32 v44, v20, v112
	v_cvt_pk_bf16_f32 v18, v18, s0
	v_lshl_add_u64 v[16:17], v[16:17], 1, s[8:9]
	global_store_short v[16:17], v18, off sc1
	v_mul_f32_e32 v16, v48, v44
	v_cvt_pk_bf16_f32 v26, v16, s0
	v_or_b32_e32 v16, 0x60, v102
	v_add_u32_e32 v18, v181, v32
	v_ashrrev_i32_e32 v17, 31, v16
	s_waitcnt vmcnt(20)
	v_fmac_f32_e32 v43, v21, v112
	s_waitcnt vmcnt(19)
	v_fmac_f32_e32 v42, v22, v112
	s_waitcnt vmcnt(17)
	v_fmac_f32_e32 v41, v23, v112
	v_fmac_f32_e32 v40, v24, v112
	v_fmac_f32_e32 v39, v25, v112
	s_waitcnt vmcnt(15)
	v_fmac_f32_e32 v35, v29, v112
	s_waitcnt vmcnt(14)
	v_fmac_f32_e32 v34, v30, v112
	s_waitcnt vmcnt(13)
	v_fmac_f32_e32 v33, v31, v112
	v_ashrrev_i32_e32 v19, 31, v18
	v_lshlrev_b64 v[20:21], 2, v[16:17]
	global_store_dword v[84:85], v47, off offset:256 sc1
	global_store_dword v[82:83], v46, off offset:256 sc1
	global_store_dword v[78:79], v44, off offset:256 sc1
	global_store_dword v[72:73], v43, off offset:256 sc1
	global_store_dword v[74:75], v42, off offset:256 sc1
	global_store_dword v[76:77], v41, off offset:256 sc1
	global_store_dword v[80:81], v40, off offset:256 sc1
	global_store_dword v[86:87], v39, off offset:256 sc1
	global_store_dword v[90:91], v38, off offset:256 sc1
	global_store_dword v[92:93], v37, off offset:256 sc1
	global_store_dword v[94:95], v36, off offset:256 sc1
	global_store_dword v[96:97], v35, off offset:256 sc1
	global_store_dword v[98:99], v34, off offset:256 sc1
	global_store_dword v[100:101], v33, off offset:256 sc1
	global_store_dword v[104:105], v114, off offset:256 sc1
	v_lshl_add_u64 v[24:25], s[64:65], 0, v[20:21]
	v_lshl_add_u64 v[18:19], v[18:19], 1, s[8:9]
	global_load_dword v29, v[104:105], off offset:384
	v_lshl_add_u64 v[22:23], s[60:61], 0, v[20:21]
	global_load_dword v17, v[24:25], off
	global_load_dword v30, v[22:23], off
	global_load_dword v28, v[88:89], off offset:384
	global_load_dword v27, v[84:85], off offset:384
	v_fmac_f32_e32 v106, v114, v114
	global_store_short v[18:19], v26, off sc1
	v_lshl_add_u64 v[18:19], s[62:63], 0, v[20:21]
	global_load_dword v102, v[18:19], off
	v_add_u32_e32 v18, v179, v32
	v_ashrrev_i32_e32 v19, 31, v18
	v_mul_f32_e32 v20, v48, v43
	v_cvt_pk_bf16_f32 v20, v20, s0
	v_lshl_add_u64 v[18:19], v[18:19], 1, s[8:9]
	global_store_short v[18:19], v20, off sc1
	v_add_u32_e32 v18, v71, v32
	v_ashrrev_i32_e32 v19, 31, v18
	v_mul_f32_e32 v20, v48, v42
	v_cvt_pk_bf16_f32 v20, v20, s0
	v_lshl_add_u64 v[18:19], v[18:19], 1, s[8:9]
	global_store_short v[18:19], v20, off sc1
	v_add_u32_e32 v18, v180, v32
	v_ashrrev_i32_e32 v19, 31, v18
	v_mul_f32_e32 v20, v48, v41
	v_cvt_pk_bf16_f32 v20, v20, s0
	v_lshl_add_u64 v[18:19], v[18:19], 1, s[8:9]
	global_store_short v[18:19], v20, off sc1
	v_add_u32_e32 v18, v182, v32
	v_ashrrev_i32_e32 v19, 31, v18
	v_mul_f32_e32 v20, v48, v40
	v_cvt_pk_bf16_f32 v20, v20, s0
	v_lshl_add_u64 v[18:19], v[18:19], 1, s[8:9]
	global_store_short v[18:19], v20, off sc1
	v_add_u32_e32 v18, v185, v32
	v_ashrrev_i32_e32 v19, 31, v18
	v_mul_f32_e32 v20, v48, v39
	v_cvt_pk_bf16_f32 v20, v20, s0
	v_lshl_add_u64 v[18:19], v[18:19], 1, s[8:9]
	global_store_short v[18:19], v20, off sc1
	v_add_u32_e32 v18, v187, v32
	v_ashrrev_i32_e32 v19, 31, v18
	v_mul_f32_e32 v20, v48, v38
	v_cvt_pk_bf16_f32 v20, v20, s0
	v_lshl_add_u64 v[18:19], v[18:19], 1, s[8:9]
	global_store_short v[18:19], v20, off sc1
	v_add_u32_e32 v18, v189, v32
	v_ashrrev_i32_e32 v19, 31, v18
	v_mul_f32_e32 v20, v48, v37
	v_cvt_pk_bf16_f32 v20, v20, s0
	v_lshl_add_u64 v[18:19], v[18:19], 1, s[8:9]
	global_store_short v[18:19], v20, off sc1
	v_add_u32_e32 v18, v190, v32
	v_ashrrev_i32_e32 v19, 31, v18
	v_mul_f32_e32 v20, v48, v36
	v_cvt_pk_bf16_f32 v20, v20, s0
	v_lshl_add_u64 v[18:19], v[18:19], 1, s[8:9]
	global_store_short v[18:19], v20, off sc1
	v_add_u32_e32 v18, v191, v32
	v_ashrrev_i32_e32 v19, 31, v18
	v_mul_f32_e32 v20, v48, v35
	v_cvt_pk_bf16_f32 v20, v20, s0
	v_lshl_add_u64 v[18:19], v[18:19], 1, s[8:9]
	global_store_short v[18:19], v20, off sc1
	v_add_u32_e32 v18, v192, v32
	v_ashrrev_i32_e32 v19, 31, v18
	v_mul_f32_e32 v20, v48, v34
	v_cvt_pk_bf16_f32 v20, v20, s0
	v_lshl_add_u64 v[18:19], v[18:19], 1, s[8:9]
	global_store_short v[18:19], v20, off sc1
	v_add_u32_e32 v18, v193, v32
	v_ashrrev_i32_e32 v19, 31, v18
	v_mul_f32_e32 v20, v48, v33
	v_cvt_pk_bf16_f32 v20, v20, s0
	v_lshl_add_u64 v[18:19], v[18:19], 1, s[8:9]
	global_store_short v[18:19], v20, off sc1
	global_load_dword v20, v[86:87], off offset:384
	v_add_u32_e32 v18, v188, v16
	global_load_dword v26, v[82:83], off offset:384
	global_load_dword v25, v[78:79], off offset:384
	global_load_dword v24, v[72:73], off offset:384
	global_load_dword v23, v[74:75], off offset:384
	global_load_dword v21, v[80:81], off offset:384
	global_load_dword v22, v[76:77], off offset:384
	s_waitcnt vmcnt(23)
	v_add_f32_e32 v17, 1.0, v17
	s_waitcnt vmcnt(22)
	v_mul_f32_e32 v32, v30, v17
	v_ashrrev_i32_e32 v19, 31, v18
	v_lshl_add_u64 v[18:19], v[18:19], 1, s[8:9]
	v_add_u32_e32 v30, v186, v16
	s_waitcnt vmcnt(18)
	v_fmac_f32_e32 v29, v0, v102
	v_mul_f32_e32 v0, v32, v29
	v_cvt_pk_bf16_f32 v0, v0, s0
	global_store_short v[18:19], v0, off sc1
	global_load_dword v19, v[90:91], off offset:384
	v_ashrrev_i32_e32 v31, 31, v30
	global_load_dword v18, v[92:93], off offset:384
	v_fmac_f32_e32 v28, v1, v102
	v_mul_f32_e32 v0, v32, v28
	v_cvt_pk_bf16_f32 v17, v0, s0
	v_lshl_add_u64 v[0:1], v[30:31], 1, s[8:9]
	global_store_short v[0:1], v17, off sc1
	v_add_u32_e32 v0, v184, v16
	v_fmac_f32_e32 v27, v2, v102
	global_load_dword v17, v[94:95], off offset:384
	v_ashrrev_i32_e32 v1, 31, v0
	v_mul_f32_e32 v2, v32, v27
	v_cvt_pk_bf16_f32 v2, v2, s0
	v_lshl_add_u64 v[0:1], v[0:1], 1, s[8:9]
	global_store_short v[0:1], v2, off sc1
	v_add_u32_e32 v0, v183, v16
	global_load_dword v2, v[96:97], off offset:384
	v_ashrrev_i32_e32 v1, 31, v0
	v_lshl_add_u64 v[0:1], v[0:1], 1, s[8:9]
	v_add_u32_e32 v30, v181, v16
	v_ashrrev_i32_e32 v31, 31, v30
	v_lshl_add_u64 v[30:31], v[30:31], 1, s[8:9]
	v_fmac_f32_e32 v106, v29, v29
	global_store_dword v[104:105], v29, off offset:384 sc1
	global_store_dword v[88:89], v28, off offset:384 sc1
	global_store_dword v[84:85], v27, off offset:384 sc1
	s_waitcnt vmcnt(16)
	v_fmac_f32_e32 v20, v9, v102
	global_store_dword v[86:87], v20, off offset:384 sc1
	s_waitcnt vmcnt(16)
	v_fmac_f32_e32 v26, v3, v102
	v_mul_f32_e32 v3, v32, v26
	v_cvt_pk_bf16_f32 v3, v3, s0
	global_store_short v[0:1], v3, off sc1
	global_load_dword v1, v[98:99], off offset:384
	s_waitcnt vmcnt(17)
	v_fmac_f32_e32 v25, v4, v102
	v_mul_f32_e32 v0, v32, v25
	v_cvt_pk_bf16_f32 v0, v0, s0
	global_store_short v[30:31], v0, off sc1
	global_load_dword v0, v[100:101], off offset:384
	v_add_u32_e32 v30, v179, v16
	s_waitcnt vmcnt(18)
	v_fmac_f32_e32 v24, v5, v102
	v_ashrrev_i32_e32 v31, 31, v30
	v_mul_f32_e32 v3, v32, v24
	v_cvt_pk_bf16_f32 v3, v3, s0
	v_lshl_add_u64 v[4:5], v[30:31], 1, s[8:9]
	global_store_short v[4:5], v3, off sc1
	v_add_u32_e32 v4, v71, v16
	s_waitcnt vmcnt(18)
	v_fmac_f32_e32 v23, v6, v102
	v_ashrrev_i32_e32 v5, 31, v4
	v_mul_f32_e32 v3, v32, v23
	v_cvt_pk_bf16_f32 v3, v3, s0
	v_lshl_add_u64 v[4:5], v[4:5], 1, s[8:9]
	global_store_short v[4:5], v3, off sc1
	v_add_u32_e32 v4, v180, v16
	s_waitcnt vmcnt(17)
	v_fmac_f32_e32 v22, v7, v102
	v_ashrrev_i32_e32 v5, 31, v4
	v_mul_f32_e32 v3, v32, v22
	v_cvt_pk_bf16_f32 v3, v3, s0
	v_lshl_add_u64 v[4:5], v[4:5], 1, s[8:9]
	global_store_short v[4:5], v3, off sc1
	v_add_u32_e32 v4, v182, v16
	v_fmac_f32_e32 v21, v8, v102
	v_ashrrev_i32_e32 v5, 31, v4
	v_mul_f32_e32 v3, v32, v21
	v_cvt_pk_bf16_f32 v3, v3, s0
	v_lshl_add_u64 v[4:5], v[4:5], 1, s[8:9]
	global_store_short v[4:5], v3, off sc1
	v_add_u32_e32 v4, v185, v16
	v_ashrrev_i32_e32 v5, 31, v4
	v_mul_f32_e32 v3, v32, v20
	v_cvt_pk_bf16_f32 v3, v3, s0
	v_lshl_add_u64 v[4:5], v[4:5], 1, s[8:9]
	global_store_short v[4:5], v3, off sc1
	v_add_u32_e32 v4, v187, v16
	s_waitcnt vmcnt(18)
	v_fmac_f32_e32 v19, v10, v102
	v_ashrrev_i32_e32 v5, 31, v4
	v_mul_f32_e32 v3, v32, v19
	v_cvt_pk_bf16_f32 v3, v3, s0
	v_lshl_add_u64 v[4:5], v[4:5], 1, s[8:9]
	global_store_short v[4:5], v3, off sc1
	v_add_u32_e32 v4, v189, v16
	s_waitcnt vmcnt(18)
	v_fmac_f32_e32 v18, v11, v102
	v_ashrrev_i32_e32 v5, 31, v4
	v_mul_f32_e32 v3, v32, v18
	v_cvt_pk_bf16_f32 v3, v3, s0
	v_lshl_add_u64 v[4:5], v[4:5], 1, s[8:9]
	global_store_short v[4:5], v3, off sc1
	v_add_u32_e32 v4, v190, v16
	s_waitcnt vmcnt(17)
	v_fmac_f32_e32 v17, v12, v102
	v_ashrrev_i32_e32 v5, 31, v4
	v_mul_f32_e32 v3, v32, v17
	v_cvt_pk_bf16_f32 v3, v3, s0
	v_lshl_add_u64 v[4:5], v[4:5], 1, s[8:9]
	global_store_short v[4:5], v3, off sc1
	v_add_u32_e32 v4, v191, v16
	s_waitcnt vmcnt(16)
	v_fmac_f32_e32 v2, v13, v102
	v_ashrrev_i32_e32 v5, 31, v4
	v_mul_f32_e32 v3, v32, v2
	v_cvt_pk_bf16_f32 v3, v3, s0
	v_lshl_add_u64 v[4:5], v[4:5], 1, s[8:9]
	global_store_short v[4:5], v3, off sc1
	v_add_u32_e32 v4, v192, v16
	v_ashrrev_i32_e32 v5, 31, v4
	v_lshl_add_u64 v[4:5], v[4:5], 1, s[8:9]
	v_xor_b32_e32 v13, 16, v164
	v_add_u32_e32 v10, v193, v16
	v_ashrrev_i32_e32 v11, 31, v10
	v_lshl_add_u64 v[10:11], v[10:11], 1, s[8:9]
	v_ashrrev_i32_e32 v71, 31, v70
	global_store_dword v[82:83], v26, off offset:384 sc1
	global_store_dword v[78:79], v25, off offset:384 sc1
	global_store_dword v[72:73], v24, off offset:384 sc1
	global_store_dword v[74:75], v23, off offset:384 sc1
	s_waitcnt vmcnt(15)
	v_fmac_f32_e32 v1, v14, v102
	v_mul_f32_e32 v3, v32, v1
	v_cvt_pk_bf16_f32 v3, v3, s0
	global_store_short v[4:5], v3, off sc1
	v_and_b32_e32 v4, 64, v164
	v_xor_b32_e32 v3, 1, v164
	v_add_u32_e32 v7, 64, v4
	v_cmp_lt_i32_e32 vcc, v3, v7
	v_xor_b32_e32 v4, 2, v164
	s_waitcnt vmcnt(14)
	v_fmac_f32_e32 v0, v15, v102
	v_cndmask_b32_e32 v3, v164, v3, vcc
	v_lshlrev_b32_e32 v3, 2, v3
	ds_bpermute_b32 v5, v3, v106
	v_cmp_lt_i32_e32 vcc, v4, v7
	v_mul_f32_e32 v12, v32, v0
	v_cvt_pk_bf16_f32 v12, v12, s0
	v_cndmask_b32_e32 v4, v164, v4, vcc
	v_lshlrev_b32_e32 v4, 2, v4
	s_waitcnt lgkmcnt(0)
	v_add_f32_e32 v6, v106, v5
	ds_bpermute_b32 v8, v4, v6
	v_xor_b32_e32 v5, 4, v164
	v_cmp_lt_i32_e32 vcc, v5, v7
	global_store_dword v[76:77], v22, off offset:384 sc1
	global_store_dword v[80:81], v21, off offset:384 sc1
	v_cndmask_b32_e32 v5, v164, v5, vcc
	v_lshlrev_b32_e32 v5, 2, v5
	s_waitcnt lgkmcnt(0)
	v_add_f32_e32 v8, v6, v8
	ds_bpermute_b32 v9, v5, v8
	v_xor_b32_e32 v6, 8, v164
	v_cmp_lt_i32_e32 vcc, v6, v7
	global_store_dword v[90:91], v19, off offset:384 sc1
	global_store_dword v[92:93], v18, off offset:384 sc1
	v_cndmask_b32_e32 v6, v164, v6, vcc
	v_lshlrev_b32_e32 v6, 2, v6
	s_waitcnt lgkmcnt(0)
	v_add_f32_e32 v8, v8, v9
	ds_bpermute_b32 v9, v6, v8
	v_cmp_lt_i32_e32 vcc, v13, v7
	global_store_dword v[94:95], v17, off offset:384 sc1
	global_store_dword v[96:97], v2, off offset:384 sc1
	v_cndmask_b32_e32 v7, v164, v13, vcc
	v_lshlrev_b32_e32 v7, 2, v7
	s_waitcnt lgkmcnt(0)
	v_add_f32_e32 v8, v8, v9
	ds_bpermute_b32 v9, v7, v8
	global_store_dword v[98:99], v1, off offset:384 sc1
	global_store_dword v[100:101], v0, off offset:384 sc1
	global_store_short v[10:11], v12, off sc1
	s_and_saveexec_b64 s[60:61], s[0:1]
	s_cbranch_execz .LBB0_1052
	s_waitcnt lgkmcnt(0)
	v_add_f32_e32 v10, v8, v9
	v_lshl_add_u64 v[8:9], v[70:71], 2, s[58:59]
	global_store_dword v[8:9], v10, off sc1

.LBB0_1122:
	s_add_i32 s58, s67, 0xffffe000
	s_lshr_b32 s58, s58, 12
	s_mulk_i32 s58, 0x1800
	s_addk_i32 s58, 0x1800
	s_cmp_gt_i32 s6, 63
	s_cselect_b32 s62, s58, 0
	s_add_i32 s6, s62, 0x4800
	s_lshl_b64 s[58:59], s[6:7], 2
	s_add_u32 s6, s14, s58
	s_addc_u32 s58, s15, s59
	s_add_u32 s60, s6, 0x5ba5000
	s_addc_u32 s61, s58, 0
	s_add_i32 s6, s62, 0x9000
	s_lshl_b64 s[58:59], s[6:7], 2
	v_mov_b32_e32 v70, s66
	s_add_u32 s6, s14, s58
	ds_read_b64 v[70:71], v70
	s_addc_u32 s69, s15, s59
	s_lshl_b32 s58, s64, 14
	s_add_i32 s58, s58, 0x80000
	s_ashr_i32 s59, s58, 31
	s_lshl_b64 s[58:59], s[58:59], 2
	s_add_u32 s58, s10, s58
	s_waitcnt lgkmcnt(0)
	v_readfirstlane_b32 s63, v70
	s_addc_u32 s59, s11, s59
	v_or_b32_e32 v102, s68, v138
	v_add_u32_e32 v70, s67, v139
	v_readfirstlane_b32 s65, v71
	s_add_u32 s62, s63, 0x2000
	v_ashrrev_i32_e32 v103, 31, v102
	v_lshlrev_b32_e32 v191, 10, v70
	s_addc_u32 s63, s65, 0
	v_lshlrev_b64 v[72:73], 2, v[102:103]
	v_or_b32_e32 v187, 0x400, v191
	v_or_b32_e32 v186, 0x4400, v191
	v_or_b32_e32 v189, 0x4c00, v191
	v_or_b32_e32 v194, 0x6c00, v191
	s_add_u32 s64, s6, 0x5ba1000
	v_lshl_add_u64 v[74:75], s[60:61], 0, v[72:73]
	v_add_u32_e32 v130, v191, v102
	v_add_u32_e32 v132, v187, v102
	v_or_b32_e32 v185, 0x800, v191
	v_or_b32_e32 v184, 0xc00, v191
	v_or_b32_e32 v182, 0x2000, v191
	v_or_b32_e32 v180, 0x2400, v191
	v_or_b32_e32 v71, 0x2800, v191
	v_or_b32_e32 v181, 0x2c00, v191
	v_or_b32_e32 v183, 0x4000, v191
	v_add_u32_e32 v112, v186, v102
	v_or_b32_e32 v188, 0x4800, v191
	v_add_u32_e32 v116, v189, v102
	v_or_b32_e32 v190, 0x6000, v191
	v_or_b32_e32 v192, 0x6400, v191
	v_or_b32_e32 v193, 0x6800, v191
	v_add_u32_e32 v128, v194, v102
	s_addc_u32 s65, s69, 0
	global_load_dword v195, v[74:75], off
	v_lshl_add_u64 v[74:75], s[62:63], 0, v[72:73]
	v_ashrrev_i32_e32 v133, 31, v132
	v_add_u32_e32 v134, v185, v102
	v_add_u32_e32 v136, v184, v102
	v_add_u32_e32 v126, v182, v102
	v_add_u32_e32 v118, v180, v102
	v_add_u32_e32 v110, v71, v102
	v_add_u32_e32 v106, v181, v102
	v_add_u32_e32 v108, v183, v102
	v_ashrrev_i32_e32 v113, 31, v112
	v_add_u32_e32 v114, v188, v102
	v_ashrrev_i32_e32 v117, 31, v116
	v_add_u32_e32 v120, v190, v102
	v_add_u32_e32 v122, v192, v102
	v_add_u32_e32 v124, v193, v102
	v_ashrrev_i32_e32 v129, 31, v128
	v_ashrrev_i32_e32 v131, 31, v130
	v_lshl_add_u64 v[72:73], s[64:65], 0, v[72:73]
	global_load_dword v196, v[74:75], off
	global_load_dword v197, v[72:73], off
	v_lshl_add_u64 v[88:89], v[132:133], 2, s[12:13]
	v_ashrrev_i32_e32 v135, 31, v134
	v_ashrrev_i32_e32 v137, 31, v136
	v_ashrrev_i32_e32 v127, 31, v126
	v_ashrrev_i32_e32 v119, 31, v118
	v_ashrrev_i32_e32 v111, 31, v110
	v_ashrrev_i32_e32 v107, 31, v106
	v_ashrrev_i32_e32 v109, 31, v108
	v_lshl_add_u64 v[86:87], v[112:113], 2, s[12:13]
	v_ashrrev_i32_e32 v115, 31, v114
	v_lshl_add_u64 v[92:93], v[116:117], 2, s[12:13]
	v_ashrrev_i32_e32 v121, 31, v120
	v_ashrrev_i32_e32 v123, 31, v122
	v_ashrrev_i32_e32 v125, 31, v124
	v_lshl_add_u64 v[100:101], v[128:129], 2, s[12:13]
	v_lshl_add_u64 v[104:105], v[130:131], 2, s[12:13]
	v_lshl_add_u64 v[84:85], v[134:135], 2, s[12:13]
	v_lshl_add_u64 v[82:83], v[136:137], 2, s[12:13]
	v_lshl_add_u64 v[78:79], v[126:127], 2, s[12:13]
	v_lshl_add_u64 v[72:73], v[118:119], 2, s[12:13]
	v_lshl_add_u64 v[74:75], v[110:111], 2, s[12:13]
	v_lshl_add_u64 v[76:77], v[106:107], 2, s[12:13]
	v_lshl_add_u64 v[80:81], v[108:109], 2, s[12:13]
	global_load_dword v179, v[88:89], off
	global_load_dword v178, v[84:85], off
	global_load_dword v177, v[82:83], off
	global_load_dword v176, v[78:79], off
	global_load_dword v175, v[72:73], off
	global_load_dword v174, v[74:75], off
	global_load_dword v173, v[76:77], off
	global_load_dword v172, v[80:81], off
	v_lshl_add_u64 v[90:91], v[114:115], 2, s[12:13]
	global_load_dword v171, v[86:87], off
	global_load_dword v169, v[90:91], off
	v_lshl_add_u64 v[94:95], v[120:121], 2, s[12:13]
	v_lshl_add_u64 v[96:97], v[122:123], 2, s[12:13]
	v_lshl_add_u64 v[98:99], v[124:125], 2, s[12:13]
	global_load_dword v170, v[92:93], off
	global_load_dword v168, v[94:95], off
	global_load_dword v167, v[96:97], off
	global_load_dword v166, v[98:99], off
	global_load_dword v103, v[100:101], off
	global_load_dword v198, v[104:105], off
	v_lshl_add_u64 v[110:111], v[110:111], 1, s[8:9]
	v_lshl_add_u64 v[106:107], v[106:107], 1, s[8:9]
	global_load_dword v255, v[88:89], off offset:128
	global_load_dword v255, v[88:89], off offset:256
	global_load_dword v255, v[88:89], off offset:384
	global_load_dword v255, v[84:85], off offset:128
	global_load_dword v255, v[84:85], off offset:256
	global_load_dword v255, v[84:85], off offset:384
	global_load_dword v255, v[82:83], off offset:128
	global_load_dword v255, v[82:83], off offset:256
	global_load_dword v255, v[82:83], off offset:384
	global_load_dword v255, v[78:79], off offset:128
	global_load_dword v255, v[78:79], off offset:256
	global_load_dword v255, v[78:79], off offset:384
	global_load_dword v255, v[72:73], off offset:128
	global_load_dword v255, v[72:73], off offset:256
	global_load_dword v255, v[72:73], off offset:384
	global_load_dword v255, v[74:75], off offset:128
	global_load_dword v255, v[74:75], off offset:256
	global_load_dword v255, v[74:75], off offset:384
	global_load_dword v255, v[76:77], off offset:128
	global_load_dword v255, v[76:77], off offset:256
	global_load_dword v255, v[76:77], off offset:384
	global_load_dword v255, v[80:81], off offset:128
	global_load_dword v255, v[80:81], off offset:256
	global_load_dword v255, v[80:81], off offset:384
	global_load_dword v255, v[86:87], off offset:128
	global_load_dword v255, v[86:87], off offset:256
	global_load_dword v255, v[86:87], off offset:384
	global_load_dword v255, v[90:91], off offset:128
	global_load_dword v255, v[90:91], off offset:256
	global_load_dword v255, v[90:91], off offset:384
	global_load_dword v255, v[92:93], off offset:128
	global_load_dword v255, v[92:93], off offset:256
	global_load_dword v255, v[92:93], off offset:384
	global_load_dword v255, v[94:95], off offset:128
	global_load_dword v255, v[94:95], off offset:256
	global_load_dword v255, v[94:95], off offset:384
	global_load_dword v255, v[96:97], off offset:128
	global_load_dword v255, v[96:97], off offset:256
	global_load_dword v255, v[96:97], off offset:384
	global_load_dword v255, v[98:99], off offset:128
	global_load_dword v255, v[98:99], off offset:256
	global_load_dword v255, v[98:99], off offset:384
	global_load_dword v255, v[100:101], off offset:128
	global_load_dword v255, v[100:101], off offset:256
	global_load_dword v255, v[100:101], off offset:384
	global_load_dword v255, v[104:105], off offset:128
	global_load_dword v255, v[104:105], off offset:256
	global_load_dword v255, v[104:105], off offset:384
	s_waitcnt vmcnt(0)
	v_add_f32_e32 v197, 1.0, v197
	v_mul_f32_e32 v196, v196, v197
	v_fmac_f32_e32 v179, v49, v195
	v_fmac_f32_e32 v178, v50, v195
	v_fmac_f32_e32 v177, v51, v195
	v_fmac_f32_e32 v176, v52, v195
	v_fmac_f32_e32 v175, v53, v195
	v_fmac_f32_e32 v174, v54, v195
	v_fmac_f32_e32 v173, v55, v195
	v_fmac_f32_e32 v172, v56, v195
	v_fmac_f32_e32 v171, v57, v195
	v_fmac_f32_e32 v169, v58, v195
	v_fmac_f32_e32 v170, v59, v195
	v_fmac_f32_e32 v168, v60, v195
	v_fmac_f32_e32 v167, v61, v195
	v_fmac_f32_e32 v166, v62, v195
	v_fmac_f32_e32 v103, v63, v195
	v_fmac_f32_e32 v198, v48, v195
	v_mul_f32_e32 v48, v196, v198
	v_cvt_pk_bf16_f32 v58, v48, s0
	v_or_b32_e32 v48, 32, v102
	v_ashrrev_i32_e32 v49, 31, v48
	v_lshlrev_b64 v[52:53], 2, v[48:49]
	global_store_dword v[88:89], v179, off sc1
	global_store_dword v[84:85], v178, off sc1
	global_store_dword v[82:83], v177, off sc1
	global_store_dword v[78:79], v176, off sc1
	global_store_dword v[72:73], v175, off sc1
	global_store_dword v[74:75], v174, off sc1
	global_store_dword v[76:77], v173, off sc1
	global_store_dword v[80:81], v172, off sc1
	global_store_dword v[86:87], v171, off sc1
	global_store_dword v[90:91], v169, off sc1
	global_store_dword v[92:93], v170, off sc1
	global_store_dword v[94:95], v168, off sc1
	global_store_dword v[96:97], v167, off sc1
	global_store_dword v[98:99], v166, off sc1
	global_store_dword v[100:101], v103, off sc1
	global_store_dword v[104:105], v198, off sc1
	v_lshl_add_u64 v[50:51], v[130:131], 1, s[8:9]
	v_lshl_add_u64 v[56:57], s[64:65], 0, v[52:53]
	global_load_dword v197, v[104:105], off offset:128
	v_lshl_add_u64 v[54:55], s[62:63], 0, v[52:53]
	global_load_dword v130, v[56:57], off
	global_load_dword v131, v[54:55], off
	v_mul_f32_e32 v49, v196, v179
	global_store_short v[50:51], v58, off sc1
	v_lshl_add_u64 v[50:51], s[60:61], 0, v[52:53]
	global_load_dword v195, v[50:51], off
	v_lshl_add_u64 v[50:51], v[132:133], 1, s[8:9]
	v_cvt_pk_bf16_f32 v49, v49, s0
	global_store_short v[50:51], v49, off sc1
	v_mul_f32_e32 v49, v196, v178
	v_lshl_add_u64 v[50:51], v[134:135], 1, s[8:9]
	v_cvt_pk_bf16_f32 v49, v49, s0
	global_store_short v[50:51], v49, off sc1
	v_mul_f32_e32 v49, v196, v177
	v_lshl_add_u64 v[50:51], v[136:137], 1, s[8:9]
	v_cvt_pk_bf16_f32 v49, v49, s0
	global_store_short v[50:51], v49, off sc1
	v_mul_f32_e32 v49, v196, v176
	v_lshl_add_u64 v[50:51], v[126:127], 1, s[8:9]
	v_cvt_pk_bf16_f32 v49, v49, s0
	global_store_short v[50:51], v49, off sc1
	v_mul_f32_e32 v49, v196, v175
	v_lshl_add_u64 v[50:51], v[118:119], 1, s[8:9]
	v_cvt_pk_bf16_f32 v49, v49, s0
	global_load_dword v62, v[84:85], off offset:128
	global_load_dword v60, v[78:79], off offset:128
	global_load_dword v59, v[72:73], off offset:128
	global_load_dword v58, v[74:75], off offset:128
	global_load_dword v56, v[80:81], off offset:128
	global_load_dword v57, v[76:77], off offset:128
	global_load_dword v55, v[86:87], off offset:128
	global_load_dword v61, v[82:83], off offset:128
	global_load_dword v54, v[90:91], off offset:128
	global_load_dword v53, v[92:93], off offset:128
	global_load_dword v52, v[94:95], off offset:128
	v_mul_f32_e32 v63, v196, v174
	global_store_short v[50:51], v49, off sc1
	global_load_dword v51, v[96:97], off offset:128
	v_cvt_pk_bf16_f32 v63, v63, s0
	global_load_dword v50, v[98:99], off offset:128
	global_load_dword v49, v[100:101], off offset:128
	s_waitcnt vmcnt(19)
	v_fmac_f32_e32 v197, v32, v195
	global_store_short v[110:111], v63, off sc1
	global_load_dword v63, v[88:89], off offset:128
	v_mul_f32_e32 v110, v196, v173
	v_cvt_pk_bf16_f32 v110, v110, s0
	global_store_short v[106:107], v110, off sc1
	v_lshl_add_u64 v[106:107], v[108:109], 1, s[8:9]
	v_mul_f32_e32 v108, v196, v172
	v_cvt_pk_bf16_f32 v108, v108, s0
	global_store_short v[106:107], v108, off sc1
	v_mul_f32_e32 v108, v196, v171
	v_lshl_add_u64 v[106:107], v[112:113], 1, s[8:9]
	v_cvt_pk_bf16_f32 v108, v108, s0
	global_store_short v[106:107], v108, off sc1
	v_mul_f32_e32 v108, v196, v169
	v_lshl_add_u64 v[106:107], v[114:115], 1, s[8:9]
	v_cvt_pk_bf16_f32 v108, v108, s0
	global_store_short v[106:107], v108, off sc1
	v_mul_f32_e32 v108, v196, v170
	v_lshl_add_u64 v[106:107], v[116:117], 1, s[8:9]
	v_cvt_pk_bf16_f32 v108, v108, s0
	global_store_short v[106:107], v108, off sc1
	v_mul_f32_e32 v108, v196, v168
	v_lshl_add_u64 v[106:107], v[120:121], 1, s[8:9]
	v_cvt_pk_bf16_f32 v108, v108, s0
	global_store_short v[106:107], v108, off sc1
	v_mul_f32_e32 v108, v196, v167
	v_lshl_add_u64 v[106:107], v[122:123], 1, s[8:9]
	v_cvt_pk_bf16_f32 v108, v108, s0
	global_store_short v[106:107], v108, off sc1
	v_mul_f32_e32 v108, v196, v166
	v_lshl_add_u64 v[106:107], v[124:125], 1, s[8:9]
	v_cvt_pk_bf16_f32 v108, v108, s0
	global_store_short v[106:107], v108, off sc1
	v_mul_f32_e32 v108, v196, v103
	v_lshl_add_u64 v[106:107], v[128:129], 1, s[8:9]
	v_cvt_pk_bf16_f32 v108, v108, s0
	global_store_short v[106:107], v108, off sc1
	v_add_f32_e32 v106, 1.0, v130
	v_mul_f32_e32 v107, v131, v106
	v_add_u32_e32 v108, v191, v48
	v_ashrrev_i32_e32 v109, 31, v108
	v_mul_f32_e32 v32, v107, v197
	s_waitcnt vmcnt(25)
	v_fmac_f32_e32 v62, v34, v195
	s_waitcnt vmcnt(18)
	v_fmac_f32_e32 v61, v35, v195
	v_fmac_f32_e32 v60, v36, v195
	v_fmac_f32_e32 v59, v37, v195
	v_fmac_f32_e32 v58, v38, v195
	v_fmac_f32_e32 v57, v39, v195
	v_fmac_f32_e32 v56, v40, v195
	v_fmac_f32_e32 v55, v41, v195
	s_waitcnt vmcnt(17)
	v_fmac_f32_e32 v54, v42, v195
	s_waitcnt vmcnt(16)
	v_fmac_f32_e32 v53, v43, v195
	s_waitcnt vmcnt(15)
	v_fmac_f32_e32 v52, v44, v195
	s_waitcnt vmcnt(13)
	v_fmac_f32_e32 v51, v45, v195
	s_waitcnt vmcnt(12)
	v_fmac_f32_e32 v50, v46, v195
	s_waitcnt vmcnt(11)
	v_fmac_f32_e32 v49, v47, v195
	global_store_dword v[104:105], v197, off offset:128 sc1
	v_lshl_add_u64 v[108:109], v[108:109], 1, s[8:9]
	v_cvt_pk_bf16_f32 v32, v32, s0
	global_store_dword v[84:85], v62, off offset:128 sc1
	global_store_dword v[82:83], v61, off offset:128 sc1
	global_store_dword v[78:79], v60, off offset:128 sc1
	global_store_dword v[72:73], v59, off offset:128 sc1
	global_store_dword v[74:75], v58, off offset:128 sc1
	global_store_dword v[76:77], v57, off offset:128 sc1
	global_store_dword v[80:81], v56, off offset:128 sc1
	global_store_dword v[86:87], v55, off offset:128 sc1
	global_store_dword v[90:91], v54, off offset:128 sc1
	global_store_dword v[92:93], v53, off offset:128 sc1
	global_store_dword v[94:95], v52, off offset:128 sc1
	global_store_dword v[96:97], v51, off offset:128 sc1
	global_store_dword v[98:99], v50, off offset:128 sc1
	global_store_dword v[100:101], v49, off offset:128 sc1
	global_store_short v[108:109], v32, off sc1
	v_add_u32_e32 v108, v187, v48
	global_load_dword v45, v[88:89], off offset:256
	v_ashrrev_i32_e32 v109, 31, v108
	v_mul_f32_e32 v113, v107, v56
	v_cvt_pk_bf16_f32 v113, v113, s0
	v_mul_f32_e32 v106, v197, v197
	v_fmac_f32_e32 v106, v198, v198
	s_waitcnt vmcnt(26)
	v_fmac_f32_e32 v63, v33, v195
	v_mul_f32_e32 v34, v107, v63
	v_lshl_add_u64 v[32:33], v[108:109], 1, s[8:9]
	v_cvt_pk_bf16_f32 v34, v34, s0
	global_store_short v[32:33], v34, off sc1
	v_add_u32_e32 v32, v185, v48
	v_ashrrev_i32_e32 v33, 31, v32
	v_mul_f32_e32 v34, v107, v62
	v_lshl_add_u64 v[32:33], v[32:33], 1, s[8:9]
	v_cvt_pk_bf16_f32 v34, v34, s0
	global_store_short v[32:33], v34, off sc1
	v_add_u32_e32 v32, v184, v48
	v_ashrrev_i32_e32 v33, 31, v32
	v_mul_f32_e32 v34, v107, v61
	v_lshl_add_u64 v[32:33], v[32:33], 1, s[8:9]
	v_cvt_pk_bf16_f32 v34, v34, s0
	global_store_short v[32:33], v34, off sc1
	v_add_u32_e32 v32, v182, v48
	v_ashrrev_i32_e32 v33, 31, v32
	v_mul_f32_e32 v34, v107, v60
	v_lshl_add_u64 v[32:33], v[32:33], 1, s[8:9]
	v_cvt_pk_bf16_f32 v34, v34, s0
	global_store_short v[32:33], v34, off sc1
	v_add_u32_e32 v32, v180, v48
	v_ashrrev_i32_e32 v33, 31, v32
	v_lshl_add_u64 v[34:35], v[32:33], 1, s[8:9]
	v_mul_f32_e32 v32, v107, v59
	v_cvt_pk_bf16_f32 v42, v32, s0
	v_or_b32_e32 v32, 64, v102
	v_ashrrev_i32_e32 v33, 31, v32
	v_lshlrev_b64 v[36:37], 2, v[32:33]
	global_store_dword v[88:89], v63, off offset:128 sc1
	v_lshl_add_u64 v[40:41], s[64:65], 0, v[36:37]
	v_lshl_add_u64 v[38:39], s[62:63], 0, v[36:37]
	global_load_dword v110, v[40:41], off
	global_load_dword v111, v[38:39], off
	v_mul_f32_e32 v33, v107, v58
	global_store_short v[34:35], v42, off sc1
	v_lshl_add_u64 v[34:35], s[60:61], 0, v[36:37]
	global_load_dword v112, v[34:35], off
	v_add_u32_e32 v34, v71, v48
	v_ashrrev_i32_e32 v35, 31, v34
	v_lshl_add_u64 v[34:35], v[34:35], 1, s[8:9]
	v_cvt_pk_bf16_f32 v33, v33, s0
	global_store_short v[34:35], v33, off sc1
	v_add_u32_e32 v34, v181, v48
	v_ashrrev_i32_e32 v35, 31, v34
	v_mul_f32_e32 v33, v107, v57
	v_lshl_add_u64 v[34:35], v[34:35], 1, s[8:9]
	v_cvt_pk_bf16_f32 v33, v33, s0
	global_load_dword v38, v[90:91], off offset:256
	global_load_dword v37, v[92:93], off offset:256
	global_load_dword v36, v[94:95], off offset:256
	global_load_dword v114, v[104:105], off offset:256
	global_load_dword v47, v[84:85], off offset:256
	global_load_dword v39, v[86:87], off offset:256
	global_load_dword v46, v[82:83], off offset:256
	global_load_dword v44, v[78:79], off offset:256
	global_load_dword v43, v[72:73], off offset:256
	global_load_dword v42, v[74:75], off offset:256
	global_load_dword v40, v[80:81], off offset:256
	global_load_dword v41, v[76:77], off offset:256
	v_add_u32_e32 v108, v183, v48
	global_store_short v[34:35], v33, off sc1
	global_load_dword v35, v[96:97], off offset:256
	v_ashrrev_i32_e32 v109, 31, v108
	global_load_dword v34, v[98:99], off offset:256
	global_load_dword v33, v[100:101], off offset:256
	v_lshl_add_u64 v[108:109], v[108:109], 1, s[8:9]
	global_store_short v[108:109], v113, off sc1
	v_add_u32_e32 v108, v186, v48
	v_ashrrev_i32_e32 v109, 31, v108
	v_mul_f32_e32 v113, v107, v55
	v_lshl_add_u64 v[108:109], v[108:109], 1, s[8:9]
	v_cvt_pk_bf16_f32 v113, v113, s0
	global_store_short v[108:109], v113, off sc1
	v_add_u32_e32 v108, v188, v48
	v_ashrrev_i32_e32 v109, 31, v108
	v_mul_f32_e32 v113, v107, v54
	v_lshl_add_u64 v[108:109], v[108:109], 1, s[8:9]
	v_cvt_pk_bf16_f32 v113, v113, s0
	global_store_short v[108:109], v113, off sc1
	v_add_u32_e32 v108, v189, v48
	v_ashrrev_i32_e32 v109, 31, v108
	v_mul_f32_e32 v113, v107, v53
	v_lshl_add_u64 v[108:109], v[108:109], 1, s[8:9]
	v_cvt_pk_bf16_f32 v113, v113, s0
	global_store_short v[108:109], v113, off sc1
	v_add_u32_e32 v108, v190, v48
	v_ashrrev_i32_e32 v109, 31, v108
	v_mul_f32_e32 v113, v107, v52
	v_lshl_add_u64 v[108:109], v[108:109], 1, s[8:9]
	v_cvt_pk_bf16_f32 v113, v113, s0
	global_store_short v[108:109], v113, off sc1
	v_add_u32_e32 v108, v192, v48
	v_ashrrev_i32_e32 v109, 31, v108
	v_mul_f32_e32 v113, v107, v51
	v_lshl_add_u64 v[108:109], v[108:109], 1, s[8:9]
	v_cvt_pk_bf16_f32 v113, v113, s0
	global_store_short v[108:109], v113, off sc1
	v_add_u32_e32 v108, v193, v48
	v_ashrrev_i32_e32 v109, 31, v108
	v_mul_f32_e32 v113, v107, v50
	v_lshl_add_u64 v[108:109], v[108:109], 1, s[8:9]
	v_cvt_pk_bf16_f32 v113, v113, s0
	global_store_short v[108:109], v113, off sc1
	v_add_u32_e32 v108, v194, v48
	v_ashrrev_i32_e32 v109, 31, v108
	v_mul_f32_e32 v48, v107, v49
	v_lshl_add_u64 v[108:109], v[108:109], 1, s[8:9]
	v_cvt_pk_bf16_f32 v48, v48, s0
	global_store_short v[108:109], v48, off sc1
	v_add_u32_e32 v108, v191, v32
	v_ashrrev_i32_e32 v109, 31, v108
	s_waitcnt vmcnt(28)
	v_add_f32_e32 v48, 1.0, v110
	s_waitcnt vmcnt(27)
	v_mul_f32_e32 v48, v111, v48
	s_waitcnt vmcnt(25)
	v_fmac_f32_e32 v45, v17, v112
	global_store_dword v[88:89], v45, off offset:256 sc1
	s_waitcnt vmcnt(24)
	v_fmac_f32_e32 v38, v26, v112
	s_waitcnt vmcnt(23)
	v_fmac_f32_e32 v37, v27, v112
	s_waitcnt vmcnt(22)
	v_fmac_f32_e32 v36, v28, v112
	s_waitcnt vmcnt(21)
	v_fmac_f32_e32 v114, v16, v112
	s_waitcnt vmcnt(20)
	v_fmac_f32_e32 v47, v18, v112
	v_mul_f32_e32 v18, v48, v114
	v_lshl_add_u64 v[16:17], v[108:109], 1, s[8:9]
	v_cvt_pk_bf16_f32 v18, v18, s0
	global_store_short v[16:17], v18, off sc1
	v_add_u32_e32 v16, v187, v32
	v_ashrrev_i32_e32 v17, 31, v16
	v_mul_f32_e32 v18, v48, v45
	v_lshl_add_u64 v[16:17], v[16:17], 1, s[8:9]
	v_cvt_pk_bf16_f32 v18, v18, s0
	global_store_short v[16:17], v18, off sc1
	v_add_u32_e32 v16, v185, v32
	v_ashrrev_i32_e32 v17, 31, v16
	v_mul_f32_e32 v18, v48, v47
	v_lshl_add_u64 v[16:17], v[16:17], 1, s[8:9]
	v_cvt_pk_bf16_f32 v18, v18, s0
	s_waitcnt vmcnt(20)
	v_fmac_f32_e32 v46, v19, v112
	global_store_short v[16:17], v18, off sc1
	v_add_u32_e32 v16, v184, v32
	v_ashrrev_i32_e32 v17, 31, v16
	v_mul_f32_e32 v18, v48, v46
	v_lshl_add_u64 v[16:17], v[16:17], 1, s[8:9]
	v_cvt_pk_bf16_f32 v18, v18, s0
	global_store_short v[16:17], v18, off sc1
	v_add_u32_e32 v16, v182, v32
	v_ashrrev_i32_e32 v17, 31, v16
	v_lshl_add_u64 v[18:19], v[16:17], 1, s[8:9]
	v_or_b32_e32 v16, 0x60, v102
	v_ashrrev_i32_e32 v17, 31, v16
	s_waitcnt vmcnt(21)
	v_fmac_f32_e32 v44, v20, v112
	s_waitcnt vmcnt(20)
	v_fmac_f32_e32 v43, v21, v112
	s_waitcnt vmcnt(19)
	v_fmac_f32_e32 v42, v22, v112
	s_waitcnt vmcnt(17)
	v_fmac_f32_e32 v41, v23, v112
	v_fmac_f32_e32 v40, v24, v112
	v_fmac_f32_e32 v39, v25, v112
	s_waitcnt vmcnt(15)
	v_fmac_f32_e32 v35, v29, v112
	s_waitcnt vmcnt(14)
	v_fmac_f32_e32 v34, v30, v112
	s_waitcnt vmcnt(13)
	v_fmac_f32_e32 v33, v31, v112
	v_lshlrev_b64 v[20:21], 2, v[16:17]
	global_store_dword v[84:85], v47, off offset:256 sc1
	global_store_dword v[82:83], v46, off offset:256 sc1
	global_store_dword v[78:79], v44, off offset:256 sc1
	global_store_dword v[72:73], v43, off offset:256 sc1
	global_store_dword v[74:75], v42, off offset:256 sc1
	global_store_dword v[76:77], v41, off offset:256 sc1
	global_store_dword v[80:81], v40, off offset:256 sc1
	global_store_dword v[86:87], v39, off offset:256 sc1
	global_store_dword v[90:91], v38, off offset:256 sc1
	global_store_dword v[92:93], v37, off offset:256 sc1
	global_store_dword v[94:95], v36, off offset:256 sc1
	global_store_dword v[96:97], v35, off offset:256 sc1
	global_store_dword v[98:99], v34, off offset:256 sc1
	global_store_dword v[100:101], v33, off offset:256 sc1
	global_store_dword v[104:105], v114, off offset:256 sc1
	v_mul_f32_e32 v26, v48, v44
	v_lshl_add_u64 v[22:23], s[62:63], 0, v[20:21]
	v_lshl_add_u64 v[24:25], s[64:65], 0, v[20:21]
	global_load_dword v29, v[104:105], off offset:384
	global_load_dword v17, v[24:25], off
	global_load_dword v30, v[22:23], off
	v_cvt_pk_bf16_f32 v22, v26, s0
	global_store_short v[18:19], v22, off sc1
	v_lshl_add_u64 v[18:19], s[60:61], 0, v[20:21]
	global_load_dword v102, v[18:19], off
	v_add_u32_e32 v18, v180, v32
	v_ashrrev_i32_e32 v19, 31, v18
	v_mul_f32_e32 v20, v48, v43
	v_lshl_add_u64 v[18:19], v[18:19], 1, s[8:9]
	v_cvt_pk_bf16_f32 v20, v20, s0
	global_store_short v[18:19], v20, off sc1
	v_add_u32_e32 v18, v71, v32
	v_ashrrev_i32_e32 v19, 31, v18
	v_mul_f32_e32 v20, v48, v42
	v_lshl_add_u64 v[18:19], v[18:19], 1, s[8:9]
	v_cvt_pk_bf16_f32 v20, v20, s0
	global_store_short v[18:19], v20, off sc1
	v_add_u32_e32 v18, v181, v32
	v_ashrrev_i32_e32 v19, 31, v18
	v_mul_f32_e32 v20, v48, v41
	v_lshl_add_u64 v[18:19], v[18:19], 1, s[8:9]
	v_cvt_pk_bf16_f32 v20, v20, s0
	global_store_short v[18:19], v20, off sc1
	v_add_u32_e32 v18, v183, v32
	v_ashrrev_i32_e32 v19, 31, v18
	v_mul_f32_e32 v20, v48, v40
	v_lshl_add_u64 v[18:19], v[18:19], 1, s[8:9]
	v_cvt_pk_bf16_f32 v20, v20, s0
	global_store_short v[18:19], v20, off sc1
	v_add_u32_e32 v18, v186, v32
	v_ashrrev_i32_e32 v19, 31, v18
	v_mul_f32_e32 v20, v48, v39
	v_lshl_add_u64 v[18:19], v[18:19], 1, s[8:9]
	v_cvt_pk_bf16_f32 v20, v20, s0
	global_store_short v[18:19], v20, off sc1
	v_add_u32_e32 v18, v188, v32
	v_ashrrev_i32_e32 v19, 31, v18
	v_mul_f32_e32 v20, v48, v38
	v_lshl_add_u64 v[18:19], v[18:19], 1, s[8:9]
	v_cvt_pk_bf16_f32 v20, v20, s0
	global_store_short v[18:19], v20, off sc1
	v_add_u32_e32 v18, v189, v32
	v_ashrrev_i32_e32 v19, 31, v18
	v_mul_f32_e32 v20, v48, v37
	v_lshl_add_u64 v[18:19], v[18:19], 1, s[8:9]
	v_cvt_pk_bf16_f32 v20, v20, s0
	global_store_short v[18:19], v20, off sc1
	v_add_u32_e32 v18, v190, v32
	v_ashrrev_i32_e32 v19, 31, v18
	v_mul_f32_e32 v20, v48, v36
	v_lshl_add_u64 v[18:19], v[18:19], 1, s[8:9]
	v_cvt_pk_bf16_f32 v20, v20, s0
	global_store_short v[18:19], v20, off sc1
	v_add_u32_e32 v18, v192, v32
	v_ashrrev_i32_e32 v19, 31, v18
	v_mul_f32_e32 v20, v48, v35
	v_lshl_add_u64 v[18:19], v[18:19], 1, s[8:9]
	v_cvt_pk_bf16_f32 v20, v20, s0
	global_load_dword v28, v[88:89], off offset:384
	global_load_dword v27, v[84:85], off offset:384
	global_load_dword v25, v[78:79], off offset:384
	global_load_dword v24, v[72:73], off offset:384
	global_load_dword v23, v[74:75], off offset:384
	global_load_dword v21, v[80:81], off offset:384
	global_load_dword v22, v[76:77], off offset:384
	v_fmac_f32_e32 v106, v114, v114
	global_store_short v[18:19], v20, off sc1
	v_add_u32_e32 v18, v193, v32
	v_ashrrev_i32_e32 v19, 31, v18
	v_mul_f32_e32 v20, v48, v34
	v_lshl_add_u64 v[18:19], v[18:19], 1, s[8:9]
	v_cvt_pk_bf16_f32 v20, v20, s0
	global_store_short v[18:19], v20, off sc1
	v_add_u32_e32 v18, v194, v32
	v_ashrrev_i32_e32 v19, 31, v18
	v_mul_f32_e32 v20, v48, v33
	v_lshl_add_u64 v[18:19], v[18:19], 1, s[8:9]
	v_cvt_pk_bf16_f32 v20, v20, s0
	global_store_short v[18:19], v20, off sc1
	global_load_dword v20, v[86:87], off offset:384
	s_waitcnt vmcnt(22)
	v_add_f32_e32 v17, 1.0, v17
	global_load_dword v26, v[82:83], off offset:384
	s_waitcnt vmcnt(22)
	v_mul_f32_e32 v32, v30, v17
	v_add_u32_e32 v18, v191, v16
	s_waitcnt vmcnt(20)
	v_fmac_f32_e32 v29, v0, v102
	v_ashrrev_i32_e32 v19, 31, v18
	v_mul_f32_e32 v0, v32, v29
	v_lshl_add_u64 v[18:19], v[18:19], 1, s[8:9]
	v_cvt_pk_bf16_f32 v0, v0, s0
	global_store_short v[18:19], v0, off sc1
	global_load_dword v19, v[90:91], off offset:384
	v_add_u32_e32 v30, v187, v16
	global_load_dword v18, v[92:93], off offset:384
	v_ashrrev_i32_e32 v31, 31, v30
	v_fmac_f32_e32 v106, v29, v29
	global_store_dword v[104:105], v29, off offset:384 sc1
	s_waitcnt vmcnt(15)
	v_fmac_f32_e32 v28, v1, v102
	v_mul_f32_e32 v17, v32, v28
	v_lshl_add_u64 v[0:1], v[30:31], 1, s[8:9]
	v_cvt_pk_bf16_f32 v17, v17, s0
	global_store_short v[0:1], v17, off sc1
	v_add_u32_e32 v0, v185, v16
	s_waitcnt vmcnt(15)
	v_fmac_f32_e32 v27, v2, v102
	global_load_dword v17, v[94:95], off offset:384
	v_ashrrev_i32_e32 v1, 31, v0
	v_mul_f32_e32 v2, v32, v27
	v_lshl_add_u64 v[0:1], v[0:1], 1, s[8:9]
	v_cvt_pk_bf16_f32 v2, v2, s0
	global_store_short v[0:1], v2, off sc1
	v_add_u32_e32 v0, v184, v16
	global_load_dword v2, v[96:97], off offset:384
	v_ashrrev_i32_e32 v1, 31, v0
	v_lshl_add_u64 v[0:1], v[0:1], 1, s[8:9]
	v_add_u32_e32 v30, v182, v16
	s_waitcnt vmcnt(17)
	v_fmac_f32_e32 v25, v4, v102
	v_ashrrev_i32_e32 v31, 31, v30
	v_lshl_add_u64 v[30:31], v[30:31], 1, s[8:9]
	s_waitcnt vmcnt(16)
	v_fmac_f32_e32 v24, v5, v102
	s_waitcnt vmcnt(15)
	v_fmac_f32_e32 v23, v6, v102
	s_waitcnt vmcnt(8)
	v_fmac_f32_e32 v26, v3, v102
	v_mul_f32_e32 v3, v32, v26
	v_cvt_pk_bf16_f32 v3, v3, s0
	global_store_short v[0:1], v3, off sc1
	global_load_dword v1, v[98:99], off offset:384
	v_mul_f32_e32 v0, v32, v25
	v_cvt_pk_bf16_f32 v0, v0, s0
	global_store_short v[30:31], v0, off sc1
	global_load_dword v0, v[100:101], off offset:384
	v_add_u32_e32 v30, v180, v16
	v_ashrrev_i32_e32 v31, 31, v30
	v_mul_f32_e32 v3, v32, v24
	v_lshl_add_u64 v[4:5], v[30:31], 1, s[8:9]
	v_cvt_pk_bf16_f32 v3, v3, s0
	global_store_short v[4:5], v3, off sc1
	v_add_u32_e32 v4, v71, v16
	v_ashrrev_i32_e32 v5, 31, v4
	v_mul_f32_e32 v3, v32, v23
	v_lshl_add_u64 v[4:5], v[4:5], 1, s[8:9]
	v_cvt_pk_bf16_f32 v3, v3, s0
	global_store_short v[4:5], v3, off sc1
	v_add_u32_e32 v4, v181, v16
	v_fmac_f32_e32 v22, v7, v102
	v_ashrrev_i32_e32 v5, 31, v4
	v_mul_f32_e32 v3, v32, v22
	v_lshl_add_u64 v[4:5], v[4:5], 1, s[8:9]
	v_cvt_pk_bf16_f32 v3, v3, s0
	global_store_short v[4:5], v3, off sc1
	v_add_u32_e32 v4, v183, v16
	v_fmac_f32_e32 v21, v8, v102
	v_ashrrev_i32_e32 v5, 31, v4
	v_mul_f32_e32 v3, v32, v21
	v_lshl_add_u64 v[4:5], v[4:5], 1, s[8:9]
	v_cvt_pk_bf16_f32 v3, v3, s0
	global_store_short v[4:5], v3, off sc1
	v_add_u32_e32 v4, v186, v16
	v_fmac_f32_e32 v20, v9, v102
	v_ashrrev_i32_e32 v5, 31, v4
	v_mul_f32_e32 v3, v32, v20
	v_lshl_add_u64 v[4:5], v[4:5], 1, s[8:9]
	v_cvt_pk_bf16_f32 v3, v3, s0
	global_store_short v[4:5], v3, off sc1
	v_add_u32_e32 v4, v188, v16
	s_waitcnt vmcnt(15)
	v_fmac_f32_e32 v19, v10, v102
	v_ashrrev_i32_e32 v5, 31, v4
	v_mul_f32_e32 v3, v32, v19
	v_lshl_add_u64 v[4:5], v[4:5], 1, s[8:9]
	v_cvt_pk_bf16_f32 v3, v3, s0
	global_store_short v[4:5], v3, off sc1
	v_add_u32_e32 v4, v189, v16
	s_waitcnt vmcnt(15)
	v_fmac_f32_e32 v18, v11, v102
	v_ashrrev_i32_e32 v5, 31, v4
	v_mul_f32_e32 v3, v32, v18
	v_lshl_add_u64 v[4:5], v[4:5], 1, s[8:9]
	v_cvt_pk_bf16_f32 v3, v3, s0
	global_store_short v[4:5], v3, off sc1
	v_add_u32_e32 v4, v190, v16
	v_ashrrev_i32_e32 v5, 31, v4
	v_lshl_add_u64 v[4:5], v[4:5], 1, s[8:9]
	v_ashrrev_i32_e32 v71, 31, v70
	global_store_dword v[88:89], v28, off offset:384 sc1
	global_store_dword v[84:85], v27, off offset:384 sc1
	global_store_dword v[82:83], v26, off offset:384 sc1
	global_store_dword v[78:79], v25, off offset:384 sc1
	s_waitcnt vmcnt(17)
	v_fmac_f32_e32 v17, v12, v102
	v_mul_f32_e32 v3, v32, v17
	v_cvt_pk_bf16_f32 v3, v3, s0
	global_store_short v[4:5], v3, off sc1
	v_add_u32_e32 v4, v192, v16
	v_ashrrev_i32_e32 v5, 31, v4
	v_lshl_add_u64 v[4:5], v[4:5], 1, s[8:9]
	s_waitcnt vmcnt(16)
	v_fmac_f32_e32 v2, v13, v102
	v_mul_f32_e32 v3, v32, v2
	v_cvt_pk_bf16_f32 v3, v3, s0
	global_store_short v[4:5], v3, off sc1
	v_add_u32_e32 v4, v193, v16
	v_ashrrev_i32_e32 v5, 31, v4
	v_lshl_add_u64 v[4:5], v[4:5], 1, s[8:9]
	v_xor_b32_e32 v12, 16, v165
	global_store_dword v[72:73], v24, off offset:384 sc1
	global_store_dword v[74:75], v23, off offset:384 sc1
	global_store_dword v[76:77], v22, off offset:384 sc1
	global_store_dword v[80:81], v21, off offset:384 sc1
	global_store_dword v[86:87], v20, off offset:384 sc1
	s_waitcnt vmcnt(20)
	v_fmac_f32_e32 v1, v14, v102
	v_mul_f32_e32 v3, v32, v1
	v_cvt_pk_bf16_f32 v3, v3, s0
	global_store_short v[4:5], v3, off sc1
	v_add_u32_e32 v4, v194, v16
	v_ashrrev_i32_e32 v5, 31, v4
	v_lshl_add_u64 v[10:11], v[4:5], 1, s[8:9]
	v_and_b32_e32 v4, 64, v165
	v_xor_b32_e32 v3, 1, v165
	v_add_u32_e32 v7, 64, v4
	v_cmp_lt_i32_e32 vcc, v3, v7
	v_xor_b32_e32 v4, 2, v165
	s_waitcnt vmcnt(19)
	v_fmac_f32_e32 v0, v15, v102
	v_cndmask_b32_e32 v3, v165, v3, vcc
	v_lshlrev_b32_e32 v3, 2, v3
	ds_bpermute_b32 v5, v3, v106
	v_cmp_lt_i32_e32 vcc, v4, v7
	global_store_dword v[90:91], v19, off offset:384 sc1
	global_store_dword v[92:93], v18, off offset:384 sc1
	v_cndmask_b32_e32 v4, v165, v4, vcc
	v_lshlrev_b32_e32 v4, 2, v4
	s_waitcnt lgkmcnt(0)
	v_add_f32_e32 v6, v106, v5
	ds_bpermute_b32 v8, v4, v6
	v_xor_b32_e32 v5, 4, v165
	v_cmp_lt_i32_e32 vcc, v5, v7
	global_store_dword v[94:95], v17, off offset:384 sc1
	global_store_dword v[96:97], v2, off offset:384 sc1
	v_cndmask_b32_e32 v5, v165, v5, vcc
	v_lshlrev_b32_e32 v5, 2, v5
	s_waitcnt lgkmcnt(0)
	v_add_f32_e32 v8, v6, v8
	ds_bpermute_b32 v9, v5, v8
	v_xor_b32_e32 v6, 8, v165
	v_cmp_lt_i32_e32 vcc, v6, v7
	global_store_dword v[98:99], v1, off offset:384 sc1
	global_store_dword v[100:101], v0, off offset:384 sc1
	v_cndmask_b32_e32 v6, v165, v6, vcc
	v_lshlrev_b32_e32 v6, 2, v6
	s_waitcnt lgkmcnt(0)
	v_add_f32_e32 v8, v8, v9
	ds_bpermute_b32 v9, v6, v8
	v_cmp_lt_i32_e32 vcc, v12, v7
	s_waitcnt lgkmcnt(0)
	v_add_f32_e32 v8, v8, v9
	v_cndmask_b32_e32 v7, v165, v12, vcc
	v_lshlrev_b32_e32 v7, 2, v7
	ds_bpermute_b32 v9, v7, v8
	v_mul_f32_e32 v12, v32, v0
	v_cvt_pk_bf16_f32 v12, v12, s0
	global_store_short v[10:11], v12, off sc1
	s_and_saveexec_b64 s[60:61], s[0:1]
	s_cbranch_execz .LBB0_1124
	s_waitcnt lgkmcnt(0)
	v_add_f32_e32 v10, v8, v9
	v_lshl_add_u64 v[8:9], v[70:71], 2, s[58:59]
	global_store_dword v[8:9], v10, off sc1

.LBB0_1326:
	s_add_i32 s58, s66, 0xffffe000
	s_lshr_b32 s58, s58, 12
	s_mulk_i32 s58, 0x1800
	v_mov_b32_e32 v70, s70
	s_add_i32 s58, s58, 0xa800
	ds_read_b64 v[70:71], v70
	s_cmp_gt_i32 s6, 63
	s_cselect_b32 s6, s58, 0x9000
	s_lshl_b64 s[58:59], s[6:7], 2
	s_add_u32 s6, s14, s58
	s_addc_u32 s65, s15, s59
	s_waitcnt lgkmcnt(0)
	v_readfirstlane_b32 s58, v70
	v_readfirstlane_b32 s59, v71
	s_add_u32 s60, s58, 0x2000
	s_addc_u32 s61, s59, 0
	s_lshl_b32 s58, s64, 14
	s_add_i32 s58, s58, 0xa0000
	s_ashr_i32 s59, s58, 31
	s_lshl_b64 s[58:59], s[58:59], 2
	s_add_u32 s58, s10, s58
	s_addc_u32 s59, s11, s59
	s_add_u32 s62, s6, 0x5ba2000
	v_or_b32_e32 v102, s68, v138
	v_add_u32_e32 v70, s66, v139
	s_addc_u32 s63, s65, 0
	v_lshlrev_b32_e32 v188, 10, v70
	v_ashrrev_i32_e32 v103, 31, v102
	s_add_u32 s64, s6, 0x5ba4000
	v_lshlrev_b64 v[72:73], 2, v[102:103]
	v_or_b32_e32 v186, 0x400, v188
	v_or_b32_e32 v185, 0x4400, v188
	v_or_b32_e32 v189, 0x4c00, v188
	v_or_b32_e32 v193, 0x6c00, v188
	s_addc_u32 s65, s65, 0
	v_lshl_add_u64 v[74:75], s[62:63], 0, v[72:73]
	v_add_u32_e32 v132, v188, v102
	v_add_u32_e32 v134, v186, v102
	v_or_b32_e32 v184, 0x800, v188
	v_or_b32_e32 v183, 0xc00, v188
	v_or_b32_e32 v181, 0x2000, v188
	v_or_b32_e32 v179, 0x2400, v188
	v_or_b32_e32 v71, 0x2800, v188
	v_or_b32_e32 v180, 0x2c00, v188
	v_or_b32_e32 v182, 0x4000, v188
	v_add_u32_e32 v112, v185, v102
	v_or_b32_e32 v187, 0x4800, v188
	v_add_u32_e32 v118, v189, v102
	v_or_b32_e32 v190, 0x6000, v188
	v_or_b32_e32 v191, 0x6400, v188
	v_or_b32_e32 v192, 0x6800, v188
	v_add_u32_e32 v128, v193, v102
	global_load_dword v194, v[74:75], off
	v_lshl_add_u64 v[74:75], s[60:61], 0, v[72:73]
	v_lshl_add_u64 v[72:73], s[64:65], 0, v[72:73]
	v_ashrrev_i32_e32 v135, 31, v134
	v_add_u32_e32 v136, v184, v102
	v_add_u32_e32 v130, v183, v102
	v_add_u32_e32 v122, v181, v102
	v_add_u32_e32 v114, v179, v102
	v_add_u32_e32 v106, v71, v102
	v_add_u32_e32 v108, v180, v102
	v_add_u32_e32 v110, v182, v102
	v_ashrrev_i32_e32 v113, 31, v112
	v_add_u32_e32 v116, v187, v102
	v_ashrrev_i32_e32 v119, 31, v118
	v_add_u32_e32 v120, v190, v102
	v_add_u32_e32 v124, v191, v102
	v_add_u32_e32 v126, v192, v102
	v_ashrrev_i32_e32 v129, 31, v128
	v_ashrrev_i32_e32 v133, 31, v132
	global_load_dword v196, v[72:73], off
	v_lshl_add_u64 v[88:89], v[134:135], 2, s[12:13]
	v_ashrrev_i32_e32 v137, 31, v136
	v_ashrrev_i32_e32 v131, 31, v130
	v_ashrrev_i32_e32 v123, 31, v122
	v_ashrrev_i32_e32 v115, 31, v114
	v_ashrrev_i32_e32 v107, 31, v106
	v_ashrrev_i32_e32 v109, 31, v108
	v_ashrrev_i32_e32 v111, 31, v110
	v_lshl_add_u64 v[86:87], v[112:113], 2, s[12:13]
	v_ashrrev_i32_e32 v117, 31, v116
	v_lshl_add_u64 v[92:93], v[118:119], 2, s[12:13]
	v_ashrrev_i32_e32 v121, 31, v120
	v_ashrrev_i32_e32 v125, 31, v124
	v_ashrrev_i32_e32 v127, 31, v126
	v_lshl_add_u64 v[100:101], v[128:129], 2, s[12:13]
	v_lshl_add_u64 v[104:105], v[132:133], 2, s[12:13]
	global_load_dword v195, v[74:75], off
	v_lshl_add_u64 v[84:85], v[136:137], 2, s[12:13]
	v_lshl_add_u64 v[82:83], v[130:131], 2, s[12:13]
	v_lshl_add_u64 v[78:79], v[122:123], 2, s[12:13]
	v_lshl_add_u64 v[72:73], v[114:115], 2, s[12:13]
	v_lshl_add_u64 v[74:75], v[106:107], 2, s[12:13]
	v_lshl_add_u64 v[76:77], v[108:109], 2, s[12:13]
	v_lshl_add_u64 v[80:81], v[110:111], 2, s[12:13]
	global_load_dword v178, v[88:89], off
	global_load_dword v177, v[84:85], off
	global_load_dword v176, v[82:83], off
	global_load_dword v175, v[78:79], off
	global_load_dword v174, v[72:73], off
	global_load_dword v173, v[74:75], off
	global_load_dword v172, v[76:77], off
	global_load_dword v171, v[80:81], off
	v_lshl_add_u64 v[90:91], v[116:117], 2, s[12:13]
	global_load_dword v170, v[86:87], off
	global_load_dword v168, v[90:91], off
	v_lshl_add_u64 v[94:95], v[120:121], 2, s[12:13]
	v_lshl_add_u64 v[96:97], v[124:125], 2, s[12:13]
	v_lshl_add_u64 v[98:99], v[126:127], 2, s[12:13]
	global_load_dword v169, v[92:93], off
	global_load_dword v167, v[94:95], off
	global_load_dword v166, v[96:97], off
	global_load_dword v165, v[98:99], off
	global_load_dword v103, v[100:101], off
	global_load_dword v197, v[104:105], off
	v_lshl_add_u64 v[106:107], v[106:107], 1, s[8:9]
	global_load_dword v255, v[88:89], off offset:128
	global_load_dword v255, v[88:89], off offset:256
	global_load_dword v255, v[88:89], off offset:384
	global_load_dword v255, v[84:85], off offset:128
	global_load_dword v255, v[84:85], off offset:256
	global_load_dword v255, v[84:85], off offset:384
	global_load_dword v255, v[82:83], off offset:128
	global_load_dword v255, v[82:83], off offset:256
	global_load_dword v255, v[82:83], off offset:384
	global_load_dword v255, v[78:79], off offset:128
	global_load_dword v255, v[78:79], off offset:256
	global_load_dword v255, v[78:79], off offset:384
	global_load_dword v255, v[72:73], off offset:128
	global_load_dword v255, v[72:73], off offset:256
	global_load_dword v255, v[72:73], off offset:384
	global_load_dword v255, v[74:75], off offset:128
	global_load_dword v255, v[74:75], off offset:256
	global_load_dword v255, v[74:75], off offset:384
	global_load_dword v255, v[76:77], off offset:128
	global_load_dword v255, v[76:77], off offset:256
	global_load_dword v255, v[76:77], off offset:384
	global_load_dword v255, v[80:81], off offset:128
	global_load_dword v255, v[80:81], off offset:256
	global_load_dword v255, v[80:81], off offset:384
	global_load_dword v255, v[86:87], off offset:128
	global_load_dword v255, v[86:87], off offset:256
	global_load_dword v255, v[86:87], off offset:384
	global_load_dword v255, v[90:91], off offset:128
	global_load_dword v255, v[90:91], off offset:256
	global_load_dword v255, v[90:91], off offset:384
	global_load_dword v255, v[92:93], off offset:128
	global_load_dword v255, v[92:93], off offset:256
	global_load_dword v255, v[92:93], off offset:384
	global_load_dword v255, v[94:95], off offset:128
	global_load_dword v255, v[94:95], off offset:256
	global_load_dword v255, v[94:95], off offset:384
	global_load_dword v255, v[96:97], off offset:128
	global_load_dword v255, v[96:97], off offset:256
	global_load_dword v255, v[96:97], off offset:384
	global_load_dword v255, v[98:99], off offset:128
	global_load_dword v255, v[98:99], off offset:256
	global_load_dword v255, v[98:99], off offset:384
	global_load_dword v255, v[100:101], off offset:128
	global_load_dword v255, v[100:101], off offset:256
	global_load_dword v255, v[100:101], off offset:384
	global_load_dword v255, v[104:105], off offset:128
	global_load_dword v255, v[104:105], off offset:256
	global_load_dword v255, v[104:105], off offset:384
	s_waitcnt vmcnt(0)
	v_add_f32_e32 v196, 1.0, v196
	v_mul_f32_e32 v195, v195, v196
	v_fmac_f32_e32 v178, v49, v194
	v_fmac_f32_e32 v177, v50, v194
	v_fmac_f32_e32 v176, v51, v194
	v_fmac_f32_e32 v175, v52, v194
	v_fmac_f32_e32 v174, v53, v194
	v_fmac_f32_e32 v173, v54, v194
	v_fmac_f32_e32 v172, v55, v194
	v_fmac_f32_e32 v171, v56, v194
	v_fmac_f32_e32 v170, v57, v194
	v_fmac_f32_e32 v168, v58, v194
	v_fmac_f32_e32 v169, v59, v194
	v_fmac_f32_e32 v167, v60, v194
	v_fmac_f32_e32 v166, v61, v194
	v_fmac_f32_e32 v165, v62, v194
	v_fmac_f32_e32 v103, v63, v194
	v_fmac_f32_e32 v197, v48, v194
	v_mul_f32_e32 v48, v195, v197
	v_cvt_pk_bf16_f32 v58, v48, s0
	v_or_b32_e32 v48, 32, v102
	v_ashrrev_i32_e32 v49, 31, v48
	v_lshlrev_b64 v[52:53], 2, v[48:49]
	global_store_dword v[88:89], v178, off sc1
	global_store_dword v[84:85], v177, off sc1
	global_store_dword v[82:83], v176, off sc1
	global_store_dword v[78:79], v175, off sc1
	global_store_dword v[72:73], v174, off sc1
	global_store_dword v[74:75], v173, off sc1
	global_store_dword v[76:77], v172, off sc1
	global_store_dword v[80:81], v171, off sc1
	global_store_dword v[86:87], v170, off sc1
	global_store_dword v[90:91], v168, off sc1
	global_store_dword v[92:93], v169, off sc1
	global_store_dword v[94:95], v167, off sc1
	global_store_dword v[96:97], v166, off sc1
	global_store_dword v[98:99], v165, off sc1
	global_store_dword v[100:101], v103, off sc1
	global_store_dword v[104:105], v197, off sc1
	v_lshl_add_u64 v[50:51], v[132:133], 1, s[8:9]
	v_lshl_add_u64 v[56:57], s[64:65], 0, v[52:53]
	global_load_dword v196, v[104:105], off offset:128
	v_lshl_add_u64 v[54:55], s[60:61], 0, v[52:53]
	global_load_dword v132, v[56:57], off
	global_load_dword v133, v[54:55], off
	v_mul_f32_e32 v49, v195, v178
	global_store_short v[50:51], v58, off sc1
	v_lshl_add_u64 v[50:51], s[62:63], 0, v[52:53]
	global_load_dword v194, v[50:51], off
	v_cvt_pk_bf16_f32 v49, v49, s0
	v_lshl_add_u64 v[50:51], v[134:135], 1, s[8:9]
	global_store_short v[50:51], v49, off sc1
	v_mul_f32_e32 v49, v195, v177
	v_cvt_pk_bf16_f32 v49, v49, s0
	v_lshl_add_u64 v[50:51], v[136:137], 1, s[8:9]
	global_store_short v[50:51], v49, off sc1
	v_mul_f32_e32 v49, v195, v176
	v_cvt_pk_bf16_f32 v49, v49, s0
	v_lshl_add_u64 v[50:51], v[130:131], 1, s[8:9]
	global_store_short v[50:51], v49, off sc1
	v_mul_f32_e32 v49, v195, v175
	v_cvt_pk_bf16_f32 v49, v49, s0
	v_lshl_add_u64 v[50:51], v[122:123], 1, s[8:9]
	global_store_short v[50:51], v49, off sc1
	v_mul_f32_e32 v49, v195, v174
	v_cvt_pk_bf16_f32 v49, v49, s0
	v_lshl_add_u64 v[50:51], v[114:115], 1, s[8:9]
	global_store_short v[50:51], v49, off sc1
	v_mul_f32_e32 v49, v195, v173
	global_load_dword v62, v[84:85], off offset:128
	global_load_dword v60, v[78:79], off offset:128
	global_load_dword v59, v[72:73], off offset:128
	global_load_dword v58, v[74:75], off offset:128
	global_load_dword v56, v[80:81], off offset:128
	global_load_dword v57, v[76:77], off offset:128
	global_load_dword v55, v[86:87], off offset:128
	global_load_dword v61, v[82:83], off offset:128
	global_load_dword v54, v[90:91], off offset:128
	global_load_dword v53, v[92:93], off offset:128
	global_load_dword v52, v[94:95], off offset:128
	global_load_dword v51, v[96:97], off offset:128
	global_load_dword v50, v[98:99], off offset:128
	v_cvt_pk_bf16_f32 v63, v49, s0
	global_load_dword v49, v[100:101], off offset:128
	s_waitcnt vmcnt(19)
	v_fmac_f32_e32 v196, v32, v194
	global_store_short v[106:107], v63, off sc1
	global_load_dword v63, v[88:89], off offset:128
	v_mul_f32_e32 v106, v195, v172
	v_cvt_pk_bf16_f32 v114, v106, s0
	v_lshl_add_u64 v[106:107], v[108:109], 1, s[8:9]
	global_store_short v[106:107], v114, off sc1
	v_mul_f32_e32 v106, v195, v171
	v_cvt_pk_bf16_f32 v108, v106, s0
	v_lshl_add_u64 v[106:107], v[110:111], 1, s[8:9]
	global_store_short v[106:107], v108, off sc1
	v_mul_f32_e32 v106, v195, v170
	v_cvt_pk_bf16_f32 v108, v106, s0
	v_lshl_add_u64 v[106:107], v[112:113], 1, s[8:9]
	global_store_short v[106:107], v108, off sc1
	v_mul_f32_e32 v106, v195, v168
	v_cvt_pk_bf16_f32 v108, v106, s0
	v_lshl_add_u64 v[106:107], v[116:117], 1, s[8:9]
	global_store_short v[106:107], v108, off sc1
	v_mul_f32_e32 v106, v195, v169
	v_cvt_pk_bf16_f32 v108, v106, s0
	v_lshl_add_u64 v[106:107], v[118:119], 1, s[8:9]
	global_store_short v[106:107], v108, off sc1
	v_mul_f32_e32 v106, v195, v167
	v_cvt_pk_bf16_f32 v108, v106, s0
	v_lshl_add_u64 v[106:107], v[120:121], 1, s[8:9]
	global_store_short v[106:107], v108, off sc1
	v_mul_f32_e32 v106, v195, v166
	v_cvt_pk_bf16_f32 v108, v106, s0
	v_lshl_add_u64 v[106:107], v[124:125], 1, s[8:9]
	global_store_short v[106:107], v108, off sc1
	v_mul_f32_e32 v106, v195, v165
	v_cvt_pk_bf16_f32 v108, v106, s0
	v_lshl_add_u64 v[106:107], v[126:127], 1, s[8:9]
	global_store_short v[106:107], v108, off sc1
	v_mul_f32_e32 v106, v195, v103
	v_cvt_pk_bf16_f32 v108, v106, s0
	v_lshl_add_u64 v[106:107], v[128:129], 1, s[8:9]
	global_store_short v[106:107], v108, off sc1
	v_add_f32_e32 v106, 1.0, v132
	v_mul_f32_e32 v110, v133, v106
	v_add_u32_e32 v106, v188, v48
	s_waitcnt vmcnt(24)
	v_fmac_f32_e32 v62, v34, v194
	s_waitcnt vmcnt(17)
	v_fmac_f32_e32 v61, v35, v194
	v_fmac_f32_e32 v60, v36, v194
	v_fmac_f32_e32 v59, v37, v194
	v_fmac_f32_e32 v58, v38, v194
	v_fmac_f32_e32 v57, v39, v194
	v_fmac_f32_e32 v56, v40, v194
	v_fmac_f32_e32 v55, v41, v194
	s_waitcnt vmcnt(16)
	v_fmac_f32_e32 v54, v42, v194
	s_waitcnt vmcnt(15)
	v_fmac_f32_e32 v53, v43, v194
	s_waitcnt vmcnt(14)
	v_fmac_f32_e32 v52, v44, v194
	s_waitcnt vmcnt(13)
	v_fmac_f32_e32 v51, v45, v194
	s_waitcnt vmcnt(12)
	v_fmac_f32_e32 v50, v46, v194
	s_waitcnt vmcnt(11)
	v_fmac_f32_e32 v49, v47, v194
	v_ashrrev_i32_e32 v107, 31, v106
	global_store_dword v[104:105], v196, off offset:128 sc1
	v_mul_f32_e32 v32, v110, v196
	global_store_dword v[84:85], v62, off offset:128 sc1
	global_store_dword v[82:83], v61, off offset:128 sc1
	global_store_dword v[78:79], v60, off offset:128 sc1
	global_store_dword v[72:73], v59, off offset:128 sc1
	global_store_dword v[74:75], v58, off offset:128 sc1
	global_store_dword v[76:77], v57, off offset:128 sc1
	global_store_dword v[80:81], v56, off offset:128 sc1
	global_store_dword v[86:87], v55, off offset:128 sc1
	global_store_dword v[90:91], v54, off offset:128 sc1
	global_store_dword v[92:93], v53, off offset:128 sc1
	global_store_dword v[94:95], v52, off offset:128 sc1
	global_store_dword v[96:97], v51, off offset:128 sc1
	global_store_dword v[98:99], v50, off offset:128 sc1
	global_store_dword v[100:101], v49, off offset:128 sc1
	v_cvt_pk_bf16_f32 v32, v32, s0
	v_lshl_add_u64 v[106:107], v[106:107], 1, s[8:9]
	v_add_u32_e32 v108, v186, v48
	global_load_dword v45, v[88:89], off offset:256
	v_ashrrev_i32_e32 v109, 31, v108
	global_store_short v[106:107], v32, off sc1
	v_mul_f32_e32 v113, v110, v56
	v_cvt_pk_bf16_f32 v113, v113, s0
	v_mul_f32_e32 v106, v196, v196
	s_waitcnt vmcnt(26)
	v_fmac_f32_e32 v63, v33, v194
	v_mul_f32_e32 v32, v110, v63
	v_cvt_pk_bf16_f32 v34, v32, s0
	v_lshl_add_u64 v[32:33], v[108:109], 1, s[8:9]
	global_store_short v[32:33], v34, off sc1
	v_add_u32_e32 v32, v184, v48
	v_ashrrev_i32_e32 v33, 31, v32
	v_mul_f32_e32 v34, v110, v62
	v_cvt_pk_bf16_f32 v34, v34, s0
	v_lshl_add_u64 v[32:33], v[32:33], 1, s[8:9]
	global_store_short v[32:33], v34, off sc1
	v_add_u32_e32 v32, v183, v48
	v_ashrrev_i32_e32 v33, 31, v32
	v_mul_f32_e32 v34, v110, v61
	v_cvt_pk_bf16_f32 v34, v34, s0
	v_lshl_add_u64 v[32:33], v[32:33], 1, s[8:9]
	global_store_short v[32:33], v34, off sc1
	v_add_u32_e32 v32, v181, v48
	v_ashrrev_i32_e32 v33, 31, v32
	v_mul_f32_e32 v34, v110, v60
	v_cvt_pk_bf16_f32 v34, v34, s0
	v_lshl_add_u64 v[32:33], v[32:33], 1, s[8:9]
	global_store_short v[32:33], v34, off sc1
	v_add_u32_e32 v32, v179, v48
	v_ashrrev_i32_e32 v33, 31, v32
	v_mul_f32_e32 v34, v110, v59
	v_cvt_pk_bf16_f32 v42, v34, s0
	v_lshl_add_u64 v[34:35], v[32:33], 1, s[8:9]
	v_or_b32_e32 v32, 64, v102
	v_ashrrev_i32_e32 v33, 31, v32
	v_lshlrev_b64 v[36:37], 2, v[32:33]
	global_store_dword v[88:89], v63, off offset:128 sc1
	v_lshl_add_u64 v[40:41], s[64:65], 0, v[36:37]
	v_lshl_add_u64 v[38:39], s[60:61], 0, v[36:37]
	global_load_dword v107, v[40:41], off
	global_load_dword v111, v[38:39], off
	v_mul_f32_e32 v33, v110, v58
	global_store_short v[34:35], v42, off sc1
	v_lshl_add_u64 v[34:35], s[62:63], 0, v[36:37]
	global_load_dword v112, v[34:35], off
	v_add_u32_e32 v34, v71, v48
	v_ashrrev_i32_e32 v35, 31, v34
	v_cvt_pk_bf16_f32 v33, v33, s0
	v_lshl_add_u64 v[34:35], v[34:35], 1, s[8:9]
	global_store_short v[34:35], v33, off sc1
	v_add_u32_e32 v34, v180, v48
	v_ashrrev_i32_e32 v35, 31, v34
	v_mul_f32_e32 v33, v110, v57
	v_cvt_pk_bf16_f32 v33, v33, s0
	v_lshl_add_u64 v[34:35], v[34:35], 1, s[8:9]
	global_load_dword v38, v[90:91], off offset:256
	global_load_dword v37, v[92:93], off offset:256
	global_load_dword v36, v[94:95], off offset:256
	global_load_dword v114, v[104:105], off offset:256
	global_load_dword v47, v[84:85], off offset:256
	global_load_dword v39, v[86:87], off offset:256
	global_load_dword v46, v[82:83], off offset:256
	global_load_dword v44, v[78:79], off offset:256
	global_load_dword v43, v[72:73], off offset:256
	global_load_dword v42, v[74:75], off offset:256
	global_load_dword v40, v[80:81], off offset:256
	global_load_dword v41, v[76:77], off offset:256
	v_add_u32_e32 v108, v182, v48
	global_store_short v[34:35], v33, off sc1
	global_load_dword v35, v[96:97], off offset:256
	v_ashrrev_i32_e32 v109, 31, v108
	global_load_dword v34, v[98:99], off offset:256
	global_load_dword v33, v[100:101], off offset:256
	v_lshl_add_u64 v[108:109], v[108:109], 1, s[8:9]
	global_store_short v[108:109], v113, off sc1
	v_add_u32_e32 v108, v185, v48
	v_ashrrev_i32_e32 v109, 31, v108
	v_mul_f32_e32 v113, v110, v55
	v_cvt_pk_bf16_f32 v113, v113, s0
	v_lshl_add_u64 v[108:109], v[108:109], 1, s[8:9]
	global_store_short v[108:109], v113, off sc1
	v_add_u32_e32 v108, v187, v48
	v_ashrrev_i32_e32 v109, 31, v108
	v_mul_f32_e32 v113, v110, v54
	v_cvt_pk_bf16_f32 v113, v113, s0
	v_lshl_add_u64 v[108:109], v[108:109], 1, s[8:9]
	global_store_short v[108:109], v113, off sc1
	v_add_u32_e32 v108, v189, v48
	v_ashrrev_i32_e32 v109, 31, v108
	v_mul_f32_e32 v113, v110, v53
	v_cvt_pk_bf16_f32 v113, v113, s0
	v_lshl_add_u64 v[108:109], v[108:109], 1, s[8:9]
	global_store_short v[108:109], v113, off sc1
	v_add_u32_e32 v108, v190, v48
	v_ashrrev_i32_e32 v109, 31, v108
	v_mul_f32_e32 v113, v110, v52
	v_cvt_pk_bf16_f32 v113, v113, s0
	v_lshl_add_u64 v[108:109], v[108:109], 1, s[8:9]
	global_store_short v[108:109], v113, off sc1
	v_add_u32_e32 v108, v191, v48
	v_ashrrev_i32_e32 v109, 31, v108
	v_mul_f32_e32 v113, v110, v51
	v_cvt_pk_bf16_f32 v113, v113, s0
	v_lshl_add_u64 v[108:109], v[108:109], 1, s[8:9]
	global_store_short v[108:109], v113, off sc1
	v_add_u32_e32 v108, v192, v48
	v_ashrrev_i32_e32 v109, 31, v108
	v_mul_f32_e32 v113, v110, v50
	v_cvt_pk_bf16_f32 v113, v113, s0
	v_lshl_add_u64 v[108:109], v[108:109], 1, s[8:9]
	global_store_short v[108:109], v113, off sc1
	v_add_u32_e32 v108, v193, v48
	v_ashrrev_i32_e32 v109, 31, v108
	v_mul_f32_e32 v48, v110, v49
	v_cvt_pk_bf16_f32 v48, v48, s0
	v_lshl_add_u64 v[108:109], v[108:109], 1, s[8:9]
	global_store_short v[108:109], v48, off sc1
	v_add_u32_e32 v108, v188, v32
	v_ashrrev_i32_e32 v109, 31, v108
	s_waitcnt vmcnt(28)
	v_add_f32_e32 v48, 1.0, v107
	s_waitcnt vmcnt(27)
	v_mul_f32_e32 v48, v111, v48
	v_fmac_f32_e32 v106, v197, v197
	s_waitcnt vmcnt(25)
	v_fmac_f32_e32 v45, v17, v112
	global_store_dword v[88:89], v45, off offset:256 sc1
	s_waitcnt vmcnt(24)
	v_fmac_f32_e32 v38, v26, v112
	s_waitcnt vmcnt(23)
	v_fmac_f32_e32 v37, v27, v112
	s_waitcnt vmcnt(22)
	v_fmac_f32_e32 v36, v28, v112
	s_waitcnt vmcnt(21)
	v_fmac_f32_e32 v114, v16, v112
	v_mul_f32_e32 v16, v48, v114
	s_waitcnt vmcnt(20)
	v_fmac_f32_e32 v47, v18, v112
	v_cvt_pk_bf16_f32 v18, v16, s0
	v_lshl_add_u64 v[16:17], v[108:109], 1, s[8:9]
	global_store_short v[16:17], v18, off sc1
	v_add_u32_e32 v16, v186, v32
	v_ashrrev_i32_e32 v17, 31, v16
	v_mul_f32_e32 v18, v48, v45
	v_cvt_pk_bf16_f32 v18, v18, s0
	v_lshl_add_u64 v[16:17], v[16:17], 1, s[8:9]
	global_store_short v[16:17], v18, off sc1
	v_add_u32_e32 v16, v184, v32
	v_ashrrev_i32_e32 v17, 31, v16
	v_mul_f32_e32 v18, v48, v47
	v_cvt_pk_bf16_f32 v18, v18, s0
	v_lshl_add_u64 v[16:17], v[16:17], 1, s[8:9]
	s_waitcnt vmcnt(20)
	v_fmac_f32_e32 v46, v19, v112
	global_store_short v[16:17], v18, off sc1
	v_add_u32_e32 v16, v183, v32
	v_ashrrev_i32_e32 v17, 31, v16
	v_mul_f32_e32 v18, v48, v46
	s_waitcnt vmcnt(20)
	v_fmac_f32_e32 v44, v20, v112
	v_cvt_pk_bf16_f32 v18, v18, s0
	v_lshl_add_u64 v[16:17], v[16:17], 1, s[8:9]
	global_store_short v[16:17], v18, off sc1
	v_mul_f32_e32 v16, v48, v44
	v_cvt_pk_bf16_f32 v26, v16, s0
	v_or_b32_e32 v16, 0x60, v102
	v_add_u32_e32 v18, v181, v32
	v_ashrrev_i32_e32 v17, 31, v16
	s_waitcnt vmcnt(20)
	v_fmac_f32_e32 v43, v21, v112
	s_waitcnt vmcnt(19)
	v_fmac_f32_e32 v42, v22, v112
	s_waitcnt vmcnt(17)
	v_fmac_f32_e32 v41, v23, v112
	v_fmac_f32_e32 v40, v24, v112
	v_fmac_f32_e32 v39, v25, v112
	s_waitcnt vmcnt(15)
	v_fmac_f32_e32 v35, v29, v112
	s_waitcnt vmcnt(14)
	v_fmac_f32_e32 v34, v30, v112
	s_waitcnt vmcnt(13)
	v_fmac_f32_e32 v33, v31, v112
	v_ashrrev_i32_e32 v19, 31, v18
	v_lshlrev_b64 v[20:21], 2, v[16:17]
	global_store_dword v[84:85], v47, off offset:256 sc1
	global_store_dword v[82:83], v46, off offset:256 sc1
	global_store_dword v[78:79], v44, off offset:256 sc1
	global_store_dword v[72:73], v43, off offset:256 sc1
	global_store_dword v[74:75], v42, off offset:256 sc1
	global_store_dword v[76:77], v41, off offset:256 sc1
	global_store_dword v[80:81], v40, off offset:256 sc1
	global_store_dword v[86:87], v39, off offset:256 sc1
	global_store_dword v[90:91], v38, off offset:256 sc1
	global_store_dword v[92:93], v37, off offset:256 sc1
	global_store_dword v[94:95], v36, off offset:256 sc1
	global_store_dword v[96:97], v35, off offset:256 sc1
	global_store_dword v[98:99], v34, off offset:256 sc1
	global_store_dword v[100:101], v33, off offset:256 sc1
	global_store_dword v[104:105], v114, off offset:256 sc1
	v_lshl_add_u64 v[24:25], s[64:65], 0, v[20:21]
	v_lshl_add_u64 v[18:19], v[18:19], 1, s[8:9]
	global_load_dword v29, v[104:105], off offset:384
	v_lshl_add_u64 v[22:23], s[60:61], 0, v[20:21]
	global_load_dword v17, v[24:25], off
	global_load_dword v30, v[22:23], off
	global_load_dword v28, v[88:89], off offset:384
	global_load_dword v27, v[84:85], off offset:384
	v_fmac_f32_e32 v106, v114, v114
	global_store_short v[18:19], v26, off sc1
	v_lshl_add_u64 v[18:19], s[62:63], 0, v[20:21]
	global_load_dword v102, v[18:19], off
	v_add_u32_e32 v18, v179, v32
	v_ashrrev_i32_e32 v19, 31, v18
	v_mul_f32_e32 v20, v48, v43
	v_cvt_pk_bf16_f32 v20, v20, s0
	v_lshl_add_u64 v[18:19], v[18:19], 1, s[8:9]
	global_store_short v[18:19], v20, off sc1
	v_add_u32_e32 v18, v71, v32
	v_ashrrev_i32_e32 v19, 31, v18
	v_mul_f32_e32 v20, v48, v42
	v_cvt_pk_bf16_f32 v20, v20, s0
	v_lshl_add_u64 v[18:19], v[18:19], 1, s[8:9]
	global_store_short v[18:19], v20, off sc1
	v_add_u32_e32 v18, v180, v32
	v_ashrrev_i32_e32 v19, 31, v18
	v_mul_f32_e32 v20, v48, v41
	v_cvt_pk_bf16_f32 v20, v20, s0
	v_lshl_add_u64 v[18:19], v[18:19], 1, s[8:9]
	global_store_short v[18:19], v20, off sc1
	v_add_u32_e32 v18, v182, v32
	v_ashrrev_i32_e32 v19, 31, v18
	v_mul_f32_e32 v20, v48, v40
	v_cvt_pk_bf16_f32 v20, v20, s0
	v_lshl_add_u64 v[18:19], v[18:19], 1, s[8:9]
	global_store_short v[18:19], v20, off sc1
	v_add_u32_e32 v18, v185, v32
	v_ashrrev_i32_e32 v19, 31, v18
	v_mul_f32_e32 v20, v48, v39
	v_cvt_pk_bf16_f32 v20, v20, s0
	v_lshl_add_u64 v[18:19], v[18:19], 1, s[8:9]
	global_store_short v[18:19], v20, off sc1
	v_add_u32_e32 v18, v187, v32
	v_ashrrev_i32_e32 v19, 31, v18
	v_mul_f32_e32 v20, v48, v38
	v_cvt_pk_bf16_f32 v20, v20, s0
	v_lshl_add_u64 v[18:19], v[18:19], 1, s[8:9]
	global_store_short v[18:19], v20, off sc1
	v_add_u32_e32 v18, v189, v32
	v_ashrrev_i32_e32 v19, 31, v18
	v_mul_f32_e32 v20, v48, v37
	v_cvt_pk_bf16_f32 v20, v20, s0
	v_lshl_add_u64 v[18:19], v[18:19], 1, s[8:9]
	global_store_short v[18:19], v20, off sc1
	v_add_u32_e32 v18, v190, v32
	v_ashrrev_i32_e32 v19, 31, v18
	v_mul_f32_e32 v20, v48, v36
	v_cvt_pk_bf16_f32 v20, v20, s0
	v_lshl_add_u64 v[18:19], v[18:19], 1, s[8:9]
	global_store_short v[18:19], v20, off sc1
	v_add_u32_e32 v18, v191, v32
	v_ashrrev_i32_e32 v19, 31, v18
	v_mul_f32_e32 v20, v48, v35
	v_cvt_pk_bf16_f32 v20, v20, s0
	v_lshl_add_u64 v[18:19], v[18:19], 1, s[8:9]
	global_store_short v[18:19], v20, off sc1
	v_add_u32_e32 v18, v192, v32
	v_ashrrev_i32_e32 v19, 31, v18
	v_mul_f32_e32 v20, v48, v34
	v_cvt_pk_bf16_f32 v20, v20, s0
	v_lshl_add_u64 v[18:19], v[18:19], 1, s[8:9]
	global_store_short v[18:19], v20, off sc1
	v_add_u32_e32 v18, v193, v32
	v_ashrrev_i32_e32 v19, 31, v18
	v_mul_f32_e32 v20, v48, v33
	v_cvt_pk_bf16_f32 v20, v20, s0
	v_lshl_add_u64 v[18:19], v[18:19], 1, s[8:9]
	global_store_short v[18:19], v20, off sc1
	global_load_dword v20, v[86:87], off offset:384
	v_add_u32_e32 v18, v188, v16
	global_load_dword v26, v[82:83], off offset:384
	global_load_dword v25, v[78:79], off offset:384
	global_load_dword v24, v[72:73], off offset:384
	global_load_dword v23, v[74:75], off offset:384
	global_load_dword v21, v[80:81], off offset:384
	global_load_dword v22, v[76:77], off offset:384
	s_waitcnt vmcnt(23)
	v_add_f32_e32 v17, 1.0, v17
	s_waitcnt vmcnt(22)
	v_mul_f32_e32 v32, v30, v17
	v_ashrrev_i32_e32 v19, 31, v18
	v_lshl_add_u64 v[18:19], v[18:19], 1, s[8:9]
	v_add_u32_e32 v30, v186, v16
	s_waitcnt vmcnt(18)
	v_fmac_f32_e32 v29, v0, v102
	v_mul_f32_e32 v0, v32, v29
	v_cvt_pk_bf16_f32 v0, v0, s0
	global_store_short v[18:19], v0, off sc1
	global_load_dword v19, v[90:91], off offset:384
	v_ashrrev_i32_e32 v31, 31, v30
	global_load_dword v18, v[92:93], off offset:384
	v_fmac_f32_e32 v28, v1, v102
	v_mul_f32_e32 v0, v32, v28
	v_cvt_pk_bf16_f32 v17, v0, s0
	v_lshl_add_u64 v[0:1], v[30:31], 1, s[8:9]
	global_store_short v[0:1], v17, off sc1
	v_add_u32_e32 v0, v184, v16
	v_fmac_f32_e32 v27, v2, v102
	global_load_dword v17, v[94:95], off offset:384
	v_ashrrev_i32_e32 v1, 31, v0
	v_mul_f32_e32 v2, v32, v27
	v_cvt_pk_bf16_f32 v2, v2, s0
	v_lshl_add_u64 v[0:1], v[0:1], 1, s[8:9]
	global_store_short v[0:1], v2, off sc1
	v_add_u32_e32 v0, v183, v16
	global_load_dword v2, v[96:97], off offset:384
	v_ashrrev_i32_e32 v1, 31, v0
	v_lshl_add_u64 v[0:1], v[0:1], 1, s[8:9]
	v_add_u32_e32 v30, v181, v16
	v_ashrrev_i32_e32 v31, 31, v30
	v_lshl_add_u64 v[30:31], v[30:31], 1, s[8:9]
	v_fmac_f32_e32 v106, v29, v29
	global_store_dword v[104:105], v29, off offset:384 sc1
	global_store_dword v[88:89], v28, off offset:384 sc1
	global_store_dword v[84:85], v27, off offset:384 sc1
	s_waitcnt vmcnt(16)
	v_fmac_f32_e32 v20, v9, v102
	global_store_dword v[86:87], v20, off offset:384 sc1
	s_waitcnt vmcnt(16)
	v_fmac_f32_e32 v26, v3, v102
	v_mul_f32_e32 v3, v32, v26
	v_cvt_pk_bf16_f32 v3, v3, s0
	global_store_short v[0:1], v3, off sc1
	global_load_dword v1, v[98:99], off offset:384
	s_waitcnt vmcnt(17)
	v_fmac_f32_e32 v25, v4, v102
	v_mul_f32_e32 v0, v32, v25
	v_cvt_pk_bf16_f32 v0, v0, s0
	global_store_short v[30:31], v0, off sc1
	global_load_dword v0, v[100:101], off offset:384
	v_add_u32_e32 v30, v179, v16
	s_waitcnt vmcnt(18)
	v_fmac_f32_e32 v24, v5, v102
	v_ashrrev_i32_e32 v31, 31, v30
	v_mul_f32_e32 v3, v32, v24
	v_cvt_pk_bf16_f32 v3, v3, s0
	v_lshl_add_u64 v[4:5], v[30:31], 1, s[8:9]
	global_store_short v[4:5], v3, off sc1
	v_add_u32_e32 v4, v71, v16
	s_waitcnt vmcnt(18)
	v_fmac_f32_e32 v23, v6, v102
	v_ashrrev_i32_e32 v5, 31, v4
	v_mul_f32_e32 v3, v32, v23
	v_cvt_pk_bf16_f32 v3, v3, s0
	v_lshl_add_u64 v[4:5], v[4:5], 1, s[8:9]
	global_store_short v[4:5], v3, off sc1
	v_add_u32_e32 v4, v180, v16
	s_waitcnt vmcnt(17)
	v_fmac_f32_e32 v22, v7, v102
	v_ashrrev_i32_e32 v5, 31, v4
	v_mul_f32_e32 v3, v32, v22
	v_cvt_pk_bf16_f32 v3, v3, s0
	v_lshl_add_u64 v[4:5], v[4:5], 1, s[8:9]
	global_store_short v[4:5], v3, off sc1
	v_add_u32_e32 v4, v182, v16
	v_fmac_f32_e32 v21, v8, v102
	v_ashrrev_i32_e32 v5, 31, v4
	v_mul_f32_e32 v3, v32, v21
	v_cvt_pk_bf16_f32 v3, v3, s0
	v_lshl_add_u64 v[4:5], v[4:5], 1, s[8:9]
	global_store_short v[4:5], v3, off sc1
	v_add_u32_e32 v4, v185, v16
	v_ashrrev_i32_e32 v5, 31, v4
	v_mul_f32_e32 v3, v32, v20
	v_cvt_pk_bf16_f32 v3, v3, s0
	v_lshl_add_u64 v[4:5], v[4:5], 1, s[8:9]
	global_store_short v[4:5], v3, off sc1
	v_add_u32_e32 v4, v187, v16
	s_waitcnt vmcnt(18)
	v_fmac_f32_e32 v19, v10, v102
	v_ashrrev_i32_e32 v5, 31, v4
	v_mul_f32_e32 v3, v32, v19
	v_cvt_pk_bf16_f32 v3, v3, s0
	v_lshl_add_u64 v[4:5], v[4:5], 1, s[8:9]
	global_store_short v[4:5], v3, off sc1
	v_add_u32_e32 v4, v189, v16
	s_waitcnt vmcnt(18)
	v_fmac_f32_e32 v18, v11, v102
	v_ashrrev_i32_e32 v5, 31, v4
	v_mul_f32_e32 v3, v32, v18
	v_cvt_pk_bf16_f32 v3, v3, s0
	v_lshl_add_u64 v[4:5], v[4:5], 1, s[8:9]
	global_store_short v[4:5], v3, off sc1
	v_add_u32_e32 v4, v190, v16
	s_waitcnt vmcnt(17)
	v_fmac_f32_e32 v17, v12, v102
	v_ashrrev_i32_e32 v5, 31, v4
	v_mul_f32_e32 v3, v32, v17
	v_cvt_pk_bf16_f32 v3, v3, s0
	v_lshl_add_u64 v[4:5], v[4:5], 1, s[8:9]
	global_store_short v[4:5], v3, off sc1
	v_add_u32_e32 v4, v191, v16
	s_waitcnt vmcnt(16)
	v_fmac_f32_e32 v2, v13, v102
	v_ashrrev_i32_e32 v5, 31, v4
	v_mul_f32_e32 v3, v32, v2
	v_cvt_pk_bf16_f32 v3, v3, s0
	v_lshl_add_u64 v[4:5], v[4:5], 1, s[8:9]
	global_store_short v[4:5], v3, off sc1
	v_add_u32_e32 v4, v192, v16
	v_ashrrev_i32_e32 v5, 31, v4
	v_lshl_add_u64 v[4:5], v[4:5], 1, s[8:9]
	v_xor_b32_e32 v13, 16, v164
	v_add_u32_e32 v10, v193, v16
	v_ashrrev_i32_e32 v11, 31, v10
	v_lshl_add_u64 v[10:11], v[10:11], 1, s[8:9]
	v_ashrrev_i32_e32 v71, 31, v70
	global_store_dword v[82:83], v26, off offset:384 sc1
	global_store_dword v[78:79], v25, off offset:384 sc1
	global_store_dword v[72:73], v24, off offset:384 sc1
	global_store_dword v[74:75], v23, off offset:384 sc1
	s_waitcnt vmcnt(15)
	v_fmac_f32_e32 v1, v14, v102
	v_mul_f32_e32 v3, v32, v1
	v_cvt_pk_bf16_f32 v3, v3, s0
	global_store_short v[4:5], v3, off sc1
	v_and_b32_e32 v4, 64, v164
	v_xor_b32_e32 v3, 1, v164
	v_add_u32_e32 v7, 64, v4
	v_cmp_lt_i32_e32 vcc, v3, v7
	v_xor_b32_e32 v4, 2, v164
	s_waitcnt vmcnt(14)
	v_fmac_f32_e32 v0, v15, v102
	v_cndmask_b32_e32 v3, v164, v3, vcc
	v_lshlrev_b32_e32 v3, 2, v3
	ds_bpermute_b32 v5, v3, v106
	v_cmp_lt_i32_e32 vcc, v4, v7
	v_mul_f32_e32 v12, v32, v0
	v_cvt_pk_bf16_f32 v12, v12, s0
	v_cndmask_b32_e32 v4, v164, v4, vcc
	v_lshlrev_b32_e32 v4, 2, v4
	s_waitcnt lgkmcnt(0)
	v_add_f32_e32 v6, v106, v5
	ds_bpermute_b32 v8, v4, v6
	v_xor_b32_e32 v5, 4, v164
	v_cmp_lt_i32_e32 vcc, v5, v7
	global_store_dword v[76:77], v22, off offset:384 sc1
	global_store_dword v[80:81], v21, off offset:384 sc1
	v_cndmask_b32_e32 v5, v164, v5, vcc
	v_lshlrev_b32_e32 v5, 2, v5
	s_waitcnt lgkmcnt(0)
	v_add_f32_e32 v8, v6, v8
	ds_bpermute_b32 v9, v5, v8
	v_xor_b32_e32 v6, 8, v164
	v_cmp_lt_i32_e32 vcc, v6, v7
	global_store_dword v[90:91], v19, off offset:384 sc1
	global_store_dword v[92:93], v18, off offset:384 sc1
	v_cndmask_b32_e32 v6, v164, v6, vcc
	v_lshlrev_b32_e32 v6, 2, v6
	s_waitcnt lgkmcnt(0)
	v_add_f32_e32 v8, v8, v9
	ds_bpermute_b32 v9, v6, v8
	v_cmp_lt_i32_e32 vcc, v13, v7
	global_store_dword v[94:95], v17, off offset:384 sc1
	global_store_dword v[96:97], v2, off offset:384 sc1
	v_cndmask_b32_e32 v7, v164, v13, vcc
	v_lshlrev_b32_e32 v7, 2, v7
	s_waitcnt lgkmcnt(0)
	v_add_f32_e32 v8, v8, v9
	ds_bpermute_b32 v9, v7, v8
	global_store_dword v[98:99], v1, off offset:384 sc1
	global_store_dword v[100:101], v0, off offset:384 sc1
	global_store_short v[10:11], v12, off sc1
	s_and_saveexec_b64 s[60:61], s[0:1]
	s_cbranch_execz .LBB0_1328
	s_waitcnt lgkmcnt(0)
	v_add_f32_e32 v10, v8, v9
	v_lshl_add_u64 v[8:9], v[70:71], 2, s[58:59]
	global_store_dword v[8:9], v10, off sc1

.LBB0_1398:
	s_add_i32 s58, s67, 0xffffe000
	s_lshr_b32 s58, s58, 12
	s_mulk_i32 s58, 0x1800
	s_addk_i32 s58, 0x1800
	s_cmp_gt_i32 s6, 63
	s_cselect_b32 s62, s58, 0
	s_add_i32 s6, s62, 0x9000
	s_lshl_b64 s[58:59], s[6:7], 2
	s_add_u32 s6, s14, s58
	s_addc_u32 s58, s15, s59
	s_add_u32 s60, s6, 0x5ba5000
	s_addc_u32 s61, s58, 0
	s_add_i32 s6, s62, 0xd800
	s_lshl_b64 s[58:59], s[6:7], 2
	v_mov_b32_e32 v70, s66
	s_add_u32 s6, s14, s58
	ds_read_b64 v[70:71], v70
	s_addc_u32 s69, s15, s59
	s_lshl_b32 s58, s64, 14
	s_add_i32 s58, s58, 0xc0000
	s_ashr_i32 s59, s58, 31
	s_lshl_b64 s[58:59], s[58:59], 2
	s_add_u32 s58, s10, s58
	s_waitcnt lgkmcnt(0)
	v_readfirstlane_b32 s63, v70
	s_addc_u32 s59, s11, s59
	v_or_b32_e32 v102, s68, v138
	v_add_u32_e32 v70, s67, v139
	v_readfirstlane_b32 s65, v71
	s_add_u32 s62, s63, 0x3000
	v_ashrrev_i32_e32 v103, 31, v102
	v_lshlrev_b32_e32 v191, 10, v70
	s_addc_u32 s63, s65, 0
	v_lshlrev_b64 v[72:73], 2, v[102:103]
	v_or_b32_e32 v187, 0x400, v191
	v_or_b32_e32 v186, 0x4400, v191
	v_or_b32_e32 v189, 0x4c00, v191
	v_or_b32_e32 v194, 0x6c00, v191
	s_add_u32 s64, s6, 0x5ba1000
	v_lshl_add_u64 v[74:75], s[60:61], 0, v[72:73]
	v_add_u32_e32 v130, v191, v102
	v_add_u32_e32 v132, v187, v102
	v_or_b32_e32 v185, 0x800, v191
	v_or_b32_e32 v184, 0xc00, v191
	v_or_b32_e32 v182, 0x2000, v191
	v_or_b32_e32 v180, 0x2400, v191
	v_or_b32_e32 v71, 0x2800, v191
	v_or_b32_e32 v181, 0x2c00, v191
	v_or_b32_e32 v183, 0x4000, v191
	v_add_u32_e32 v112, v186, v102
	v_or_b32_e32 v188, 0x4800, v191
	v_add_u32_e32 v116, v189, v102
	v_or_b32_e32 v190, 0x6000, v191
	v_or_b32_e32 v192, 0x6400, v191
	v_or_b32_e32 v193, 0x6800, v191
	v_add_u32_e32 v128, v194, v102
	s_addc_u32 s65, s69, 0
	global_load_dword v195, v[74:75], off
	v_lshl_add_u64 v[74:75], s[62:63], 0, v[72:73]
	v_ashrrev_i32_e32 v133, 31, v132
	v_add_u32_e32 v134, v185, v102
	v_add_u32_e32 v136, v184, v102
	v_add_u32_e32 v126, v182, v102
	v_add_u32_e32 v118, v180, v102
	v_add_u32_e32 v110, v71, v102
	v_add_u32_e32 v106, v181, v102
	v_add_u32_e32 v108, v183, v102
	v_ashrrev_i32_e32 v113, 31, v112
	v_add_u32_e32 v114, v188, v102
	v_ashrrev_i32_e32 v117, 31, v116
	v_add_u32_e32 v120, v190, v102
	v_add_u32_e32 v122, v192, v102
	v_add_u32_e32 v124, v193, v102
	v_ashrrev_i32_e32 v129, 31, v128
	v_ashrrev_i32_e32 v131, 31, v130
	v_lshl_add_u64 v[72:73], s[64:65], 0, v[72:73]
	global_load_dword v196, v[74:75], off
	global_load_dword v197, v[72:73], off
	v_lshl_add_u64 v[88:89], v[132:133], 2, s[12:13]
	v_ashrrev_i32_e32 v135, 31, v134
	v_ashrrev_i32_e32 v137, 31, v136
	v_ashrrev_i32_e32 v127, 31, v126
	v_ashrrev_i32_e32 v119, 31, v118
	v_ashrrev_i32_e32 v111, 31, v110
	v_ashrrev_i32_e32 v107, 31, v106
	v_ashrrev_i32_e32 v109, 31, v108
	v_lshl_add_u64 v[86:87], v[112:113], 2, s[12:13]
	v_ashrrev_i32_e32 v115, 31, v114
	v_lshl_add_u64 v[92:93], v[116:117], 2, s[12:13]
	v_ashrrev_i32_e32 v121, 31, v120
	v_ashrrev_i32_e32 v123, 31, v122
	v_ashrrev_i32_e32 v125, 31, v124
	v_lshl_add_u64 v[100:101], v[128:129], 2, s[12:13]
	v_lshl_add_u64 v[104:105], v[130:131], 2, s[12:13]
	v_lshl_add_u64 v[84:85], v[134:135], 2, s[12:13]
	v_lshl_add_u64 v[82:83], v[136:137], 2, s[12:13]
	v_lshl_add_u64 v[78:79], v[126:127], 2, s[12:13]
	v_lshl_add_u64 v[72:73], v[118:119], 2, s[12:13]
	v_lshl_add_u64 v[74:75], v[110:111], 2, s[12:13]
	v_lshl_add_u64 v[76:77], v[106:107], 2, s[12:13]
	v_lshl_add_u64 v[80:81], v[108:109], 2, s[12:13]
	global_load_dword v179, v[88:89], off
	global_load_dword v178, v[84:85], off
	global_load_dword v177, v[82:83], off
	global_load_dword v176, v[78:79], off
	global_load_dword v175, v[72:73], off
	global_load_dword v174, v[74:75], off
	global_load_dword v173, v[76:77], off
	global_load_dword v172, v[80:81], off
	v_lshl_add_u64 v[90:91], v[114:115], 2, s[12:13]
	global_load_dword v171, v[86:87], off
	global_load_dword v169, v[90:91], off
	v_lshl_add_u64 v[94:95], v[120:121], 2, s[12:13]
	v_lshl_add_u64 v[96:97], v[122:123], 2, s[12:13]
	v_lshl_add_u64 v[98:99], v[124:125], 2, s[12:13]
	global_load_dword v170, v[92:93], off
	global_load_dword v168, v[94:95], off
	global_load_dword v167, v[96:97], off
	global_load_dword v166, v[98:99], off
	global_load_dword v103, v[100:101], off
	global_load_dword v198, v[104:105], off
	v_lshl_add_u64 v[110:111], v[110:111], 1, s[8:9]
	v_lshl_add_u64 v[106:107], v[106:107], 1, s[8:9]
	global_load_dword v255, v[88:89], off offset:128
	global_load_dword v255, v[88:89], off offset:256
	global_load_dword v255, v[88:89], off offset:384
	global_load_dword v255, v[84:85], off offset:128
	global_load_dword v255, v[84:85], off offset:256
	global_load_dword v255, v[84:85], off offset:384
	global_load_dword v255, v[82:83], off offset:128
	global_load_dword v255, v[82:83], off offset:256
	global_load_dword v255, v[82:83], off offset:384
	global_load_dword v255, v[78:79], off offset:128
	global_load_dword v255, v[78:79], off offset:256
	global_load_dword v255, v[78:79], off offset:384
	global_load_dword v255, v[72:73], off offset:128
	global_load_dword v255, v[72:73], off offset:256
	global_load_dword v255, v[72:73], off offset:384
	global_load_dword v255, v[74:75], off offset:128
	global_load_dword v255, v[74:75], off offset:256
	global_load_dword v255, v[74:75], off offset:384
	global_load_dword v255, v[76:77], off offset:128
	global_load_dword v255, v[76:77], off offset:256
	global_load_dword v255, v[76:77], off offset:384
	global_load_dword v255, v[80:81], off offset:128
	global_load_dword v255, v[80:81], off offset:256
	global_load_dword v255, v[80:81], off offset:384
	global_load_dword v255, v[86:87], off offset:128
	global_load_dword v255, v[86:87], off offset:256
	global_load_dword v255, v[86:87], off offset:384
	global_load_dword v255, v[90:91], off offset:128
	global_load_dword v255, v[90:91], off offset:256
	global_load_dword v255, v[90:91], off offset:384
	global_load_dword v255, v[92:93], off offset:128
	global_load_dword v255, v[92:93], off offset:256
	global_load_dword v255, v[92:93], off offset:384
	global_load_dword v255, v[94:95], off offset:128
	global_load_dword v255, v[94:95], off offset:256
	global_load_dword v255, v[94:95], off offset:384
	global_load_dword v255, v[96:97], off offset:128
	global_load_dword v255, v[96:97], off offset:256
	global_load_dword v255, v[96:97], off offset:384
	global_load_dword v255, v[98:99], off offset:128
	global_load_dword v255, v[98:99], off offset:256
	global_load_dword v255, v[98:99], off offset:384
	global_load_dword v255, v[100:101], off offset:128
	global_load_dword v255, v[100:101], off offset:256
	global_load_dword v255, v[100:101], off offset:384
	global_load_dword v255, v[104:105], off offset:128
	global_load_dword v255, v[104:105], off offset:256
	global_load_dword v255, v[104:105], off offset:384
	s_waitcnt vmcnt(0)
	v_add_f32_e32 v197, 1.0, v197
	v_mul_f32_e32 v196, v196, v197
	v_fmac_f32_e32 v179, v49, v195
	v_fmac_f32_e32 v178, v50, v195
	v_fmac_f32_e32 v177, v51, v195
	v_fmac_f32_e32 v176, v52, v195
	v_fmac_f32_e32 v175, v53, v195
	v_fmac_f32_e32 v174, v54, v195
	v_fmac_f32_e32 v173, v55, v195
	v_fmac_f32_e32 v172, v56, v195
	v_fmac_f32_e32 v171, v57, v195
	v_fmac_f32_e32 v169, v58, v195
	v_fmac_f32_e32 v170, v59, v195
	v_fmac_f32_e32 v168, v60, v195
	v_fmac_f32_e32 v167, v61, v195
	v_fmac_f32_e32 v166, v62, v195
	v_fmac_f32_e32 v103, v63, v195
	v_fmac_f32_e32 v198, v48, v195
	v_mul_f32_e32 v48, v196, v198
	v_cvt_pk_bf16_f32 v58, v48, s0
	v_or_b32_e32 v48, 32, v102
	v_ashrrev_i32_e32 v49, 31, v48
	v_lshlrev_b64 v[52:53], 2, v[48:49]
	global_store_dword v[88:89], v179, off sc1
	global_store_dword v[84:85], v178, off sc1
	global_store_dword v[82:83], v177, off sc1
	global_store_dword v[78:79], v176, off sc1
	global_store_dword v[72:73], v175, off sc1
	global_store_dword v[74:75], v174, off sc1
	global_store_dword v[76:77], v173, off sc1
	global_store_dword v[80:81], v172, off sc1
	global_store_dword v[86:87], v171, off sc1
	global_store_dword v[90:91], v169, off sc1
	global_store_dword v[92:93], v170, off sc1
	global_store_dword v[94:95], v168, off sc1
	global_store_dword v[96:97], v167, off sc1
	global_store_dword v[98:99], v166, off sc1
	global_store_dword v[100:101], v103, off sc1
	global_store_dword v[104:105], v198, off sc1
	v_lshl_add_u64 v[50:51], v[130:131], 1, s[8:9]
	v_lshl_add_u64 v[56:57], s[64:65], 0, v[52:53]
	global_load_dword v197, v[104:105], off offset:128
	v_lshl_add_u64 v[54:55], s[62:63], 0, v[52:53]
	global_load_dword v130, v[56:57], off
	global_load_dword v131, v[54:55], off
	v_mul_f32_e32 v49, v196, v179
	global_store_short v[50:51], v58, off sc1
	v_lshl_add_u64 v[50:51], s[60:61], 0, v[52:53]
	global_load_dword v195, v[50:51], off
	v_lshl_add_u64 v[50:51], v[132:133], 1, s[8:9]
	v_cvt_pk_bf16_f32 v49, v49, s0
	global_store_short v[50:51], v49, off sc1
	v_mul_f32_e32 v49, v196, v178
	v_lshl_add_u64 v[50:51], v[134:135], 1, s[8:9]
	v_cvt_pk_bf16_f32 v49, v49, s0
	global_store_short v[50:51], v49, off sc1
	v_mul_f32_e32 v49, v196, v177
	v_lshl_add_u64 v[50:51], v[136:137], 1, s[8:9]
	v_cvt_pk_bf16_f32 v49, v49, s0
	global_store_short v[50:51], v49, off sc1
	v_mul_f32_e32 v49, v196, v176
	v_lshl_add_u64 v[50:51], v[126:127], 1, s[8:9]
	v_cvt_pk_bf16_f32 v49, v49, s0
	global_store_short v[50:51], v49, off sc1
	v_mul_f32_e32 v49, v196, v175
	v_lshl_add_u64 v[50:51], v[118:119], 1, s[8:9]
	v_cvt_pk_bf16_f32 v49, v49, s0
	global_load_dword v62, v[84:85], off offset:128
	global_load_dword v60, v[78:79], off offset:128
	global_load_dword v59, v[72:73], off offset:128
	global_load_dword v58, v[74:75], off offset:128
	global_load_dword v56, v[80:81], off offset:128
	global_load_dword v57, v[76:77], off offset:128
	global_load_dword v55, v[86:87], off offset:128
	global_load_dword v61, v[82:83], off offset:128
	global_load_dword v54, v[90:91], off offset:128
	global_load_dword v53, v[92:93], off offset:128
	global_load_dword v52, v[94:95], off offset:128
	v_mul_f32_e32 v63, v196, v174
	global_store_short v[50:51], v49, off sc1
	global_load_dword v51, v[96:97], off offset:128
	v_cvt_pk_bf16_f32 v63, v63, s0
	global_load_dword v50, v[98:99], off offset:128
	global_load_dword v49, v[100:101], off offset:128
	s_waitcnt vmcnt(19)
	v_fmac_f32_e32 v197, v32, v195
	global_store_short v[110:111], v63, off sc1
	global_load_dword v63, v[88:89], off offset:128
	v_mul_f32_e32 v110, v196, v173
	v_cvt_pk_bf16_f32 v110, v110, s0
	global_store_short v[106:107], v110, off sc1
	v_lshl_add_u64 v[106:107], v[108:109], 1, s[8:9]
	v_mul_f32_e32 v108, v196, v172
	v_cvt_pk_bf16_f32 v108, v108, s0
	global_store_short v[106:107], v108, off sc1
	v_mul_f32_e32 v108, v196, v171
	v_lshl_add_u64 v[106:107], v[112:113], 1, s[8:9]
	v_cvt_pk_bf16_f32 v108, v108, s0
	global_store_short v[106:107], v108, off sc1
	v_mul_f32_e32 v108, v196, v169
	v_lshl_add_u64 v[106:107], v[114:115], 1, s[8:9]
	v_cvt_pk_bf16_f32 v108, v108, s0
	global_store_short v[106:107], v108, off sc1
	v_mul_f32_e32 v108, v196, v170
	v_lshl_add_u64 v[106:107], v[116:117], 1, s[8:9]
	v_cvt_pk_bf16_f32 v108, v108, s0
	global_store_short v[106:107], v108, off sc1
	v_mul_f32_e32 v108, v196, v168
	v_lshl_add_u64 v[106:107], v[120:121], 1, s[8:9]
	v_cvt_pk_bf16_f32 v108, v108, s0
	global_store_short v[106:107], v108, off sc1
	v_mul_f32_e32 v108, v196, v167
	v_lshl_add_u64 v[106:107], v[122:123], 1, s[8:9]
	v_cvt_pk_bf16_f32 v108, v108, s0
	global_store_short v[106:107], v108, off sc1
	v_mul_f32_e32 v108, v196, v166
	v_lshl_add_u64 v[106:107], v[124:125], 1, s[8:9]
	v_cvt_pk_bf16_f32 v108, v108, s0
	global_store_short v[106:107], v108, off sc1
	v_mul_f32_e32 v108, v196, v103
	v_lshl_add_u64 v[106:107], v[128:129], 1, s[8:9]
	v_cvt_pk_bf16_f32 v108, v108, s0
	global_store_short v[106:107], v108, off sc1
	v_add_f32_e32 v106, 1.0, v130
	v_mul_f32_e32 v107, v131, v106
	v_add_u32_e32 v108, v191, v48
	v_ashrrev_i32_e32 v109, 31, v108
	v_mul_f32_e32 v32, v107, v197
	s_waitcnt vmcnt(25)
	v_fmac_f32_e32 v62, v34, v195
	s_waitcnt vmcnt(18)
	v_fmac_f32_e32 v61, v35, v195
	v_fmac_f32_e32 v60, v36, v195
	v_fmac_f32_e32 v59, v37, v195
	v_fmac_f32_e32 v58, v38, v195
	v_fmac_f32_e32 v57, v39, v195
	v_fmac_f32_e32 v56, v40, v195
	v_fmac_f32_e32 v55, v41, v195
	s_waitcnt vmcnt(17)
	v_fmac_f32_e32 v54, v42, v195
	s_waitcnt vmcnt(16)
	v_fmac_f32_e32 v53, v43, v195
	s_waitcnt vmcnt(15)
	v_fmac_f32_e32 v52, v44, v195
	s_waitcnt vmcnt(13)
	v_fmac_f32_e32 v51, v45, v195
	s_waitcnt vmcnt(12)
	v_fmac_f32_e32 v50, v46, v195
	s_waitcnt vmcnt(11)
	v_fmac_f32_e32 v49, v47, v195
	global_store_dword v[104:105], v197, off offset:128 sc1
	v_lshl_add_u64 v[108:109], v[108:109], 1, s[8:9]
	v_cvt_pk_bf16_f32 v32, v32, s0
	global_store_dword v[84:85], v62, off offset:128 sc1
	global_store_dword v[82:83], v61, off offset:128 sc1
	global_store_dword v[78:79], v60, off offset:128 sc1
	global_store_dword v[72:73], v59, off offset:128 sc1
	global_store_dword v[74:75], v58, off offset:128 sc1
	global_store_dword v[76:77], v57, off offset:128 sc1
	global_store_dword v[80:81], v56, off offset:128 sc1
	global_store_dword v[86:87], v55, off offset:128 sc1
	global_store_dword v[90:91], v54, off offset:128 sc1
	global_store_dword v[92:93], v53, off offset:128 sc1
	global_store_dword v[94:95], v52, off offset:128 sc1
	global_store_dword v[96:97], v51, off offset:128 sc1
	global_store_dword v[98:99], v50, off offset:128 sc1
	global_store_dword v[100:101], v49, off offset:128 sc1
	global_store_short v[108:109], v32, off sc1
	v_add_u32_e32 v108, v187, v48
	global_load_dword v45, v[88:89], off offset:256
	v_ashrrev_i32_e32 v109, 31, v108
	v_mul_f32_e32 v113, v107, v56
	v_cvt_pk_bf16_f32 v113, v113, s0
	v_mul_f32_e32 v106, v197, v197
	v_fmac_f32_e32 v106, v198, v198
	s_waitcnt vmcnt(26)
	v_fmac_f32_e32 v63, v33, v195
	v_mul_f32_e32 v34, v107, v63
	v_lshl_add_u64 v[32:33], v[108:109], 1, s[8:9]
	v_cvt_pk_bf16_f32 v34, v34, s0
	global_store_short v[32:33], v34, off sc1
	v_add_u32_e32 v32, v185, v48
	v_ashrrev_i32_e32 v33, 31, v32
	v_mul_f32_e32 v34, v107, v62
	v_lshl_add_u64 v[32:33], v[32:33], 1, s[8:9]
	v_cvt_pk_bf16_f32 v34, v34, s0
	global_store_short v[32:33], v34, off sc1
	v_add_u32_e32 v32, v184, v48
	v_ashrrev_i32_e32 v33, 31, v32
	v_mul_f32_e32 v34, v107, v61
	v_lshl_add_u64 v[32:33], v[32:33], 1, s[8:9]
	v_cvt_pk_bf16_f32 v34, v34, s0
	global_store_short v[32:33], v34, off sc1
	v_add_u32_e32 v32, v182, v48
	v_ashrrev_i32_e32 v33, 31, v32
	v_mul_f32_e32 v34, v107, v60
	v_lshl_add_u64 v[32:33], v[32:33], 1, s[8:9]
	v_cvt_pk_bf16_f32 v34, v34, s0
	global_store_short v[32:33], v34, off sc1
	v_add_u32_e32 v32, v180, v48
	v_ashrrev_i32_e32 v33, 31, v32
	v_lshl_add_u64 v[34:35], v[32:33], 1, s[8:9]
	v_mul_f32_e32 v32, v107, v59
	v_cvt_pk_bf16_f32 v42, v32, s0
	v_or_b32_e32 v32, 64, v102
	v_ashrrev_i32_e32 v33, 31, v32
	v_lshlrev_b64 v[36:37], 2, v[32:33]
	global_store_dword v[88:89], v63, off offset:128 sc1
	v_lshl_add_u64 v[40:41], s[64:65], 0, v[36:37]
	v_lshl_add_u64 v[38:39], s[62:63], 0, v[36:37]
	global_load_dword v110, v[40:41], off
	global_load_dword v111, v[38:39], off
	v_mul_f32_e32 v33, v107, v58
	global_store_short v[34:35], v42, off sc1
	v_lshl_add_u64 v[34:35], s[60:61], 0, v[36:37]
	global_load_dword v112, v[34:35], off
	v_add_u32_e32 v34, v71, v48
	v_ashrrev_i32_e32 v35, 31, v34
	v_lshl_add_u64 v[34:35], v[34:35], 1, s[8:9]
	v_cvt_pk_bf16_f32 v33, v33, s0
	global_store_short v[34:35], v33, off sc1
	v_add_u32_e32 v34, v181, v48
	v_ashrrev_i32_e32 v35, 31, v34
	v_mul_f32_e32 v33, v107, v57
	v_lshl_add_u64 v[34:35], v[34:35], 1, s[8:9]
	v_cvt_pk_bf16_f32 v33, v33, s0
	global_load_dword v38, v[90:91], off offset:256
	global_load_dword v37, v[92:93], off offset:256
	global_load_dword v36, v[94:95], off offset:256
	global_load_dword v114, v[104:105], off offset:256
	global_load_dword v47, v[84:85], off offset:256
	global_load_dword v39, v[86:87], off offset:256
	global_load_dword v46, v[82:83], off offset:256
	global_load_dword v44, v[78:79], off offset:256
	global_load_dword v43, v[72:73], off offset:256
	global_load_dword v42, v[74:75], off offset:256
	global_load_dword v40, v[80:81], off offset:256
	global_load_dword v41, v[76:77], off offset:256
	v_add_u32_e32 v108, v183, v48
	global_store_short v[34:35], v33, off sc1
	global_load_dword v35, v[96:97], off offset:256
	v_ashrrev_i32_e32 v109, 31, v108
	global_load_dword v34, v[98:99], off offset:256
	global_load_dword v33, v[100:101], off offset:256
	v_lshl_add_u64 v[108:109], v[108:109], 1, s[8:9]
	global_store_short v[108:109], v113, off sc1
	v_add_u32_e32 v108, v186, v48
	v_ashrrev_i32_e32 v109, 31, v108
	v_mul_f32_e32 v113, v107, v55
	v_lshl_add_u64 v[108:109], v[108:109], 1, s[8:9]
	v_cvt_pk_bf16_f32 v113, v113, s0
	global_store_short v[108:109], v113, off sc1
	v_add_u32_e32 v108, v188, v48
	v_ashrrev_i32_e32 v109, 31, v108
	v_mul_f32_e32 v113, v107, v54
	v_lshl_add_u64 v[108:109], v[108:109], 1, s[8:9]
	v_cvt_pk_bf16_f32 v113, v113, s0
	global_store_short v[108:109], v113, off sc1
	v_add_u32_e32 v108, v189, v48
	v_ashrrev_i32_e32 v109, 31, v108
	v_mul_f32_e32 v113, v107, v53
	v_lshl_add_u64 v[108:109], v[108:109], 1, s[8:9]
	v_cvt_pk_bf16_f32 v113, v113, s0
	global_store_short v[108:109], v113, off sc1
	v_add_u32_e32 v108, v190, v48
	v_ashrrev_i32_e32 v109, 31, v108
	v_mul_f32_e32 v113, v107, v52
	v_lshl_add_u64 v[108:109], v[108:109], 1, s[8:9]
	v_cvt_pk_bf16_f32 v113, v113, s0
	global_store_short v[108:109], v113, off sc1
	v_add_u32_e32 v108, v192, v48
	v_ashrrev_i32_e32 v109, 31, v108
	v_mul_f32_e32 v113, v107, v51
	v_lshl_add_u64 v[108:109], v[108:109], 1, s[8:9]
	v_cvt_pk_bf16_f32 v113, v113, s0
	global_store_short v[108:109], v113, off sc1
	v_add_u32_e32 v108, v193, v48
	v_ashrrev_i32_e32 v109, 31, v108
	v_mul_f32_e32 v113, v107, v50
	v_lshl_add_u64 v[108:109], v[108:109], 1, s[8:9]
	v_cvt_pk_bf16_f32 v113, v113, s0
	global_store_short v[108:109], v113, off sc1
	v_add_u32_e32 v108, v194, v48
	v_ashrrev_i32_e32 v109, 31, v108
	v_mul_f32_e32 v48, v107, v49
	v_lshl_add_u64 v[108:109], v[108:109], 1, s[8:9]
	v_cvt_pk_bf16_f32 v48, v48, s0
	global_store_short v[108:109], v48, off sc1
	v_add_u32_e32 v108, v191, v32
	v_ashrrev_i32_e32 v109, 31, v108
	s_waitcnt vmcnt(28)
	v_add_f32_e32 v48, 1.0, v110
	s_waitcnt vmcnt(27)
	v_mul_f32_e32 v48, v111, v48
	s_waitcnt vmcnt(25)
	v_fmac_f32_e32 v45, v17, v112
	global_store_dword v[88:89], v45, off offset:256 sc1
	s_waitcnt vmcnt(24)
	v_fmac_f32_e32 v38, v26, v112
	s_waitcnt vmcnt(23)
	v_fmac_f32_e32 v37, v27, v112
	s_waitcnt vmcnt(22)
	v_fmac_f32_e32 v36, v28, v112
	s_waitcnt vmcnt(21)
	v_fmac_f32_e32 v114, v16, v112
	s_waitcnt vmcnt(20)
	v_fmac_f32_e32 v47, v18, v112
	v_mul_f32_e32 v18, v48, v114
	v_lshl_add_u64 v[16:17], v[108:109], 1, s[8:9]
	v_cvt_pk_bf16_f32 v18, v18, s0
	global_store_short v[16:17], v18, off sc1
	v_add_u32_e32 v16, v187, v32
	v_ashrrev_i32_e32 v17, 31, v16
	v_mul_f32_e32 v18, v48, v45
	v_lshl_add_u64 v[16:17], v[16:17], 1, s[8:9]
	v_cvt_pk_bf16_f32 v18, v18, s0
	global_store_short v[16:17], v18, off sc1
	v_add_u32_e32 v16, v185, v32
	v_ashrrev_i32_e32 v17, 31, v16
	v_mul_f32_e32 v18, v48, v47
	v_lshl_add_u64 v[16:17], v[16:17], 1, s[8:9]
	v_cvt_pk_bf16_f32 v18, v18, s0
	s_waitcnt vmcnt(20)
	v_fmac_f32_e32 v46, v19, v112
	global_store_short v[16:17], v18, off sc1
	v_add_u32_e32 v16, v184, v32
	v_ashrrev_i32_e32 v17, 31, v16
	v_mul_f32_e32 v18, v48, v46
	v_lshl_add_u64 v[16:17], v[16:17], 1, s[8:9]
	v_cvt_pk_bf16_f32 v18, v18, s0
	global_store_short v[16:17], v18, off sc1
	v_add_u32_e32 v16, v182, v32
	v_ashrrev_i32_e32 v17, 31, v16
	v_lshl_add_u64 v[18:19], v[16:17], 1, s[8:9]
	v_or_b32_e32 v16, 0x60, v102
	v_ashrrev_i32_e32 v17, 31, v16
	s_waitcnt vmcnt(21)
	v_fmac_f32_e32 v44, v20, v112
	s_waitcnt vmcnt(20)
	v_fmac_f32_e32 v43, v21, v112
	s_waitcnt vmcnt(19)
	v_fmac_f32_e32 v42, v22, v112
	s_waitcnt vmcnt(17)
	v_fmac_f32_e32 v41, v23, v112
	v_fmac_f32_e32 v40, v24, v112
	v_fmac_f32_e32 v39, v25, v112
	s_waitcnt vmcnt(15)
	v_fmac_f32_e32 v35, v29, v112
	s_waitcnt vmcnt(14)
	v_fmac_f32_e32 v34, v30, v112
	s_waitcnt vmcnt(13)
	v_fmac_f32_e32 v33, v31, v112
	v_lshlrev_b64 v[20:21], 2, v[16:17]
	global_store_dword v[84:85], v47, off offset:256 sc1
	global_store_dword v[82:83], v46, off offset:256 sc1
	global_store_dword v[78:79], v44, off offset:256 sc1
	global_store_dword v[72:73], v43, off offset:256 sc1
	global_store_dword v[74:75], v42, off offset:256 sc1
	global_store_dword v[76:77], v41, off offset:256 sc1
	global_store_dword v[80:81], v40, off offset:256 sc1
	global_store_dword v[86:87], v39, off offset:256 sc1
	global_store_dword v[90:91], v38, off offset:256 sc1
	global_store_dword v[92:93], v37, off offset:256 sc1
	global_store_dword v[94:95], v36, off offset:256 sc1
	global_store_dword v[96:97], v35, off offset:256 sc1
	global_store_dword v[98:99], v34, off offset:256 sc1
	global_store_dword v[100:101], v33, off offset:256 sc1
	global_store_dword v[104:105], v114, off offset:256 sc1
	v_mul_f32_e32 v26, v48, v44
	v_lshl_add_u64 v[22:23], s[62:63], 0, v[20:21]
	v_lshl_add_u64 v[24:25], s[64:65], 0, v[20:21]
	global_load_dword v29, v[104:105], off offset:384
	global_load_dword v17, v[24:25], off
	global_load_dword v30, v[22:23], off
	v_cvt_pk_bf16_f32 v22, v26, s0
	global_store_short v[18:19], v22, off sc1
	v_lshl_add_u64 v[18:19], s[60:61], 0, v[20:21]
	global_load_dword v102, v[18:19], off
	v_add_u32_e32 v18, v180, v32
	v_ashrrev_i32_e32 v19, 31, v18
	v_mul_f32_e32 v20, v48, v43
	v_lshl_add_u64 v[18:19], v[18:19], 1, s[8:9]
	v_cvt_pk_bf16_f32 v20, v20, s0
	global_store_short v[18:19], v20, off sc1
	v_add_u32_e32 v18, v71, v32
	v_ashrrev_i32_e32 v19, 31, v18
	v_mul_f32_e32 v20, v48, v42
	v_lshl_add_u64 v[18:19], v[18:19], 1, s[8:9]
	v_cvt_pk_bf16_f32 v20, v20, s0
	global_store_short v[18:19], v20, off sc1
	v_add_u32_e32 v18, v181, v32
	v_ashrrev_i32_e32 v19, 31, v18
	v_mul_f32_e32 v20, v48, v41
	v_lshl_add_u64 v[18:19], v[18:19], 1, s[8:9]
	v_cvt_pk_bf16_f32 v20, v20, s0
	global_store_short v[18:19], v20, off sc1
	v_add_u32_e32 v18, v183, v32
	v_ashrrev_i32_e32 v19, 31, v18
	v_mul_f32_e32 v20, v48, v40
	v_lshl_add_u64 v[18:19], v[18:19], 1, s[8:9]
	v_cvt_pk_bf16_f32 v20, v20, s0
	global_store_short v[18:19], v20, off sc1
	v_add_u32_e32 v18, v186, v32
	v_ashrrev_i32_e32 v19, 31, v18
	v_mul_f32_e32 v20, v48, v39
	v_lshl_add_u64 v[18:19], v[18:19], 1, s[8:9]
	v_cvt_pk_bf16_f32 v20, v20, s0
	global_store_short v[18:19], v20, off sc1
	v_add_u32_e32 v18, v188, v32
	v_ashrrev_i32_e32 v19, 31, v18
	v_mul_f32_e32 v20, v48, v38
	v_lshl_add_u64 v[18:19], v[18:19], 1, s[8:9]
	v_cvt_pk_bf16_f32 v20, v20, s0
	global_store_short v[18:19], v20, off sc1
	v_add_u32_e32 v18, v189, v32
	v_ashrrev_i32_e32 v19, 31, v18
	v_mul_f32_e32 v20, v48, v37
	v_lshl_add_u64 v[18:19], v[18:19], 1, s[8:9]
	v_cvt_pk_bf16_f32 v20, v20, s0
	global_store_short v[18:19], v20, off sc1
	v_add_u32_e32 v18, v190, v32
	v_ashrrev_i32_e32 v19, 31, v18
	v_mul_f32_e32 v20, v48, v36
	v_lshl_add_u64 v[18:19], v[18:19], 1, s[8:9]
	v_cvt_pk_bf16_f32 v20, v20, s0
	global_store_short v[18:19], v20, off sc1
	v_add_u32_e32 v18, v192, v32
	v_ashrrev_i32_e32 v19, 31, v18
	v_mul_f32_e32 v20, v48, v35
	v_lshl_add_u64 v[18:19], v[18:19], 1, s[8:9]
	v_cvt_pk_bf16_f32 v20, v20, s0
	global_load_dword v28, v[88:89], off offset:384
	global_load_dword v27, v[84:85], off offset:384
	global_load_dword v25, v[78:79], off offset:384
	global_load_dword v24, v[72:73], off offset:384
	global_load_dword v23, v[74:75], off offset:384
	global_load_dword v21, v[80:81], off offset:384
	global_load_dword v22, v[76:77], off offset:384
	v_fmac_f32_e32 v106, v114, v114
	global_store_short v[18:19], v20, off sc1
	v_add_u32_e32 v18, v193, v32
	v_ashrrev_i32_e32 v19, 31, v18
	v_mul_f32_e32 v20, v48, v34
	v_lshl_add_u64 v[18:19], v[18:19], 1, s[8:9]
	v_cvt_pk_bf16_f32 v20, v20, s0
	global_store_short v[18:19], v20, off sc1
	v_add_u32_e32 v18, v194, v32
	v_ashrrev_i32_e32 v19, 31, v18
	v_mul_f32_e32 v20, v48, v33
	v_lshl_add_u64 v[18:19], v[18:19], 1, s[8:9]
	v_cvt_pk_bf16_f32 v20, v20, s0
	global_store_short v[18:19], v20, off sc1
	global_load_dword v20, v[86:87], off offset:384
	s_waitcnt vmcnt(22)
	v_add_f32_e32 v17, 1.0, v17
	global_load_dword v26, v[82:83], off offset:384
	s_waitcnt vmcnt(22)
	v_mul_f32_e32 v32, v30, v17
	v_add_u32_e32 v18, v191, v16
	s_waitcnt vmcnt(20)
	v_fmac_f32_e32 v29, v0, v102
	v_ashrrev_i32_e32 v19, 31, v18
	v_mul_f32_e32 v0, v32, v29
	v_lshl_add_u64 v[18:19], v[18:19], 1, s[8:9]
	v_cvt_pk_bf16_f32 v0, v0, s0
	global_store_short v[18:19], v0, off sc1
	global_load_dword v19, v[90:91], off offset:384
	v_add_u32_e32 v30, v187, v16
	global_load_dword v18, v[92:93], off offset:384
	v_ashrrev_i32_e32 v31, 31, v30
	v_fmac_f32_e32 v106, v29, v29
	global_store_dword v[104:105], v29, off offset:384 sc1
	s_waitcnt vmcnt(15)
	v_fmac_f32_e32 v28, v1, v102
	v_mul_f32_e32 v17, v32, v28
	v_lshl_add_u64 v[0:1], v[30:31], 1, s[8:9]
	v_cvt_pk_bf16_f32 v17, v17, s0
	global_store_short v[0:1], v17, off sc1
	v_add_u32_e32 v0, v185, v16
	s_waitcnt vmcnt(15)
	v_fmac_f32_e32 v27, v2, v102
	global_load_dword v17, v[94:95], off offset:384
	v_ashrrev_i32_e32 v1, 31, v0
	v_mul_f32_e32 v2, v32, v27
	v_lshl_add_u64 v[0:1], v[0:1], 1, s[8:9]
	v_cvt_pk_bf16_f32 v2, v2, s0
	global_store_short v[0:1], v2, off sc1
	v_add_u32_e32 v0, v184, v16
	global_load_dword v2, v[96:97], off offset:384
	v_ashrrev_i32_e32 v1, 31, v0
	v_lshl_add_u64 v[0:1], v[0:1], 1, s[8:9]
	v_add_u32_e32 v30, v182, v16
	s_waitcnt vmcnt(17)
	v_fmac_f32_e32 v25, v4, v102
	v_ashrrev_i32_e32 v31, 31, v30
	v_lshl_add_u64 v[30:31], v[30:31], 1, s[8:9]
	s_waitcnt vmcnt(16)
	v_fmac_f32_e32 v24, v5, v102
	s_waitcnt vmcnt(15)
	v_fmac_f32_e32 v23, v6, v102
	s_waitcnt vmcnt(8)
	v_fmac_f32_e32 v26, v3, v102
	v_mul_f32_e32 v3, v32, v26
	v_cvt_pk_bf16_f32 v3, v3, s0
	global_store_short v[0:1], v3, off sc1
	global_load_dword v1, v[98:99], off offset:384
	v_mul_f32_e32 v0, v32, v25
	v_cvt_pk_bf16_f32 v0, v0, s0
	global_store_short v[30:31], v0, off sc1
	global_load_dword v0, v[100:101], off offset:384
	v_add_u32_e32 v30, v180, v16
	v_ashrrev_i32_e32 v31, 31, v30
	v_mul_f32_e32 v3, v32, v24
	v_lshl_add_u64 v[4:5], v[30:31], 1, s[8:9]
	v_cvt_pk_bf16_f32 v3, v3, s0
	global_store_short v[4:5], v3, off sc1
	v_add_u32_e32 v4, v71, v16
	v_ashrrev_i32_e32 v5, 31, v4
	v_mul_f32_e32 v3, v32, v23
	v_lshl_add_u64 v[4:5], v[4:5], 1, s[8:9]
	v_cvt_pk_bf16_f32 v3, v3, s0
	global_store_short v[4:5], v3, off sc1
	v_add_u32_e32 v4, v181, v16
	v_fmac_f32_e32 v22, v7, v102
	v_ashrrev_i32_e32 v5, 31, v4
	v_mul_f32_e32 v3, v32, v22
	v_lshl_add_u64 v[4:5], v[4:5], 1, s[8:9]
	v_cvt_pk_bf16_f32 v3, v3, s0
	global_store_short v[4:5], v3, off sc1
	v_add_u32_e32 v4, v183, v16
	v_fmac_f32_e32 v21, v8, v102
	v_ashrrev_i32_e32 v5, 31, v4
	v_mul_f32_e32 v3, v32, v21
	v_lshl_add_u64 v[4:5], v[4:5], 1, s[8:9]
	v_cvt_pk_bf16_f32 v3, v3, s0
	global_store_short v[4:5], v3, off sc1
	v_add_u32_e32 v4, v186, v16
	v_fmac_f32_e32 v20, v9, v102
	v_ashrrev_i32_e32 v5, 31, v4
	v_mul_f32_e32 v3, v32, v20
	v_lshl_add_u64 v[4:5], v[4:5], 1, s[8:9]
	v_cvt_pk_bf16_f32 v3, v3, s0
	global_store_short v[4:5], v3, off sc1
	v_add_u32_e32 v4, v188, v16
	s_waitcnt vmcnt(15)
	v_fmac_f32_e32 v19, v10, v102
	v_ashrrev_i32_e32 v5, 31, v4
	v_mul_f32_e32 v3, v32, v19
	v_lshl_add_u64 v[4:5], v[4:5], 1, s[8:9]
	v_cvt_pk_bf16_f32 v3, v3, s0
	global_store_short v[4:5], v3, off sc1
	v_add_u32_e32 v4, v189, v16
	s_waitcnt vmcnt(15)
	v_fmac_f32_e32 v18, v11, v102
	v_ashrrev_i32_e32 v5, 31, v4
	v_mul_f32_e32 v3, v32, v18
	v_lshl_add_u64 v[4:5], v[4:5], 1, s[8:9]
	v_cvt_pk_bf16_f32 v3, v3, s0
	global_store_short v[4:5], v3, off sc1
	v_add_u32_e32 v4, v190, v16
	v_ashrrev_i32_e32 v5, 31, v4
	v_lshl_add_u64 v[4:5], v[4:5], 1, s[8:9]
	v_ashrrev_i32_e32 v71, 31, v70
	global_store_dword v[88:89], v28, off offset:384 sc1
	global_store_dword v[84:85], v27, off offset:384 sc1
	global_store_dword v[82:83], v26, off offset:384 sc1
	global_store_dword v[78:79], v25, off offset:384 sc1
	s_waitcnt vmcnt(17)
	v_fmac_f32_e32 v17, v12, v102
	v_mul_f32_e32 v3, v32, v17
	v_cvt_pk_bf16_f32 v3, v3, s0
	global_store_short v[4:5], v3, off sc1
	v_add_u32_e32 v4, v192, v16
	v_ashrrev_i32_e32 v5, 31, v4
	v_lshl_add_u64 v[4:5], v[4:5], 1, s[8:9]
	s_waitcnt vmcnt(16)
	v_fmac_f32_e32 v2, v13, v102
	v_mul_f32_e32 v3, v32, v2
	v_cvt_pk_bf16_f32 v3, v3, s0
	global_store_short v[4:5], v3, off sc1
	v_add_u32_e32 v4, v193, v16
	v_ashrrev_i32_e32 v5, 31, v4
	v_lshl_add_u64 v[4:5], v[4:5], 1, s[8:9]
	v_xor_b32_e32 v12, 16, v165
	global_store_dword v[72:73], v24, off offset:384 sc1
	global_store_dword v[74:75], v23, off offset:384 sc1
	global_store_dword v[76:77], v22, off offset:384 sc1
	global_store_dword v[80:81], v21, off offset:384 sc1
	global_store_dword v[86:87], v20, off offset:384 sc1
	s_waitcnt vmcnt(20)
	v_fmac_f32_e32 v1, v14, v102
	v_mul_f32_e32 v3, v32, v1
	v_cvt_pk_bf16_f32 v3, v3, s0
	global_store_short v[4:5], v3, off sc1
	v_add_u32_e32 v4, v194, v16
	v_ashrrev_i32_e32 v5, 31, v4
	v_lshl_add_u64 v[10:11], v[4:5], 1, s[8:9]
	v_and_b32_e32 v4, 64, v165
	v_xor_b32_e32 v3, 1, v165
	v_add_u32_e32 v7, 64, v4
	v_cmp_lt_i32_e32 vcc, v3, v7
	v_xor_b32_e32 v4, 2, v165
	s_waitcnt vmcnt(19)
	v_fmac_f32_e32 v0, v15, v102
	v_cndmask_b32_e32 v3, v165, v3, vcc
	v_lshlrev_b32_e32 v3, 2, v3
	ds_bpermute_b32 v5, v3, v106
	v_cmp_lt_i32_e32 vcc, v4, v7
	global_store_dword v[90:91], v19, off offset:384 sc1
	global_store_dword v[92:93], v18, off offset:384 sc1
	v_cndmask_b32_e32 v4, v165, v4, vcc
	v_lshlrev_b32_e32 v4, 2, v4
	s_waitcnt lgkmcnt(0)
	v_add_f32_e32 v6, v106, v5
	ds_bpermute_b32 v8, v4, v6
	v_xor_b32_e32 v5, 4, v165
	v_cmp_lt_i32_e32 vcc, v5, v7
	global_store_dword v[94:95], v17, off offset:384 sc1
	global_store_dword v[96:97], v2, off offset:384 sc1
	v_cndmask_b32_e32 v5, v165, v5, vcc
	v_lshlrev_b32_e32 v5, 2, v5
	s_waitcnt lgkmcnt(0)
	v_add_f32_e32 v8, v6, v8
	ds_bpermute_b32 v9, v5, v8
	v_xor_b32_e32 v6, 8, v165
	v_cmp_lt_i32_e32 vcc, v6, v7
	global_store_dword v[98:99], v1, off offset:384 sc1
	global_store_dword v[100:101], v0, off offset:384 sc1
	v_cndmask_b32_e32 v6, v165, v6, vcc
	v_lshlrev_b32_e32 v6, 2, v6
	s_waitcnt lgkmcnt(0)
	v_add_f32_e32 v8, v8, v9
	ds_bpermute_b32 v9, v6, v8
	v_cmp_lt_i32_e32 vcc, v12, v7
	s_waitcnt lgkmcnt(0)
	v_add_f32_e32 v8, v8, v9
	v_cndmask_b32_e32 v7, v165, v12, vcc
	v_lshlrev_b32_e32 v7, 2, v7
	ds_bpermute_b32 v9, v7, v8
	v_mul_f32_e32 v12, v32, v0
	v_cvt_pk_bf16_f32 v12, v12, s0
	global_store_short v[10:11], v12, off sc1
	s_and_saveexec_b64 s[60:61], s[0:1]
	s_cbranch_execz .LBB0_1400
	s_waitcnt lgkmcnt(0)
	v_add_f32_e32 v10, v8, v9
	v_lshl_add_u64 v[8:9], v[70:71], 2, s[58:59]
	global_store_dword v[8:9], v10, off sc1

.LBB0_1569:
	s_add_i32 s58, s66, 0xffffe000
	s_lshr_b32 s58, s58, 12
	s_mulk_i32 s58, 0x1800
	v_mov_b32_e32 v70, s70
	s_add_i32 s58, s58, 0xf000
	ds_read_b64 v[70:71], v70
	s_cmp_gt_i32 s6, 63
	s_cselect_b32 s6, s58, 0xd800
	s_lshl_b64 s[58:59], s[6:7], 2
	s_add_u32 s6, s14, s58
	s_addc_u32 s65, s15, s59
	s_waitcnt lgkmcnt(0)
	v_readfirstlane_b32 s58, v70
	v_readfirstlane_b32 s59, v71
	s_add_u32 s60, s58, 0x3000
	s_addc_u32 s61, s59, 0
	s_lshl_b32 s58, s64, 14
	s_add_i32 s58, s58, 0xe0000
	s_ashr_i32 s59, s58, 31
	s_lshl_b64 s[58:59], s[58:59], 2
	s_add_u32 s58, s10, s58
	s_addc_u32 s59, s11, s59
	s_add_u32 s62, s6, 0x5ba2000
	v_or_b32_e32 v102, s68, v138
	v_add_u32_e32 v70, s66, v139
	s_addc_u32 s63, s65, 0
	v_lshlrev_b32_e32 v188, 10, v70
	v_ashrrev_i32_e32 v103, 31, v102
	s_add_u32 s64, s6, 0x5ba4000
	v_lshlrev_b64 v[72:73], 2, v[102:103]
	v_or_b32_e32 v186, 0x400, v188
	v_or_b32_e32 v185, 0x4400, v188
	v_or_b32_e32 v189, 0x4c00, v188
	v_or_b32_e32 v193, 0x6c00, v188
	s_addc_u32 s65, s65, 0
	v_lshl_add_u64 v[74:75], s[62:63], 0, v[72:73]
	v_add_u32_e32 v132, v188, v102
	v_add_u32_e32 v134, v186, v102
	v_or_b32_e32 v184, 0x800, v188
	v_or_b32_e32 v183, 0xc00, v188
	v_or_b32_e32 v181, 0x2000, v188
	v_or_b32_e32 v179, 0x2400, v188
	v_or_b32_e32 v71, 0x2800, v188
	v_or_b32_e32 v180, 0x2c00, v188
	v_or_b32_e32 v182, 0x4000, v188
	v_add_u32_e32 v112, v185, v102
	v_or_b32_e32 v187, 0x4800, v188
	v_add_u32_e32 v118, v189, v102
	v_or_b32_e32 v190, 0x6000, v188
	v_or_b32_e32 v191, 0x6400, v188
	v_or_b32_e32 v192, 0x6800, v188
	v_add_u32_e32 v128, v193, v102
	global_load_dword v194, v[74:75], off
	v_lshl_add_u64 v[74:75], s[60:61], 0, v[72:73]
	v_lshl_add_u64 v[72:73], s[64:65], 0, v[72:73]
	v_ashrrev_i32_e32 v135, 31, v134
	v_add_u32_e32 v136, v184, v102
	v_add_u32_e32 v130, v183, v102
	v_add_u32_e32 v122, v181, v102
	v_add_u32_e32 v114, v179, v102
	v_add_u32_e32 v106, v71, v102
	v_add_u32_e32 v108, v180, v102
	v_add_u32_e32 v110, v182, v102
	v_ashrrev_i32_e32 v113, 31, v112
	v_add_u32_e32 v116, v187, v102
	v_ashrrev_i32_e32 v119, 31, v118
	v_add_u32_e32 v120, v190, v102
	v_add_u32_e32 v124, v191, v102
	v_add_u32_e32 v126, v192, v102
	v_ashrrev_i32_e32 v129, 31, v128
	v_ashrrev_i32_e32 v133, 31, v132
	global_load_dword v196, v[72:73], off
	v_lshl_add_u64 v[88:89], v[134:135], 2, s[12:13]
	v_ashrrev_i32_e32 v137, 31, v136
	v_ashrrev_i32_e32 v131, 31, v130
	v_ashrrev_i32_e32 v123, 31, v122
	v_ashrrev_i32_e32 v115, 31, v114
	v_ashrrev_i32_e32 v107, 31, v106
	v_ashrrev_i32_e32 v109, 31, v108
	v_ashrrev_i32_e32 v111, 31, v110
	v_lshl_add_u64 v[86:87], v[112:113], 2, s[12:13]
	v_ashrrev_i32_e32 v117, 31, v116
	v_lshl_add_u64 v[92:93], v[118:119], 2, s[12:13]
	v_ashrrev_i32_e32 v121, 31, v120
	v_ashrrev_i32_e32 v125, 31, v124
	v_ashrrev_i32_e32 v127, 31, v126
	v_lshl_add_u64 v[100:101], v[128:129], 2, s[12:13]
	v_lshl_add_u64 v[104:105], v[132:133], 2, s[12:13]
	global_load_dword v195, v[74:75], off
	v_lshl_add_u64 v[84:85], v[136:137], 2, s[12:13]
	v_lshl_add_u64 v[82:83], v[130:131], 2, s[12:13]
	v_lshl_add_u64 v[78:79], v[122:123], 2, s[12:13]
	v_lshl_add_u64 v[72:73], v[114:115], 2, s[12:13]
	v_lshl_add_u64 v[74:75], v[106:107], 2, s[12:13]
	v_lshl_add_u64 v[76:77], v[108:109], 2, s[12:13]
	v_lshl_add_u64 v[80:81], v[110:111], 2, s[12:13]
	global_load_dword v178, v[88:89], off
	global_load_dword v177, v[84:85], off
	global_load_dword v176, v[82:83], off
	global_load_dword v175, v[78:79], off
	global_load_dword v174, v[72:73], off
	global_load_dword v173, v[74:75], off
	global_load_dword v172, v[76:77], off
	global_load_dword v171, v[80:81], off
	v_lshl_add_u64 v[90:91], v[116:117], 2, s[12:13]
	global_load_dword v170, v[86:87], off
	global_load_dword v168, v[90:91], off
	v_lshl_add_u64 v[94:95], v[120:121], 2, s[12:13]
	v_lshl_add_u64 v[96:97], v[124:125], 2, s[12:13]
	v_lshl_add_u64 v[98:99], v[126:127], 2, s[12:13]
	global_load_dword v169, v[92:93], off
	global_load_dword v167, v[94:95], off
	global_load_dword v166, v[96:97], off
	global_load_dword v165, v[98:99], off
	global_load_dword v103, v[100:101], off
	global_load_dword v197, v[104:105], off
	v_lshl_add_u64 v[106:107], v[106:107], 1, s[8:9]
	global_load_dword v255, v[88:89], off offset:128
	global_load_dword v255, v[88:89], off offset:256
	global_load_dword v255, v[88:89], off offset:384
	global_load_dword v255, v[84:85], off offset:128
	global_load_dword v255, v[84:85], off offset:256
	global_load_dword v255, v[84:85], off offset:384
	global_load_dword v255, v[82:83], off offset:128
	global_load_dword v255, v[82:83], off offset:256
	global_load_dword v255, v[82:83], off offset:384
	global_load_dword v255, v[78:79], off offset:128
	global_load_dword v255, v[78:79], off offset:256
	global_load_dword v255, v[78:79], off offset:384
	global_load_dword v255, v[72:73], off offset:128
	global_load_dword v255, v[72:73], off offset:256
	global_load_dword v255, v[72:73], off offset:384
	global_load_dword v255, v[74:75], off offset:128
	global_load_dword v255, v[74:75], off offset:256
	global_load_dword v255, v[74:75], off offset:384
	global_load_dword v255, v[76:77], off offset:128
	global_load_dword v255, v[76:77], off offset:256
	global_load_dword v255, v[76:77], off offset:384
	global_load_dword v255, v[80:81], off offset:128
	global_load_dword v255, v[80:81], off offset:256
	global_load_dword v255, v[80:81], off offset:384
	global_load_dword v255, v[86:87], off offset:128
	global_load_dword v255, v[86:87], off offset:256
	global_load_dword v255, v[86:87], off offset:384
	global_load_dword v255, v[90:91], off offset:128
	global_load_dword v255, v[90:91], off offset:256
	global_load_dword v255, v[90:91], off offset:384
	global_load_dword v255, v[92:93], off offset:128
	global_load_dword v255, v[92:93], off offset:256
	global_load_dword v255, v[92:93], off offset:384
	global_load_dword v255, v[94:95], off offset:128
	global_load_dword v255, v[94:95], off offset:256
	global_load_dword v255, v[94:95], off offset:384
	global_load_dword v255, v[96:97], off offset:128
	global_load_dword v255, v[96:97], off offset:256
	global_load_dword v255, v[96:97], off offset:384
	global_load_dword v255, v[98:99], off offset:128
	global_load_dword v255, v[98:99], off offset:256
	global_load_dword v255, v[98:99], off offset:384
	global_load_dword v255, v[100:101], off offset:128
	global_load_dword v255, v[100:101], off offset:256
	global_load_dword v255, v[100:101], off offset:384
	global_load_dword v255, v[104:105], off offset:128
	global_load_dword v255, v[104:105], off offset:256
	global_load_dword v255, v[104:105], off offset:384
	s_waitcnt vmcnt(0)
	v_add_f32_e32 v196, 1.0, v196
	v_mul_f32_e32 v195, v195, v196
	v_fmac_f32_e32 v178, v49, v194
	v_fmac_f32_e32 v177, v50, v194
	v_fmac_f32_e32 v176, v51, v194
	v_fmac_f32_e32 v175, v52, v194
	v_fmac_f32_e32 v174, v53, v194
	v_fmac_f32_e32 v173, v54, v194
	v_fmac_f32_e32 v172, v55, v194
	v_fmac_f32_e32 v171, v56, v194
	v_fmac_f32_e32 v170, v57, v194
	v_fmac_f32_e32 v168, v58, v194
	v_fmac_f32_e32 v169, v59, v194
	v_fmac_f32_e32 v167, v60, v194
	v_fmac_f32_e32 v166, v61, v194
	v_fmac_f32_e32 v165, v62, v194
	v_fmac_f32_e32 v103, v63, v194
	v_fmac_f32_e32 v197, v48, v194
	v_mul_f32_e32 v48, v195, v197
	v_cvt_pk_bf16_f32 v58, v48, s0
	v_or_b32_e32 v48, 32, v102
	v_ashrrev_i32_e32 v49, 31, v48
	v_lshlrev_b64 v[52:53], 2, v[48:49]
	global_store_dword v[88:89], v178, off sc1
	global_store_dword v[84:85], v177, off sc1
	global_store_dword v[82:83], v176, off sc1
	global_store_dword v[78:79], v175, off sc1
	global_store_dword v[72:73], v174, off sc1
	global_store_dword v[74:75], v173, off sc1
	global_store_dword v[76:77], v172, off sc1
	global_store_dword v[80:81], v171, off sc1
	global_store_dword v[86:87], v170, off sc1
	global_store_dword v[90:91], v168, off sc1
	global_store_dword v[92:93], v169, off sc1
	global_store_dword v[94:95], v167, off sc1
	global_store_dword v[96:97], v166, off sc1
	global_store_dword v[98:99], v165, off sc1
	global_store_dword v[100:101], v103, off sc1
	global_store_dword v[104:105], v197, off sc1
	v_lshl_add_u64 v[50:51], v[132:133], 1, s[8:9]
	v_lshl_add_u64 v[56:57], s[64:65], 0, v[52:53]
	global_load_dword v196, v[104:105], off offset:128
	v_lshl_add_u64 v[54:55], s[60:61], 0, v[52:53]
	global_load_dword v132, v[56:57], off
	global_load_dword v133, v[54:55], off
	v_mul_f32_e32 v49, v195, v178
	global_store_short v[50:51], v58, off sc1
	v_lshl_add_u64 v[50:51], s[62:63], 0, v[52:53]
	global_load_dword v194, v[50:51], off
	v_cvt_pk_bf16_f32 v49, v49, s0
	v_lshl_add_u64 v[50:51], v[134:135], 1, s[8:9]
	global_store_short v[50:51], v49, off sc1
	v_mul_f32_e32 v49, v195, v177
	v_cvt_pk_bf16_f32 v49, v49, s0
	v_lshl_add_u64 v[50:51], v[136:137], 1, s[8:9]
	global_store_short v[50:51], v49, off sc1
	v_mul_f32_e32 v49, v195, v176
	v_cvt_pk_bf16_f32 v49, v49, s0
	v_lshl_add_u64 v[50:51], v[130:131], 1, s[8:9]
	global_store_short v[50:51], v49, off sc1
	v_mul_f32_e32 v49, v195, v175
	v_cvt_pk_bf16_f32 v49, v49, s0
	v_lshl_add_u64 v[50:51], v[122:123], 1, s[8:9]
	global_store_short v[50:51], v49, off sc1
	v_mul_f32_e32 v49, v195, v174
	v_cvt_pk_bf16_f32 v49, v49, s0
	v_lshl_add_u64 v[50:51], v[114:115], 1, s[8:9]
	global_store_short v[50:51], v49, off sc1
	v_mul_f32_e32 v49, v195, v173
	global_load_dword v62, v[84:85], off offset:128
	global_load_dword v60, v[78:79], off offset:128
	global_load_dword v59, v[72:73], off offset:128
	global_load_dword v58, v[74:75], off offset:128
	global_load_dword v56, v[80:81], off offset:128
	global_load_dword v57, v[76:77], off offset:128
	global_load_dword v55, v[86:87], off offset:128
	global_load_dword v61, v[82:83], off offset:128
	global_load_dword v54, v[90:91], off offset:128
	global_load_dword v53, v[92:93], off offset:128
	global_load_dword v52, v[94:95], off offset:128
	global_load_dword v51, v[96:97], off offset:128
	global_load_dword v50, v[98:99], off offset:128
	v_cvt_pk_bf16_f32 v63, v49, s0
	global_load_dword v49, v[100:101], off offset:128
	s_waitcnt vmcnt(19)
	v_fmac_f32_e32 v196, v32, v194
	global_store_short v[106:107], v63, off sc1
	global_load_dword v63, v[88:89], off offset:128
	v_mul_f32_e32 v106, v195, v172
	v_cvt_pk_bf16_f32 v114, v106, s0
	v_lshl_add_u64 v[106:107], v[108:109], 1, s[8:9]
	global_store_short v[106:107], v114, off sc1
	v_mul_f32_e32 v106, v195, v171
	v_cvt_pk_bf16_f32 v108, v106, s0
	v_lshl_add_u64 v[106:107], v[110:111], 1, s[8:9]
	global_store_short v[106:107], v108, off sc1
	v_mul_f32_e32 v106, v195, v170
	v_cvt_pk_bf16_f32 v108, v106, s0
	v_lshl_add_u64 v[106:107], v[112:113], 1, s[8:9]
	global_store_short v[106:107], v108, off sc1
	v_mul_f32_e32 v106, v195, v168
	v_cvt_pk_bf16_f32 v108, v106, s0
	v_lshl_add_u64 v[106:107], v[116:117], 1, s[8:9]
	global_store_short v[106:107], v108, off sc1
	v_mul_f32_e32 v106, v195, v169
	v_cvt_pk_bf16_f32 v108, v106, s0
	v_lshl_add_u64 v[106:107], v[118:119], 1, s[8:9]
	global_store_short v[106:107], v108, off sc1
	v_mul_f32_e32 v106, v195, v167
	v_cvt_pk_bf16_f32 v108, v106, s0
	v_lshl_add_u64 v[106:107], v[120:121], 1, s[8:9]
	global_store_short v[106:107], v108, off sc1
	v_mul_f32_e32 v106, v195, v166
	v_cvt_pk_bf16_f32 v108, v106, s0
	v_lshl_add_u64 v[106:107], v[124:125], 1, s[8:9]
	global_store_short v[106:107], v108, off sc1
	v_mul_f32_e32 v106, v195, v165
	v_cvt_pk_bf16_f32 v108, v106, s0
	v_lshl_add_u64 v[106:107], v[126:127], 1, s[8:9]
	global_store_short v[106:107], v108, off sc1
	v_mul_f32_e32 v106, v195, v103
	v_cvt_pk_bf16_f32 v108, v106, s0
	v_lshl_add_u64 v[106:107], v[128:129], 1, s[8:9]
	global_store_short v[106:107], v108, off sc1
	v_add_f32_e32 v106, 1.0, v132
	v_mul_f32_e32 v110, v133, v106
	v_add_u32_e32 v106, v188, v48
	s_waitcnt vmcnt(24)
	v_fmac_f32_e32 v62, v34, v194
	s_waitcnt vmcnt(17)
	v_fmac_f32_e32 v61, v35, v194
	v_fmac_f32_e32 v60, v36, v194
	v_fmac_f32_e32 v59, v37, v194
	v_fmac_f32_e32 v58, v38, v194
	v_fmac_f32_e32 v57, v39, v194
	v_fmac_f32_e32 v56, v40, v194
	v_fmac_f32_e32 v55, v41, v194
	s_waitcnt vmcnt(16)
	v_fmac_f32_e32 v54, v42, v194
	s_waitcnt vmcnt(15)
	v_fmac_f32_e32 v53, v43, v194
	s_waitcnt vmcnt(14)
	v_fmac_f32_e32 v52, v44, v194
	s_waitcnt vmcnt(13)
	v_fmac_f32_e32 v51, v45, v194
	s_waitcnt vmcnt(12)
	v_fmac_f32_e32 v50, v46, v194
	s_waitcnt vmcnt(11)
	v_fmac_f32_e32 v49, v47, v194
	v_ashrrev_i32_e32 v107, 31, v106
	global_store_dword v[104:105], v196, off offset:128 sc1
	v_mul_f32_e32 v32, v110, v196
	global_store_dword v[84:85], v62, off offset:128 sc1
	global_store_dword v[82:83], v61, off offset:128 sc1
	global_store_dword v[78:79], v60, off offset:128 sc1
	global_store_dword v[72:73], v59, off offset:128 sc1
	global_store_dword v[74:75], v58, off offset:128 sc1
	global_store_dword v[76:77], v57, off offset:128 sc1
	global_store_dword v[80:81], v56, off offset:128 sc1
	global_store_dword v[86:87], v55, off offset:128 sc1
	global_store_dword v[90:91], v54, off offset:128 sc1
	global_store_dword v[92:93], v53, off offset:128 sc1
	global_store_dword v[94:95], v52, off offset:128 sc1
	global_store_dword v[96:97], v51, off offset:128 sc1
	global_store_dword v[98:99], v50, off offset:128 sc1
	global_store_dword v[100:101], v49, off offset:128 sc1
	v_cvt_pk_bf16_f32 v32, v32, s0
	v_lshl_add_u64 v[106:107], v[106:107], 1, s[8:9]
	v_add_u32_e32 v108, v186, v48
	global_load_dword v45, v[88:89], off offset:256
	v_ashrrev_i32_e32 v109, 31, v108
	global_store_short v[106:107], v32, off sc1
	v_mul_f32_e32 v113, v110, v56
	v_cvt_pk_bf16_f32 v113, v113, s0
	v_mul_f32_e32 v106, v196, v196
	s_waitcnt vmcnt(26)
	v_fmac_f32_e32 v63, v33, v194
	v_mul_f32_e32 v32, v110, v63
	v_cvt_pk_bf16_f32 v34, v32, s0
	v_lshl_add_u64 v[32:33], v[108:109], 1, s[8:9]
	global_store_short v[32:33], v34, off sc1
	v_add_u32_e32 v32, v184, v48
	v_ashrrev_i32_e32 v33, 31, v32
	v_mul_f32_e32 v34, v110, v62
	v_cvt_pk_bf16_f32 v34, v34, s0
	v_lshl_add_u64 v[32:33], v[32:33], 1, s[8:9]
	global_store_short v[32:33], v34, off sc1
	v_add_u32_e32 v32, v183, v48
	v_ashrrev_i32_e32 v33, 31, v32
	v_mul_f32_e32 v34, v110, v61
	v_cvt_pk_bf16_f32 v34, v34, s0
	v_lshl_add_u64 v[32:33], v[32:33], 1, s[8:9]
	global_store_short v[32:33], v34, off sc1
	v_add_u32_e32 v32, v181, v48
	v_ashrrev_i32_e32 v33, 31, v32
	v_mul_f32_e32 v34, v110, v60
	v_cvt_pk_bf16_f32 v34, v34, s0
	v_lshl_add_u64 v[32:33], v[32:33], 1, s[8:9]
	global_store_short v[32:33], v34, off sc1
	v_add_u32_e32 v32, v179, v48
	v_ashrrev_i32_e32 v33, 31, v32
	v_mul_f32_e32 v34, v110, v59
	v_cvt_pk_bf16_f32 v42, v34, s0
	v_lshl_add_u64 v[34:35], v[32:33], 1, s[8:9]
	v_or_b32_e32 v32, 64, v102
	v_ashrrev_i32_e32 v33, 31, v32
	v_lshlrev_b64 v[36:37], 2, v[32:33]
	global_store_dword v[88:89], v63, off offset:128 sc1
	v_lshl_add_u64 v[40:41], s[64:65], 0, v[36:37]
	v_lshl_add_u64 v[38:39], s[60:61], 0, v[36:37]
	global_load_dword v107, v[40:41], off
	global_load_dword v111, v[38:39], off
	v_mul_f32_e32 v33, v110, v58
	global_store_short v[34:35], v42, off sc1
	v_lshl_add_u64 v[34:35], s[62:63], 0, v[36:37]
	global_load_dword v112, v[34:35], off
	v_add_u32_e32 v34, v71, v48
	v_ashrrev_i32_e32 v35, 31, v34
	v_cvt_pk_bf16_f32 v33, v33, s0
	v_lshl_add_u64 v[34:35], v[34:35], 1, s[8:9]
	global_store_short v[34:35], v33, off sc1
	v_add_u32_e32 v34, v180, v48
	v_ashrrev_i32_e32 v35, 31, v34
	v_mul_f32_e32 v33, v110, v57
	v_cvt_pk_bf16_f32 v33, v33, s0
	v_lshl_add_u64 v[34:35], v[34:35], 1, s[8:9]
	global_load_dword v38, v[90:91], off offset:256
	global_load_dword v37, v[92:93], off offset:256
	global_load_dword v36, v[94:95], off offset:256
	global_load_dword v114, v[104:105], off offset:256
	global_load_dword v47, v[84:85], off offset:256
	global_load_dword v39, v[86:87], off offset:256
	global_load_dword v46, v[82:83], off offset:256
	global_load_dword v44, v[78:79], off offset:256
	global_load_dword v43, v[72:73], off offset:256
	global_load_dword v42, v[74:75], off offset:256
	global_load_dword v40, v[80:81], off offset:256
	global_load_dword v41, v[76:77], off offset:256
	v_add_u32_e32 v108, v182, v48
	global_store_short v[34:35], v33, off sc1
	global_load_dword v35, v[96:97], off offset:256
	v_ashrrev_i32_e32 v109, 31, v108
	global_load_dword v34, v[98:99], off offset:256
	global_load_dword v33, v[100:101], off offset:256
	v_lshl_add_u64 v[108:109], v[108:109], 1, s[8:9]
	global_store_short v[108:109], v113, off sc1
	v_add_u32_e32 v108, v185, v48
	v_ashrrev_i32_e32 v109, 31, v108
	v_mul_f32_e32 v113, v110, v55
	v_cvt_pk_bf16_f32 v113, v113, s0
	v_lshl_add_u64 v[108:109], v[108:109], 1, s[8:9]
	global_store_short v[108:109], v113, off sc1
	v_add_u32_e32 v108, v187, v48
	v_ashrrev_i32_e32 v109, 31, v108
	v_mul_f32_e32 v113, v110, v54
	v_cvt_pk_bf16_f32 v113, v113, s0
	v_lshl_add_u64 v[108:109], v[108:109], 1, s[8:9]
	global_store_short v[108:109], v113, off sc1
	v_add_u32_e32 v108, v189, v48
	v_ashrrev_i32_e32 v109, 31, v108
	v_mul_f32_e32 v113, v110, v53
	v_cvt_pk_bf16_f32 v113, v113, s0
	v_lshl_add_u64 v[108:109], v[108:109], 1, s[8:9]
	global_store_short v[108:109], v113, off sc1
	v_add_u32_e32 v108, v190, v48
	v_ashrrev_i32_e32 v109, 31, v108
	v_mul_f32_e32 v113, v110, v52
	v_cvt_pk_bf16_f32 v113, v113, s0
	v_lshl_add_u64 v[108:109], v[108:109], 1, s[8:9]
	global_store_short v[108:109], v113, off sc1
	v_add_u32_e32 v108, v191, v48
	v_ashrrev_i32_e32 v109, 31, v108
	v_mul_f32_e32 v113, v110, v51
	v_cvt_pk_bf16_f32 v113, v113, s0
	v_lshl_add_u64 v[108:109], v[108:109], 1, s[8:9]
	global_store_short v[108:109], v113, off sc1
	v_add_u32_e32 v108, v192, v48
	v_ashrrev_i32_e32 v109, 31, v108
	v_mul_f32_e32 v113, v110, v50
	v_cvt_pk_bf16_f32 v113, v113, s0
	v_lshl_add_u64 v[108:109], v[108:109], 1, s[8:9]
	global_store_short v[108:109], v113, off sc1
	v_add_u32_e32 v108, v193, v48
	v_ashrrev_i32_e32 v109, 31, v108
	v_mul_f32_e32 v48, v110, v49
	v_cvt_pk_bf16_f32 v48, v48, s0
	v_lshl_add_u64 v[108:109], v[108:109], 1, s[8:9]
	global_store_short v[108:109], v48, off sc1
	v_add_u32_e32 v108, v188, v32
	v_ashrrev_i32_e32 v109, 31, v108
	s_waitcnt vmcnt(28)
	v_add_f32_e32 v48, 1.0, v107
	s_waitcnt vmcnt(27)
	v_mul_f32_e32 v48, v111, v48
	v_fmac_f32_e32 v106, v197, v197
	s_waitcnt vmcnt(25)
	v_fmac_f32_e32 v45, v17, v112
	global_store_dword v[88:89], v45, off offset:256 sc1
	s_waitcnt vmcnt(24)
	v_fmac_f32_e32 v38, v26, v112
	s_waitcnt vmcnt(23)
	v_fmac_f32_e32 v37, v27, v112
	s_waitcnt vmcnt(22)
	v_fmac_f32_e32 v36, v28, v112
	s_waitcnt vmcnt(21)
	v_fmac_f32_e32 v114, v16, v112
	v_mul_f32_e32 v16, v48, v114
	s_waitcnt vmcnt(20)
	v_fmac_f32_e32 v47, v18, v112
	v_cvt_pk_bf16_f32 v18, v16, s0
	v_lshl_add_u64 v[16:17], v[108:109], 1, s[8:9]
	global_store_short v[16:17], v18, off sc1
	v_add_u32_e32 v16, v186, v32
	v_ashrrev_i32_e32 v17, 31, v16
	v_mul_f32_e32 v18, v48, v45
	v_cvt_pk_bf16_f32 v18, v18, s0
	v_lshl_add_u64 v[16:17], v[16:17], 1, s[8:9]
	global_store_short v[16:17], v18, off sc1
	v_add_u32_e32 v16, v184, v32
	v_ashrrev_i32_e32 v17, 31, v16
	v_mul_f32_e32 v18, v48, v47
	v_cvt_pk_bf16_f32 v18, v18, s0
	v_lshl_add_u64 v[16:17], v[16:17], 1, s[8:9]
	s_waitcnt vmcnt(20)
	v_fmac_f32_e32 v46, v19, v112
	global_store_short v[16:17], v18, off sc1
	v_add_u32_e32 v16, v183, v32
	v_ashrrev_i32_e32 v17, 31, v16
	v_mul_f32_e32 v18, v48, v46
	s_waitcnt vmcnt(20)
	v_fmac_f32_e32 v44, v20, v112
	v_cvt_pk_bf16_f32 v18, v18, s0
	v_lshl_add_u64 v[16:17], v[16:17], 1, s[8:9]
	global_store_short v[16:17], v18, off sc1
	v_mul_f32_e32 v16, v48, v44
	v_cvt_pk_bf16_f32 v26, v16, s0
	v_or_b32_e32 v16, 0x60, v102
	v_add_u32_e32 v18, v181, v32
	v_ashrrev_i32_e32 v17, 31, v16
	s_waitcnt vmcnt(20)
	v_fmac_f32_e32 v43, v21, v112
	s_waitcnt vmcnt(19)
	v_fmac_f32_e32 v42, v22, v112
	s_waitcnt vmcnt(17)
	v_fmac_f32_e32 v41, v23, v112
	v_fmac_f32_e32 v40, v24, v112
	v_fmac_f32_e32 v39, v25, v112
	s_waitcnt vmcnt(15)
	v_fmac_f32_e32 v35, v29, v112
	s_waitcnt vmcnt(14)
	v_fmac_f32_e32 v34, v30, v112
	s_waitcnt vmcnt(13)
	v_fmac_f32_e32 v33, v31, v112
	v_ashrrev_i32_e32 v19, 31, v18
	v_lshlrev_b64 v[20:21], 2, v[16:17]
	global_store_dword v[84:85], v47, off offset:256 sc1
	global_store_dword v[82:83], v46, off offset:256 sc1
	global_store_dword v[78:79], v44, off offset:256 sc1
	global_store_dword v[72:73], v43, off offset:256 sc1
	global_store_dword v[74:75], v42, off offset:256 sc1
	global_store_dword v[76:77], v41, off offset:256 sc1
	global_store_dword v[80:81], v40, off offset:256 sc1
	global_store_dword v[86:87], v39, off offset:256 sc1
	global_store_dword v[90:91], v38, off offset:256 sc1
	global_store_dword v[92:93], v37, off offset:256 sc1
	global_store_dword v[94:95], v36, off offset:256 sc1
	global_store_dword v[96:97], v35, off offset:256 sc1
	global_store_dword v[98:99], v34, off offset:256 sc1
	global_store_dword v[100:101], v33, off offset:256 sc1
	global_store_dword v[104:105], v114, off offset:256 sc1
	v_lshl_add_u64 v[24:25], s[64:65], 0, v[20:21]
	v_lshl_add_u64 v[18:19], v[18:19], 1, s[8:9]
	global_load_dword v29, v[104:105], off offset:384
	v_lshl_add_u64 v[22:23], s[60:61], 0, v[20:21]
	global_load_dword v17, v[24:25], off
	global_load_dword v30, v[22:23], off
	global_load_dword v28, v[88:89], off offset:384
	global_load_dword v27, v[84:85], off offset:384
	v_fmac_f32_e32 v106, v114, v114
	global_store_short v[18:19], v26, off sc1
	v_lshl_add_u64 v[18:19], s[62:63], 0, v[20:21]
	global_load_dword v102, v[18:19], off
	v_add_u32_e32 v18, v179, v32
	v_ashrrev_i32_e32 v19, 31, v18
	v_mul_f32_e32 v20, v48, v43
	v_cvt_pk_bf16_f32 v20, v20, s0
	v_lshl_add_u64 v[18:19], v[18:19], 1, s[8:9]
	global_store_short v[18:19], v20, off sc1
	v_add_u32_e32 v18, v71, v32
	v_ashrrev_i32_e32 v19, 31, v18
	v_mul_f32_e32 v20, v48, v42
	v_cvt_pk_bf16_f32 v20, v20, s0
	v_lshl_add_u64 v[18:19], v[18:19], 1, s[8:9]
	global_store_short v[18:19], v20, off sc1
	v_add_u32_e32 v18, v180, v32
	v_ashrrev_i32_e32 v19, 31, v18
	v_mul_f32_e32 v20, v48, v41
	v_cvt_pk_bf16_f32 v20, v20, s0
	v_lshl_add_u64 v[18:19], v[18:19], 1, s[8:9]
	global_store_short v[18:19], v20, off sc1
	v_add_u32_e32 v18, v182, v32
	v_ashrrev_i32_e32 v19, 31, v18
	v_mul_f32_e32 v20, v48, v40
	v_cvt_pk_bf16_f32 v20, v20, s0
	v_lshl_add_u64 v[18:19], v[18:19], 1, s[8:9]
	global_store_short v[18:19], v20, off sc1
	v_add_u32_e32 v18, v185, v32
	v_ashrrev_i32_e32 v19, 31, v18
	v_mul_f32_e32 v20, v48, v39
	v_cvt_pk_bf16_f32 v20, v20, s0
	v_lshl_add_u64 v[18:19], v[18:19], 1, s[8:9]
	global_store_short v[18:19], v20, off sc1
	v_add_u32_e32 v18, v187, v32
	v_ashrrev_i32_e32 v19, 31, v18
	v_mul_f32_e32 v20, v48, v38
	v_cvt_pk_bf16_f32 v20, v20, s0
	v_lshl_add_u64 v[18:19], v[18:19], 1, s[8:9]
	global_store_short v[18:19], v20, off sc1
	v_add_u32_e32 v18, v189, v32
	v_ashrrev_i32_e32 v19, 31, v18
	v_mul_f32_e32 v20, v48, v37
	v_cvt_pk_bf16_f32 v20, v20, s0
	v_lshl_add_u64 v[18:19], v[18:19], 1, s[8:9]
	global_store_short v[18:19], v20, off sc1
	v_add_u32_e32 v18, v190, v32
	v_ashrrev_i32_e32 v19, 31, v18
	v_mul_f32_e32 v20, v48, v36
	v_cvt_pk_bf16_f32 v20, v20, s0
	v_lshl_add_u64 v[18:19], v[18:19], 1, s[8:9]
	global_store_short v[18:19], v20, off sc1
	v_add_u32_e32 v18, v191, v32
	v_ashrrev_i32_e32 v19, 31, v18
	v_mul_f32_e32 v20, v48, v35
	v_cvt_pk_bf16_f32 v20, v20, s0
	v_lshl_add_u64 v[18:19], v[18:19], 1, s[8:9]
	global_store_short v[18:19], v20, off sc1
	v_add_u32_e32 v18, v192, v32
	v_ashrrev_i32_e32 v19, 31, v18
	v_mul_f32_e32 v20, v48, v34
	v_cvt_pk_bf16_f32 v20, v20, s0
	v_lshl_add_u64 v[18:19], v[18:19], 1, s[8:9]
	global_store_short v[18:19], v20, off sc1
	v_add_u32_e32 v18, v193, v32
	v_ashrrev_i32_e32 v19, 31, v18
	v_mul_f32_e32 v20, v48, v33
	v_cvt_pk_bf16_f32 v20, v20, s0
	v_lshl_add_u64 v[18:19], v[18:19], 1, s[8:9]
	global_store_short v[18:19], v20, off sc1
	global_load_dword v20, v[86:87], off offset:384
	v_add_u32_e32 v18, v188, v16
	global_load_dword v26, v[82:83], off offset:384
	global_load_dword v25, v[78:79], off offset:384
	global_load_dword v24, v[72:73], off offset:384
	global_load_dword v23, v[74:75], off offset:384
	global_load_dword v21, v[80:81], off offset:384
	global_load_dword v22, v[76:77], off offset:384
	s_waitcnt vmcnt(23)
	v_add_f32_e32 v17, 1.0, v17
	s_waitcnt vmcnt(22)
	v_mul_f32_e32 v32, v30, v17
	v_ashrrev_i32_e32 v19, 31, v18
	v_lshl_add_u64 v[18:19], v[18:19], 1, s[8:9]
	v_add_u32_e32 v30, v186, v16
	s_waitcnt vmcnt(18)
	v_fmac_f32_e32 v29, v0, v102
	v_mul_f32_e32 v0, v32, v29
	v_cvt_pk_bf16_f32 v0, v0, s0
	global_store_short v[18:19], v0, off sc1
	global_load_dword v19, v[90:91], off offset:384
	v_ashrrev_i32_e32 v31, 31, v30
	global_load_dword v18, v[92:93], off offset:384
	v_fmac_f32_e32 v28, v1, v102
	v_mul_f32_e32 v0, v32, v28
	v_cvt_pk_bf16_f32 v17, v0, s0
	v_lshl_add_u64 v[0:1], v[30:31], 1, s[8:9]
	global_store_short v[0:1], v17, off sc1
	v_add_u32_e32 v0, v184, v16
	v_fmac_f32_e32 v27, v2, v102
	global_load_dword v17, v[94:95], off offset:384
	v_ashrrev_i32_e32 v1, 31, v0
	v_mul_f32_e32 v2, v32, v27
	v_cvt_pk_bf16_f32 v2, v2, s0
	v_lshl_add_u64 v[0:1], v[0:1], 1, s[8:9]
	global_store_short v[0:1], v2, off sc1
	v_add_u32_e32 v0, v183, v16
	global_load_dword v2, v[96:97], off offset:384
	v_ashrrev_i32_e32 v1, 31, v0
	v_lshl_add_u64 v[0:1], v[0:1], 1, s[8:9]
	v_add_u32_e32 v30, v181, v16
	v_ashrrev_i32_e32 v31, 31, v30
	v_lshl_add_u64 v[30:31], v[30:31], 1, s[8:9]
	v_fmac_f32_e32 v106, v29, v29
	global_store_dword v[104:105], v29, off offset:384 sc1
	global_store_dword v[88:89], v28, off offset:384 sc1
	global_store_dword v[84:85], v27, off offset:384 sc1
	s_waitcnt vmcnt(16)
	v_fmac_f32_e32 v20, v9, v102
	global_store_dword v[86:87], v20, off offset:384 sc1
	s_waitcnt vmcnt(16)
	v_fmac_f32_e32 v26, v3, v102
	v_mul_f32_e32 v3, v32, v26
	v_cvt_pk_bf16_f32 v3, v3, s0
	global_store_short v[0:1], v3, off sc1
	global_load_dword v1, v[98:99], off offset:384
	s_waitcnt vmcnt(17)
	v_fmac_f32_e32 v25, v4, v102
	v_mul_f32_e32 v0, v32, v25
	v_cvt_pk_bf16_f32 v0, v0, s0
	global_store_short v[30:31], v0, off sc1
	global_load_dword v0, v[100:101], off offset:384
	v_add_u32_e32 v30, v179, v16
	s_waitcnt vmcnt(18)
	v_fmac_f32_e32 v24, v5, v102
	v_ashrrev_i32_e32 v31, 31, v30
	v_mul_f32_e32 v3, v32, v24
	v_cvt_pk_bf16_f32 v3, v3, s0
	v_lshl_add_u64 v[4:5], v[30:31], 1, s[8:9]
	global_store_short v[4:5], v3, off sc1
	v_add_u32_e32 v4, v71, v16
	s_waitcnt vmcnt(18)
	v_fmac_f32_e32 v23, v6, v102
	v_ashrrev_i32_e32 v5, 31, v4
	v_mul_f32_e32 v3, v32, v23
	v_cvt_pk_bf16_f32 v3, v3, s0
	v_lshl_add_u64 v[4:5], v[4:5], 1, s[8:9]
	global_store_short v[4:5], v3, off sc1
	v_add_u32_e32 v4, v180, v16
	s_waitcnt vmcnt(17)
	v_fmac_f32_e32 v22, v7, v102
	v_ashrrev_i32_e32 v5, 31, v4
	v_mul_f32_e32 v3, v32, v22
	v_cvt_pk_bf16_f32 v3, v3, s0
	v_lshl_add_u64 v[4:5], v[4:5], 1, s[8:9]
	global_store_short v[4:5], v3, off sc1
	v_add_u32_e32 v4, v182, v16
	v_fmac_f32_e32 v21, v8, v102
	v_ashrrev_i32_e32 v5, 31, v4
	v_mul_f32_e32 v3, v32, v21
	v_cvt_pk_bf16_f32 v3, v3, s0
	v_lshl_add_u64 v[4:5], v[4:5], 1, s[8:9]
	global_store_short v[4:5], v3, off sc1
	v_add_u32_e32 v4, v185, v16
	v_ashrrev_i32_e32 v5, 31, v4
	v_mul_f32_e32 v3, v32, v20
	v_cvt_pk_bf16_f32 v3, v3, s0
	v_lshl_add_u64 v[4:5], v[4:5], 1, s[8:9]
	global_store_short v[4:5], v3, off sc1
	v_add_u32_e32 v4, v187, v16
	s_waitcnt vmcnt(18)
	v_fmac_f32_e32 v19, v10, v102
	v_ashrrev_i32_e32 v5, 31, v4
	v_mul_f32_e32 v3, v32, v19
	v_cvt_pk_bf16_f32 v3, v3, s0
	v_lshl_add_u64 v[4:5], v[4:5], 1, s[8:9]
	global_store_short v[4:5], v3, off sc1
	v_add_u32_e32 v4, v189, v16
	s_waitcnt vmcnt(18)
	v_fmac_f32_e32 v18, v11, v102
	v_ashrrev_i32_e32 v5, 31, v4
	v_mul_f32_e32 v3, v32, v18
	v_cvt_pk_bf16_f32 v3, v3, s0
	v_lshl_add_u64 v[4:5], v[4:5], 1, s[8:9]
	global_store_short v[4:5], v3, off sc1
	v_add_u32_e32 v4, v190, v16
	s_waitcnt vmcnt(17)
	v_fmac_f32_e32 v17, v12, v102
	v_ashrrev_i32_e32 v5, 31, v4
	v_mul_f32_e32 v3, v32, v17
	v_cvt_pk_bf16_f32 v3, v3, s0
	v_lshl_add_u64 v[4:5], v[4:5], 1, s[8:9]
	global_store_short v[4:5], v3, off sc1
	v_add_u32_e32 v4, v191, v16
	s_waitcnt vmcnt(16)
	v_fmac_f32_e32 v2, v13, v102
	v_ashrrev_i32_e32 v5, 31, v4
	v_mul_f32_e32 v3, v32, v2
	v_cvt_pk_bf16_f32 v3, v3, s0
	v_lshl_add_u64 v[4:5], v[4:5], 1, s[8:9]
	global_store_short v[4:5], v3, off sc1
	v_add_u32_e32 v4, v192, v16
	v_ashrrev_i32_e32 v5, 31, v4
	v_lshl_add_u64 v[4:5], v[4:5], 1, s[8:9]
	v_xor_b32_e32 v13, 16, v164
	v_add_u32_e32 v10, v193, v16
	v_ashrrev_i32_e32 v11, 31, v10
	v_lshl_add_u64 v[10:11], v[10:11], 1, s[8:9]
	v_ashrrev_i32_e32 v71, 31, v70
	global_store_dword v[82:83], v26, off offset:384 sc1
	global_store_dword v[78:79], v25, off offset:384 sc1
	global_store_dword v[72:73], v24, off offset:384 sc1
	global_store_dword v[74:75], v23, off offset:384 sc1
	s_waitcnt vmcnt(15)
	v_fmac_f32_e32 v1, v14, v102
	v_mul_f32_e32 v3, v32, v1
	v_cvt_pk_bf16_f32 v3, v3, s0
	global_store_short v[4:5], v3, off sc1
	v_and_b32_e32 v4, 64, v164
	v_xor_b32_e32 v3, 1, v164
	v_add_u32_e32 v7, 64, v4
	v_cmp_lt_i32_e32 vcc, v3, v7
	v_xor_b32_e32 v4, 2, v164
	s_waitcnt vmcnt(14)
	v_fmac_f32_e32 v0, v15, v102
	v_cndmask_b32_e32 v3, v164, v3, vcc
	v_lshlrev_b32_e32 v3, 2, v3
	ds_bpermute_b32 v5, v3, v106
	v_cmp_lt_i32_e32 vcc, v4, v7
	v_mul_f32_e32 v12, v32, v0
	v_cvt_pk_bf16_f32 v12, v12, s0
	v_cndmask_b32_e32 v4, v164, v4, vcc
	v_lshlrev_b32_e32 v4, 2, v4
	s_waitcnt lgkmcnt(0)
	v_add_f32_e32 v6, v106, v5
	ds_bpermute_b32 v8, v4, v6
	v_xor_b32_e32 v5, 4, v164
	v_cmp_lt_i32_e32 vcc, v5, v7
	global_store_dword v[76:77], v22, off offset:384 sc1
	global_store_dword v[80:81], v21, off offset:384 sc1
	v_cndmask_b32_e32 v5, v164, v5, vcc
	v_lshlrev_b32_e32 v5, 2, v5
	s_waitcnt lgkmcnt(0)
	v_add_f32_e32 v8, v6, v8
	ds_bpermute_b32 v9, v5, v8
	v_xor_b32_e32 v6, 8, v164
	v_cmp_lt_i32_e32 vcc, v6, v7
	global_store_dword v[90:91], v19, off offset:384 sc1
	global_store_dword v[92:93], v18, off offset:384 sc1
	v_cndmask_b32_e32 v6, v164, v6, vcc
	v_lshlrev_b32_e32 v6, 2, v6
	s_waitcnt lgkmcnt(0)
	v_add_f32_e32 v8, v8, v9
	ds_bpermute_b32 v9, v6, v8
	v_cmp_lt_i32_e32 vcc, v13, v7
	global_store_dword v[94:95], v17, off offset:384 sc1
	global_store_dword v[96:97], v2, off offset:384 sc1
	v_cndmask_b32_e32 v7, v164, v13, vcc
	v_lshlrev_b32_e32 v7, 2, v7
	s_waitcnt lgkmcnt(0)
	v_add_f32_e32 v8, v8, v9
	ds_bpermute_b32 v9, v7, v8
	global_store_dword v[98:99], v1, off offset:384 sc1
	global_store_dword v[100:101], v0, off offset:384 sc1
	global_store_short v[10:11], v12, off sc1
	s_and_saveexec_b64 s[60:61], s[0:1]
	s_cbranch_execz .LBB0_1571
	s_waitcnt lgkmcnt(0)
	v_add_f32_e32 v10, v8, v9
	v_lshl_add_u64 v[8:9], v[70:71], 2, s[58:59]
	global_store_dword v[8:9], v10, off sc1

.LBB0_1636:
	s_add_i32 s52, s11, 0xffffe000
	s_lshr_b32 s52, s52, 12
	s_mulk_i32 s52, 0x1800
	s_add_i32 s52, s52, 0xf000
	s_cmp_gt_i32 s2, 63
	s_cselect_b32 s2, s52, 0xd800
	s_lshl_b64 s[52:53], s[2:3], 2
	s_add_u32 s2, s14, s52
	s_addc_u32 s53, s15, s53
	s_add_u32 s52, s2, 0x5ba5000
	v_or_b32_e32 v72, s16, v74
	s_addc_u32 s53, s53, 0
	v_ashrrev_i32_e32 v73, 31, v72
	v_lshl_add_u64 v[70:71], v[72:73], 2, s[52:53]
	global_load_dword v146, v[70:71], off
	v_add_lshl_u32 v71, s11, v75, 10
	v_or_b32_e32 v73, 0x400, v71
	v_add_u32_e32 v102, v73, v72
	v_ashrrev_i32_e32 v103, 31, v102
	v_or_b32_e32 v101, 0x800, v71
	v_lshl_add_u64 v[116:117], v[102:103], 2, s[12:13]
	v_add_u32_e32 v102, v101, v72
	v_ashrrev_i32_e32 v103, 31, v102
	v_lshl_add_u64 v[118:119], v[102:103], 2, s[12:13]
	v_or_b32_e32 v102, 0xc00, v71
	v_add_u32_e32 v104, v102, v72
	v_ashrrev_i32_e32 v105, 31, v104
	v_or_b32_e32 v103, 0x2000, v71
	v_lshl_add_u64 v[120:121], v[104:105], 2, s[12:13]
	v_add_u32_e32 v104, v103, v72
	v_ashrrev_i32_e32 v105, 31, v104
	v_lshl_add_u64 v[122:123], v[104:105], 2, s[12:13]
	v_or_b32_e32 v104, 0x2400, v71
	v_add_u32_e32 v106, v104, v72
	v_ashrrev_i32_e32 v107, 31, v106
	v_or_b32_e32 v105, 0x2800, v71
	v_lshl_add_u64 v[124:125], v[106:107], 2, s[12:13]
	v_add_u32_e32 v106, v105, v72
	v_ashrrev_i32_e32 v107, 31, v106
	v_lshl_add_u64 v[126:127], v[106:107], 2, s[12:13]
	v_or_b32_e32 v106, 0x2c00, v71
	v_add_u32_e32 v108, v106, v72
	v_ashrrev_i32_e32 v109, 31, v108
	v_or_b32_e32 v107, 0x4000, v71
	v_lshl_add_u64 v[128:129], v[108:109], 2, s[12:13]
	v_add_u32_e32 v108, v107, v72
	v_ashrrev_i32_e32 v109, 31, v108
	v_lshl_add_u64 v[130:131], v[108:109], 2, s[12:13]
	v_or_b32_e32 v108, 0x4400, v71
	v_add_u32_e32 v110, v108, v72
	v_ashrrev_i32_e32 v111, 31, v110
	v_or_b32_e32 v109, 0x4800, v71
	v_lshl_add_u64 v[132:133], v[110:111], 2, s[12:13]
	v_add_u32_e32 v110, v109, v72
	v_ashrrev_i32_e32 v111, 31, v110
	v_lshl_add_u64 v[134:135], v[110:111], 2, s[12:13]
	v_or_b32_e32 v110, 0x4c00, v71
	v_add_u32_e32 v112, v110, v72
	v_ashrrev_i32_e32 v113, 31, v112
	v_or_b32_e32 v111, 0x6000, v71
	v_lshl_add_u64 v[136:137], v[112:113], 2, s[12:13]
	v_add_u32_e32 v112, v111, v72
	v_ashrrev_i32_e32 v113, 31, v112
	v_lshl_add_u64 v[138:139], v[112:113], 2, s[12:13]
	v_or_b32_e32 v112, 0x6400, v71
	v_add_u32_e32 v114, v112, v72
	v_ashrrev_i32_e32 v115, 31, v114
	v_or_b32_e32 v113, 0x6800, v71
	v_lshl_add_u64 v[140:141], v[114:115], 2, s[12:13]
	v_add_u32_e32 v114, v113, v72
	v_ashrrev_i32_e32 v115, 31, v114
	v_lshl_add_u64 v[142:143], v[114:115], 2, s[12:13]
	v_or_b32_e32 v114, 0x6c00, v71
	v_add_u32_e32 v144, v114, v72
	v_ashrrev_i32_e32 v145, 31, v144
	v_add_u32_e32 v70, v71, v72
	v_lshl_add_u64 v[144:145], v[144:145], 2, s[12:13]
	global_load_dword v147, v[116:117], off
	global_load_dword v148, v[118:119], off
	global_load_dword v149, v[120:121], off
	global_load_dword v150, v[122:123], off
	global_load_dword v151, v[124:125], off
	global_load_dword v152, v[126:127], off
	global_load_dword v153, v[128:129], off
	global_load_dword v154, v[130:131], off
	global_load_dword v155, v[132:133], off
	global_load_dword v156, v[134:135], off
	global_load_dword v115, v[136:137], off
	global_load_dword v157, v[138:139], off
	global_load_dword v158, v[140:141], off
	global_load_dword v159, v[142:143], off
	global_load_dword v160, v[144:145], off
	v_ashrrev_i32_e32 v71, 31, v70
	v_lshl_add_u64 v[70:71], v[70:71], 2, s[12:13]
	global_load_dword v161, v[70:71], off
	s_add_i32 s10, s10, s33
	s_cmpk_gt_i32 s10, 0x3ff
	global_load_dword v255, v[116:117], off offset:128
	global_load_dword v255, v[116:117], off offset:256
	global_load_dword v255, v[116:117], off offset:384
	global_load_dword v255, v[118:119], off offset:128
	global_load_dword v255, v[118:119], off offset:256
	global_load_dword v255, v[118:119], off offset:384
	global_load_dword v255, v[120:121], off offset:128
	global_load_dword v255, v[120:121], off offset:256
	global_load_dword v255, v[120:121], off offset:384
	global_load_dword v255, v[122:123], off offset:128
	global_load_dword v255, v[122:123], off offset:256
	global_load_dword v255, v[122:123], off offset:384
	global_load_dword v255, v[124:125], off offset:128
	global_load_dword v255, v[124:125], off offset:256
	global_load_dword v255, v[124:125], off offset:384
	global_load_dword v255, v[126:127], off offset:128
	global_load_dword v255, v[126:127], off offset:256
	global_load_dword v255, v[126:127], off offset:384
	global_load_dword v255, v[128:129], off offset:128
	global_load_dword v255, v[128:129], off offset:256
	global_load_dword v255, v[128:129], off offset:384
	global_load_dword v255, v[130:131], off offset:128
	global_load_dword v255, v[130:131], off offset:256
	global_load_dword v255, v[130:131], off offset:384
	global_load_dword v255, v[132:133], off offset:128
	global_load_dword v255, v[132:133], off offset:256
	global_load_dword v255, v[132:133], off offset:384
	global_load_dword v255, v[134:135], off offset:128
	global_load_dword v255, v[134:135], off offset:256
	global_load_dword v255, v[134:135], off offset:384
	global_load_dword v255, v[136:137], off offset:128
	global_load_dword v255, v[136:137], off offset:256
	global_load_dword v255, v[136:137], off offset:384
	global_load_dword v255, v[138:139], off offset:128
	global_load_dword v255, v[138:139], off offset:256
	global_load_dword v255, v[138:139], off offset:384
	global_load_dword v255, v[140:141], off offset:128
	global_load_dword v255, v[140:141], off offset:256
	global_load_dword v255, v[140:141], off offset:384
	global_load_dword v255, v[142:143], off offset:128
	global_load_dword v255, v[142:143], off offset:256
	global_load_dword v255, v[142:143], off offset:384
	global_load_dword v255, v[144:145], off offset:128
	global_load_dword v255, v[144:145], off offset:256
	global_load_dword v255, v[144:145], off offset:384
	global_load_dword v255, v[70:71], off offset:128
	global_load_dword v255, v[70:71], off offset:256
	global_load_dword v255, v[70:71], off offset:384
	s_waitcnt vmcnt(0)
	v_fmac_f32_e32 v147, v49, v146
	v_fmac_f32_e32 v148, v50, v146
	v_fmac_f32_e32 v149, v51, v146
	v_fmac_f32_e32 v150, v52, v146
	v_fmac_f32_e32 v151, v53, v146
	v_fmac_f32_e32 v152, v54, v146
	v_fmac_f32_e32 v153, v55, v146
	v_fmac_f32_e32 v154, v56, v146
	v_fmac_f32_e32 v155, v57, v146
	v_fmac_f32_e32 v156, v58, v146
	v_fmac_f32_e32 v115, v59, v146
	v_fmac_f32_e32 v157, v60, v146
	v_fmac_f32_e32 v158, v61, v146
	v_fmac_f32_e32 v159, v62, v146
	v_fmac_f32_e32 v160, v63, v146
	global_store_dword v[116:117], v147, off sc1
	global_store_dword v[118:119], v148, off sc1
	global_store_dword v[120:121], v149, off sc1
	global_store_dword v[122:123], v150, off sc1
	global_store_dword v[124:125], v151, off sc1
	global_store_dword v[126:127], v152, off sc1
	global_store_dword v[128:129], v153, off sc1
	global_store_dword v[130:131], v154, off sc1
	global_store_dword v[132:133], v155, off sc1
	global_store_dword v[134:135], v156, off sc1
	global_store_dword v[136:137], v115, off sc1
	global_store_dword v[138:139], v157, off sc1
	global_store_dword v[140:141], v158, off sc1
	global_store_dword v[142:143], v159, off sc1
	global_store_dword v[144:145], v160, off sc1
	global_load_dword v115, v[70:71], off offset:128
	v_fmac_f32_e32 v161, v48, v146
	v_or_b32_e32 v48, 32, v72
	v_ashrrev_i32_e32 v49, 31, v48
	global_store_dword v[70:71], v161, off sc1
	v_lshl_add_u64 v[50:51], v[48:49], 2, s[52:53]
	global_load_dword v134, v[50:51], off
	v_add_u32_e32 v50, v73, v48
	v_add_u32_e32 v118, v108, v48
	v_add_u32_e32 v52, v101, v48
	v_add_u32_e32 v54, v102, v48
	v_add_u32_e32 v56, v103, v48
	v_add_u32_e32 v58, v104, v48
	v_add_u32_e32 v60, v105, v48
	v_add_u32_e32 v62, v106, v48
	v_add_u32_e32 v116, v107, v48
	v_add_u32_e32 v120, v109, v48
	v_add_u32_e32 v122, v110, v48
	v_add_u32_e32 v124, v111, v48
	v_add_u32_e32 v126, v112, v48
	v_ashrrev_i32_e32 v51, 31, v50
	v_ashrrev_i32_e32 v119, 31, v118
	v_add_u32_e32 v128, v113, v48
	v_add_u32_e32 v48, v114, v48
	v_ashrrev_i32_e32 v53, 31, v52
	v_ashrrev_i32_e32 v55, 31, v54
	v_ashrrev_i32_e32 v57, 31, v56
	v_ashrrev_i32_e32 v59, 31, v58
	v_ashrrev_i32_e32 v61, 31, v60
	v_ashrrev_i32_e32 v63, 31, v62
	v_ashrrev_i32_e32 v117, 31, v116
	v_ashrrev_i32_e32 v121, 31, v120
	v_ashrrev_i32_e32 v123, 31, v122
	v_ashrrev_i32_e32 v125, 31, v124
	v_lshl_add_u64 v[50:51], v[50:51], 2, s[12:13]
	v_lshl_add_u64 v[118:119], v[118:119], 2, s[12:13]
	v_ashrrev_i32_e32 v127, 31, v126
	v_ashrrev_i32_e32 v129, 31, v128
	v_ashrrev_i32_e32 v49, 31, v48
	v_lshl_add_u64 v[52:53], v[52:53], 2, s[12:13]
	v_lshl_add_u64 v[54:55], v[54:55], 2, s[12:13]
	v_lshl_add_u64 v[56:57], v[56:57], 2, s[12:13]
	v_lshl_add_u64 v[58:59], v[58:59], 2, s[12:13]
	v_lshl_add_u64 v[60:61], v[60:61], 2, s[12:13]
	v_lshl_add_u64 v[62:63], v[62:63], 2, s[12:13]
	v_lshl_add_u64 v[116:117], v[116:117], 2, s[12:13]
	v_lshl_add_u64 v[120:121], v[120:121], 2, s[12:13]
	v_lshl_add_u64 v[122:123], v[122:123], 2, s[12:13]
	v_lshl_add_u64 v[124:125], v[124:125], 2, s[12:13]
	v_lshl_add_u64 v[126:127], v[126:127], 2, s[12:13]
	v_lshl_add_u64 v[128:129], v[128:129], 2, s[12:13]
	v_lshl_add_u64 v[48:49], v[48:49], 2, s[12:13]
	v_or_b32_e32 v130, 64, v72
	v_ashrrev_i32_e32 v131, 31, v130
	v_lshl_add_u64 v[132:133], v[130:131], 2, s[52:53]
	s_waitcnt vmcnt(0)
	v_fmac_f32_e32 v115, v32, v134
	global_store_dword v[70:71], v115, off offset:128 sc1
	global_load_dword v32, v[50:51], off
	s_nop 0
	global_load_dword v115, v[52:53], off
	global_load_dword v135, v[54:55], off
	global_load_dword v136, v[56:57], off
	global_load_dword v137, v[58:59], off
	global_load_dword v138, v[60:61], off
	global_load_dword v139, v[62:63], off
	global_load_dword v140, v[116:117], off
	global_load_dword v141, v[118:119], off
	global_load_dword v142, v[120:121], off
	global_load_dword v143, v[122:123], off
	global_load_dword v144, v[124:125], off
	global_load_dword v145, v[126:127], off
	global_load_dword v146, v[128:129], off
	global_load_dword v147, v[48:49], off
	s_waitcnt vmcnt(14)
	v_fmac_f32_e32 v32, v33, v134
	s_waitcnt vmcnt(13)
	v_fmac_f32_e32 v115, v34, v134
	s_waitcnt vmcnt(12)
	v_fmac_f32_e32 v135, v35, v134
	s_waitcnt vmcnt(11)
	v_fmac_f32_e32 v136, v36, v134
	s_waitcnt vmcnt(10)
	v_fmac_f32_e32 v137, v37, v134
	s_waitcnt vmcnt(9)
	v_fmac_f32_e32 v138, v38, v134
	s_waitcnt vmcnt(8)
	v_fmac_f32_e32 v139, v39, v134
	s_waitcnt vmcnt(7)
	v_fmac_f32_e32 v140, v40, v134
	s_waitcnt vmcnt(6)
	v_fmac_f32_e32 v141, v41, v134
	s_waitcnt vmcnt(5)
	v_fmac_f32_e32 v142, v42, v134
	s_waitcnt vmcnt(4)
	v_fmac_f32_e32 v143, v43, v134
	s_waitcnt vmcnt(3)
	v_fmac_f32_e32 v144, v44, v134
	s_waitcnt vmcnt(2)
	v_fmac_f32_e32 v145, v45, v134
	s_waitcnt vmcnt(1)
	v_fmac_f32_e32 v146, v46, v134
	s_waitcnt vmcnt(0)
	v_fmac_f32_e32 v147, v47, v134
	global_store_dword v[50:51], v32, off sc1
	global_store_dword v[52:53], v115, off sc1
	global_store_dword v[54:55], v135, off sc1
	global_store_dword v[56:57], v136, off sc1
	global_store_dword v[58:59], v137, off sc1
	global_store_dword v[60:61], v138, off sc1
	global_store_dword v[62:63], v139, off sc1
	global_store_dword v[116:117], v140, off sc1
	global_store_dword v[118:119], v141, off sc1
	global_store_dword v[120:121], v142, off sc1
	global_store_dword v[122:123], v143, off sc1
	global_store_dword v[124:125], v144, off sc1
	global_store_dword v[126:127], v145, off sc1
	global_store_dword v[128:129], v146, off sc1
	global_store_dword v[48:49], v147, off sc1
	global_load_dword v115, v[132:133], off
	global_load_dword v62, v[70:71], off offset:256
	v_add_u32_e32 v32, v73, v130
	v_add_u32_e32 v34, v101, v130
	v_add_u32_e32 v36, v102, v130
	v_add_u32_e32 v38, v103, v130
	v_add_u32_e32 v40, v104, v130
	v_add_u32_e32 v42, v105, v130
	v_add_u32_e32 v44, v106, v130
	v_add_u32_e32 v46, v107, v130
	v_add_u32_e32 v48, v108, v130
	v_add_u32_e32 v50, v109, v130
	v_add_u32_e32 v52, v110, v130
	v_add_u32_e32 v54, v111, v130
	v_add_u32_e32 v56, v112, v130
	v_add_u32_e32 v58, v113, v130
	v_add_u32_e32 v60, v114, v130
	v_ashrrev_i32_e32 v33, 31, v32
	v_ashrrev_i32_e32 v35, 31, v34
	v_ashrrev_i32_e32 v37, 31, v36
	v_ashrrev_i32_e32 v39, 31, v38
	v_ashrrev_i32_e32 v41, 31, v40
	v_ashrrev_i32_e32 v43, 31, v42
	v_ashrrev_i32_e32 v45, 31, v44
	v_ashrrev_i32_e32 v47, 31, v46
	v_ashrrev_i32_e32 v49, 31, v48
	v_ashrrev_i32_e32 v51, 31, v50
	v_ashrrev_i32_e32 v53, 31, v52
	v_ashrrev_i32_e32 v55, 31, v54
	v_ashrrev_i32_e32 v57, 31, v56
	v_ashrrev_i32_e32 v59, 31, v58
	v_ashrrev_i32_e32 v61, 31, v60
	v_lshl_add_u64 v[32:33], v[32:33], 2, s[12:13]
	v_lshl_add_u64 v[34:35], v[34:35], 2, s[12:13]
	v_lshl_add_u64 v[36:37], v[36:37], 2, s[12:13]
	v_lshl_add_u64 v[38:39], v[38:39], 2, s[12:13]
	v_lshl_add_u64 v[40:41], v[40:41], 2, s[12:13]
	v_lshl_add_u64 v[42:43], v[42:43], 2, s[12:13]
	v_lshl_add_u64 v[44:45], v[44:45], 2, s[12:13]
	v_lshl_add_u64 v[46:47], v[46:47], 2, s[12:13]
	v_lshl_add_u64 v[48:49], v[48:49], 2, s[12:13]
	v_lshl_add_u64 v[50:51], v[50:51], 2, s[12:13]
	v_lshl_add_u64 v[52:53], v[52:53], 2, s[12:13]
	v_lshl_add_u64 v[54:55], v[54:55], 2, s[12:13]
	v_lshl_add_u64 v[56:57], v[56:57], 2, s[12:13]
	v_lshl_add_u64 v[58:59], v[58:59], 2, s[12:13]
	v_lshl_add_u64 v[60:61], v[60:61], 2, s[12:13]
	s_waitcnt vmcnt(0)
	v_fmac_f32_e32 v62, v16, v115
	global_store_dword v[70:71], v62, off offset:256 sc1
	global_load_dword v16, v[32:33], off
	global_load_dword v118, v[34:35], off
	global_load_dword v119, v[36:37], off
	global_load_dword v120, v[38:39], off
	global_load_dword v121, v[40:41], off
	global_load_dword v122, v[42:43], off
	global_load_dword v123, v[44:45], off
	global_load_dword v124, v[46:47], off
	global_load_dword v125, v[48:49], off
	global_load_dword v126, v[50:51], off
	global_load_dword v127, v[52:53], off
	global_load_dword v128, v[54:55], off
	global_load_dword v129, v[56:57], off
	global_load_dword v130, v[58:59], off
	global_load_dword v131, v[60:61], off
	v_or_b32_e32 v62, 0x60, v72
	v_ashrrev_i32_e32 v63, 31, v62
	v_lshl_add_u64 v[116:117], v[62:63], 2, s[52:53]
	s_waitcnt vmcnt(14)
	v_fmac_f32_e32 v16, v17, v115
	s_waitcnt vmcnt(13)
	v_fmac_f32_e32 v118, v18, v115
	s_waitcnt vmcnt(12)
	v_fmac_f32_e32 v119, v19, v115
	s_waitcnt vmcnt(11)
	v_fmac_f32_e32 v120, v20, v115
	s_waitcnt vmcnt(10)
	v_fmac_f32_e32 v121, v21, v115
	s_waitcnt vmcnt(9)
	v_fmac_f32_e32 v122, v22, v115
	s_waitcnt vmcnt(8)
	v_fmac_f32_e32 v123, v23, v115
	s_waitcnt vmcnt(7)
	v_fmac_f32_e32 v124, v24, v115
	s_waitcnt vmcnt(6)
	v_fmac_f32_e32 v125, v25, v115
	s_waitcnt vmcnt(5)
	v_fmac_f32_e32 v126, v26, v115
	s_waitcnt vmcnt(4)
	v_fmac_f32_e32 v127, v27, v115
	s_waitcnt vmcnt(3)
	v_fmac_f32_e32 v128, v28, v115
	s_waitcnt vmcnt(2)
	v_fmac_f32_e32 v129, v29, v115
	s_waitcnt vmcnt(1)
	v_fmac_f32_e32 v130, v30, v115
	s_waitcnt vmcnt(0)
	v_fmac_f32_e32 v131, v31, v115
	global_store_dword v[32:33], v16, off sc1
	global_store_dword v[34:35], v118, off sc1
	global_store_dword v[36:37], v119, off sc1
	global_store_dword v[38:39], v120, off sc1
	global_store_dword v[40:41], v121, off sc1
	global_store_dword v[42:43], v122, off sc1
	global_store_dword v[44:45], v123, off sc1
	global_store_dword v[46:47], v124, off sc1
	global_store_dword v[48:49], v125, off sc1
	global_store_dword v[50:51], v126, off sc1
	global_store_dword v[52:53], v127, off sc1
	global_store_dword v[54:55], v128, off sc1
	global_store_dword v[56:57], v129, off sc1
	global_store_dword v[58:59], v130, off sc1
	global_store_dword v[60:61], v131, off sc1
	global_load_dword v46, v[116:117], off
	global_load_dword v47, v[70:71], off offset:384
	v_add_u32_e32 v16, v73, v62
	v_add_u32_e32 v18, v101, v62
	v_add_u32_e32 v20, v102, v62
	v_add_u32_e32 v22, v103, v62
	v_add_u32_e32 v24, v104, v62
	v_add_u32_e32 v26, v105, v62
	v_add_u32_e32 v28, v106, v62
	v_add_u32_e32 v30, v107, v62
	v_add_u32_e32 v32, v108, v62
	v_add_u32_e32 v34, v109, v62
	v_add_u32_e32 v36, v110, v62
	v_add_u32_e32 v38, v111, v62
	v_add_u32_e32 v40, v112, v62
	v_add_u32_e32 v42, v113, v62
	v_add_u32_e32 v44, v114, v62
	v_ashrrev_i32_e32 v17, 31, v16
	v_ashrrev_i32_e32 v19, 31, v18
	v_ashrrev_i32_e32 v21, 31, v20
	v_ashrrev_i32_e32 v23, 31, v22
	v_ashrrev_i32_e32 v25, 31, v24
	v_ashrrev_i32_e32 v27, 31, v26
	v_ashrrev_i32_e32 v29, 31, v28
	v_ashrrev_i32_e32 v31, 31, v30
	v_ashrrev_i32_e32 v33, 31, v32
	v_ashrrev_i32_e32 v35, 31, v34
	v_ashrrev_i32_e32 v37, 31, v36
	v_ashrrev_i32_e32 v39, 31, v38
	v_ashrrev_i32_e32 v41, 31, v40
	v_ashrrev_i32_e32 v43, 31, v42
	v_ashrrev_i32_e32 v45, 31, v44
	v_lshl_add_u64 v[16:17], v[16:17], 2, s[12:13]
	v_lshl_add_u64 v[18:19], v[18:19], 2, s[12:13]
	v_lshl_add_u64 v[20:21], v[20:21], 2, s[12:13]
	v_lshl_add_u64 v[22:23], v[22:23], 2, s[12:13]
	v_lshl_add_u64 v[24:25], v[24:25], 2, s[12:13]
	v_lshl_add_u64 v[26:27], v[26:27], 2, s[12:13]
	v_lshl_add_u64 v[28:29], v[28:29], 2, s[12:13]
	v_lshl_add_u64 v[30:31], v[30:31], 2, s[12:13]
	v_lshl_add_u64 v[32:33], v[32:33], 2, s[12:13]
	v_lshl_add_u64 v[34:35], v[34:35], 2, s[12:13]
	v_lshl_add_u64 v[36:37], v[36:37], 2, s[12:13]
	v_lshl_add_u64 v[38:39], v[38:39], 2, s[12:13]
	v_lshl_add_u64 v[40:41], v[40:41], 2, s[12:13]
	v_lshl_add_u64 v[42:43], v[42:43], 2, s[12:13]
	v_lshl_add_u64 v[44:45], v[44:45], 2, s[12:13]
	s_waitcnt vmcnt(0)
	v_fmac_f32_e32 v47, v0, v46
	global_store_dword v[70:71], v47, off offset:384 sc1
	global_load_dword v0, v[16:17], off
	s_nop 0
	global_load_dword v47, v[18:19], off
	global_load_dword v48, v[20:21], off
	global_load_dword v49, v[22:23], off
	global_load_dword v50, v[24:25], off
	global_load_dword v51, v[26:27], off
	global_load_dword v52, v[28:29], off
	global_load_dword v53, v[30:31], off
	global_load_dword v54, v[32:33], off
	global_load_dword v55, v[34:35], off
	global_load_dword v56, v[36:37], off
	global_load_dword v57, v[38:39], off
	global_load_dword v58, v[40:41], off
	global_load_dword v59, v[42:43], off
	global_load_dword v60, v[44:45], off
	s_waitcnt vmcnt(14)
	v_fmac_f32_e32 v0, v1, v46
	s_waitcnt vmcnt(13)
	v_fmac_f32_e32 v47, v2, v46
	s_waitcnt vmcnt(12)
	v_fmac_f32_e32 v48, v3, v46
	s_waitcnt vmcnt(11)
	v_fmac_f32_e32 v49, v4, v46
	s_waitcnt vmcnt(10)
	v_fmac_f32_e32 v50, v5, v46
	s_waitcnt vmcnt(9)
	v_fmac_f32_e32 v51, v6, v46
	s_waitcnt vmcnt(8)
	v_fmac_f32_e32 v52, v7, v46
	s_waitcnt vmcnt(7)
	v_fmac_f32_e32 v53, v8, v46
	s_waitcnt vmcnt(6)
	v_fmac_f32_e32 v54, v9, v46
	s_waitcnt vmcnt(5)
	v_fmac_f32_e32 v55, v10, v46
	s_waitcnt vmcnt(4)
	v_fmac_f32_e32 v56, v11, v46
	s_waitcnt vmcnt(3)
	v_fmac_f32_e32 v57, v12, v46
	s_waitcnt vmcnt(2)
	v_fmac_f32_e32 v58, v13, v46
	s_waitcnt vmcnt(1)
	v_fmac_f32_e32 v59, v14, v46
	s_waitcnt vmcnt(0)
	v_fmac_f32_e32 v60, v15, v46
	global_store_dword v[16:17], v0, off sc1
	global_store_dword v[18:19], v47, off sc1
	global_store_dword v[20:21], v48, off sc1
	global_store_dword v[22:23], v49, off sc1
	global_store_dword v[24:25], v50, off sc1
	global_store_dword v[26:27], v51, off sc1
	global_store_dword v[28:29], v52, off sc1
	global_store_dword v[30:31], v53, off sc1
	global_store_dword v[32:33], v54, off sc1
	global_store_dword v[34:35], v55, off sc1
	global_store_dword v[36:37], v56, off sc1
	global_store_dword v[38:39], v57, off sc1
	global_store_dword v[40:41], v58, off sc1
	global_store_dword v[42:43], v59, off sc1
	global_store_dword v[44:45], v60, off sc1
	s_cbranch_scc1 .LBB0_1641
